# up-proj rewritten too: same 256x128/BK32 pipelined GEMM with k-blocked hn (rowpass b stores remapped) and wt_up; conv3+gelu epilogue via DPP row shifts, hbuf written blocked
# speedup vs baseline: 1.0303x; 1.0303x over previous
_Z11mega_kernel6Params:
	s_add_u32 s4, s0, 0x138
	v_writelane_b32 v244, s2, 0
	s_load_dwordx2 s[8:9], s[0:1], 0x0
	s_load_dwordx2 s[2:3], s[0:1], 0x138
	v_and_b32_e32 v154, 0x3ff, v0
	v_cmp_gt_u32_e32 vcc, 4, v154
	s_waitcnt lgkmcnt(0)
	v_writelane_b32 v244, s2, 1
	s_nop 1
	v_writelane_b32 v244, s3, 2
	v_writelane_b32 v244, s0, 3
	s_addc_u32 s5, s1, 0
	s_nop 0
	v_writelane_b32 v244, s1, 4
	s_and_saveexec_b64 s[6:7], vcc
	v_mov_b32_e32 v1, 0x12000
	v_lshl_or_b32 v1, v154, 2, v1
	v_mov_b32_e32 v2, 0
	ds_write_b32 v1, v2
	s_or_b64 exec, exec, s[6:7]
	v_readlane_b32 s0, v244, 3
	v_readlane_b32 s1, v244, 4
	s_load_dwordx2 s[64:65], s[0:1], 0x130
	s_load_dwordx4 s[12:15], s[0:1], 0xa8
	s_load_dwordx2 s[10:11], s[0:1], 0xc0
	s_cmp_lg_u64 s[8:9], 0
	s_waitcnt lgkmcnt(0)
	v_writelane_b32 v244, s12, 58
	v_writelane_b32 v244, s14, 59
	v_writelane_b32 v244, s10, 60
	v_writelane_b32 v244, s11, 61
	s_barrier
	s_cbranch_scc1 .LBB0_14
	v_lshrrev_b32_e32 v1, 20, v0
	v_lshrrev_b32_e32 v0, 10, v0
	v_or_b32_e32 v0, v0, v1
	s_movk_i32 s0, 0x3ff
	v_and_or_b32 v0, v0, s0, v154
	v_cmp_eq_u32_e32 vcc, 0, v0
	s_barrier
	s_and_saveexec_b64 s[0:1], vcc
	s_cbranch_execz .LBB0_13
	buffer_wbl2 sc1
	s_load_dwordx2 s[4:5], s[4:5], 0x58
	s_mov_b64 s[6:7], exec
	v_mbcnt_lo_u32_b32 v0, s6, 0
	v_mbcnt_hi_u32_b32 v0, s7, v0
	v_cmp_eq_u32_e32 vcc, 0, v0
	s_waitcnt lgkmcnt(0)
	s_load_dword s2, s[4:5], 0x28
	s_and_saveexec_b64 s[8:9], vcc
	s_cbranch_execz .LBB0_6
	s_bcnt1_i32_b64 s3, s[6:7]
	v_mov_b32_e32 v1, 0
	v_mov_b32_e32 v2, s3
	global_atomic_add v1, v1, v2, s[4:5] offset:32 sc0

.LBB0_21:
	v_readlane_b32 s6, v244, 1
	v_readlane_b32 s7, v244, 2
	s_cmp_lt_u32 s70, 11
	v_readlane_b32 s0, v244, 3
	s_mov_b32 s71, s6
	s_cselect_b64 s[6:7], -1, 0
	s_add_i32 s20, s70, -9
	v_readlane_b32 s1, v244, 4
	v_readlane_b32 s3, v244, 0
	s_cmp_gt_u32 s70, 10
	s_cselect_b64 s[22:23], -1, 0
	s_waitcnt lgkmcnt(0)
	s_load_dwordx2 s[24:25], s[0:1], 0xb8
	s_and_b64 s[18:19], s[22:23], exec
	s_cselect_b32 s18, s20, s70
	s_cmp_lt_u32 s70, 2
	s_cselect_b32 s19, s70, s18
	s_cmp_eq_u32 s19, 9
	s_cbranch_scc1 .Lgy_entry
	s_cmp_eq_u32 s19, 8
	s_cbranch_scc1 .Lup_entry
	s_cmp_lt_i32 s19, 5
	s_cbranch_scc1 .LBB0_46
	s_and_b64 s[20:21], s[22:23], exec
	s_cselect_b32 s18, 0x18000, 0
	s_waitcnt lgkmcnt(0)
	s_add_u32 s66, s24, s18
	s_addc_u32 s80, s25, 0
	s_cmp_gt_i32 s19, 7
	s_cbranch_scc0 .LBB0_47
	s_cmp_gt_i32 s19, 8
	s_cbranch_scc0 .LBB0_48
	s_cmp_gt_i32 s19, 9
	s_cbranch_scc0 .LBB0_64
	s_mov_b64 s[20:21], 0
	s_mov_b64 s[24:25], 0
	s_cmp_eq_u32 s19, 10
	v_writelane_b32 v244, s20, 56
	s_nop 1
	v_writelane_b32 v244, s21, 57
	s_cbranch_scc0 .LBB0_65
	s_load_dwordx2 s[30:31], s[0:1], 0x68
	s_and_b64 vcc, exec, s[6:7]
	s_cbranch_vccz .LBB0_334
	s_lshl_b32 s18, s71, 2
	s_abs_i32 s6, s18
	v_cvt_f32_u32_e32 v0, s6
	s_waitcnt vmcnt(0)
	v_mov_b32_e32 v34, v154
	v_mov_b32_e32 v2, v154
	s_sub_i32 s26, 0, s6
	v_rcp_iflag_f32_e32 v0, v0
	s_nop 0
	v_mul_f32_e32 v0, 0x4f7ffffe, v0
	v_cvt_u32_f32_e32 v0, v0
	v_readfirstlane_b32 s7, v2
	s_ashr_i32 s20, s7, 6
	s_add_i32 s7, s18, 0x3fff
	v_readfirstlane_b32 s27, v0
	s_mul_i32 s26, s26, s27
	s_mul_hi_u32 s26, s27, s26
	s_xor_b32 s21, s7, s18
	s_abs_i32 s7, s7
	s_add_i32 s27, s27, s26
	s_mul_hi_u32 s26, s7, s27
	s_mul_i32 s27, s26, s6
	s_sub_i32 s7, s7, s27
	s_ashr_i32 s21, s21, 31
	s_add_i32 s27, s26, 1
	s_sub_i32 s28, s7, s6
	s_cmp_ge_u32 s7, s6
	s_cselect_b32 s26, s27, s26
	s_cselect_b32 s7, s28, s7
	s_add_i32 s27, s26, 1
	s_cmp_ge_u32 s7, s6
	s_cselect_b32 s6, s27, s26
	s_xor_b32 s6, s6, s21
	s_lshl_b32 s52, s3, 2
	s_sub_i32 s7, s6, s21
	s_add_i32 s6, s20, s52
	s_mul_i32 s6, s6, s7
	s_cmpk_gt_i32 s6, 0x3fff
	s_cbranch_scc1 .LBB0_335
	s_load_dwordx2 s[26:27], s[0:1], 0x110
	s_ashr_i32 s20, s6, 12
	s_mulk_i32 s20, 0x1800
	v_lshlrev_b32_e32 v0, 2, v34
	v_and_b32_e32 v35, 0xfc, v0
	s_waitcnt lgkmcnt(0)
	s_cmp_lg_u64 s[26:27], 0
	s_cselect_b64 s[40:41], -1, 0
	s_ashr_i32 s21, s20, 31
	s_lshl_b64 s[34:35], s[20:21], 2
	s_add_u32 s20, s66, s34
	s_addc_u32 s21, s80, s35
	s_add_u32 s36, s20, 0x5000
	s_addc_u32 s37, s21, 0
	s_and_b64 vcc, exec, s[40:41]
	v_lshlrev_b32_e32 v0, 2, v35
	s_cbranch_vccz .LBB0_30
	v_lshl_add_u64 v[10:11], s[36:37], 0, v[0:1]
	v_add_co_u32_e32 v6, vcc, 0x30000, v10
	global_load_dwordx4 v[2:5], v0, s[36:37]
	s_nop 0
	v_addc_co_u32_e32 v7, vcc, 0, v11, vcc
	global_load_dwordx4 v[6:9], v[6:7], off
	s_waitcnt vmcnt(0)
	v_pk_add_f32 v[6:7], v[2:3], v[6:7]
	v_add_co_u32_e32 v2, vcc, 0x60000, v10
	v_pk_add_f32 v[8:9], v[4:5], v[8:9]
	s_nop 0
	v_addc_co_u32_e32 v3, vcc, 0, v11, vcc
	global_load_dwordx4 v[2:5], v[2:3], off
	s_waitcnt vmcnt(0)
	v_pk_add_f32 v[6:7], v[6:7], v[2:3]
	v_add_co_u32_e32 v2, vcc, 0x90000, v10
	v_pk_add_f32 v[8:9], v[8:9], v[4:5]
	s_nop 0
	v_addc_co_u32_e32 v3, vcc, 0, v11, vcc
	global_load_dwordx4 v[2:5], v[2:3], off
	s_waitcnt vmcnt(0)
	v_pk_add_f32 v[68:69], v[8:9], v[4:5]
	v_pk_add_f32 v[66:67], v[6:7], v[2:3]
	global_load_dwordx4 v[2:5], v0, s[30:31]

.LBB0_104:
	s_waitcnt lgkmcnt(0)
	s_barrier
	ds_write_b128 v170, v[94:97] offset:32768
	ds_write_b128 v171, v[66:69] offset:32768
	ds_write_b128 v170, v[86:89] offset:36864
	ds_write_b128 v171, v[54:57] offset:36864
	ds_write_b128 v170, v[78:81] offset:40960
	ds_write_b128 v171, v[46:49] offset:40960
	ds_write_b128 v170, v[70:73] offset:45056
	ds_write_b128 v171, v[38:41] offset:45056
	s_waitcnt lgkmcnt(0)
	s_barrier
	v_or_b32_e32 v106, s20, v103
	v_add_u32_e32 v108, s56, v99
	v_ashrrev_i32_e32 v107, 31, v106
	v_cmp_gt_i32_e32 vcc, s88, v108
	v_lshl_add_u64 v[106:107], v[106:107], 1, s[36:37]
	s_and_b64 s[48:49], s[38:39], vcc
	v_add_u32_e32 v0, s21, v108
	s_and_saveexec_b64 s[50:51], s[48:49]
	s_cbranch_execz .LBB0_106
	ds_read_b128 v[110:113], v172 offset:32512
	ds_read_b128 v[114:117], v173 offset:32256
	v_cmp_lt_i32_e32 vcc, 0, v108
	s_waitcnt lgkmcnt(0)
	s_nop 0
	v_cndmask_b32_e32 v111, 0, v111, vcc
	v_cndmask_b32_e32 v110, 0, v110, vcc
	v_cndmask_b32_e32 v113, 0, v113, vcc
	v_cndmask_b32_e32 v112, 0, v112, vcc
	v_cmp_lt_i32_e32 vcc, 1, v108
	v_pk_mul_f32 v[110:111], v[30:31], v[110:111]
	v_pk_mul_f32 v[112:113], v[32:33], v[112:113]
	v_cndmask_b32_e32 v115, 0, v115, vcc
	v_cndmask_b32_e32 v114, 0, v114, vcc
	v_pk_fma_f32 v[94:95], v[26:27], v[94:95], v[110:111]
	v_cndmask_b32_e32 v117, 0, v117, vcc
	v_pk_fma_f32 v[94:95], v[22:23], v[114:115], v[94:95]
	v_cndmask_b32_e32 v116, 0, v116, vcc
	v_pk_add_f32 v[94:95], v[18:19], v[94:95]
	v_pk_fma_f32 v[96:97], v[28:29], v[96:97], v[112:113]
	v_mul_f32_e32 v109, 0x3d372713, v94
	v_mul_f32_e32 v109, v94, v109
	v_mul_f32_e32 v110, 0x3d372713, v95
	v_fma_f32 v109, v94, v109, v94
	v_mul_f32_e32 v110, v95, v110
	v_mul_f32_e32 v109, 0x3f4c422a, v109
	v_fma_f32 v110, v95, v110, v95
	v_mul_f32_e32 v109, 0xc038aa3b, v109
	v_mul_f32_e32 v110, 0x3f4c422a, v110
	v_exp_f32_e32 v109, v109
	v_mul_f32_e32 v110, 0xc038aa3b, v110
	v_exp_f32_e32 v111, v110
	v_pk_fma_f32 v[96:97], v[24:25], v[116:117], v[96:97]
	v_add_f32_e32 v109, 1.0, v109
	v_pk_add_f32 v[96:97], v[20:21], v[96:97]
	v_rcp_f32_e32 v110, v109
	v_add_f32_e32 v109, 1.0, v111
	v_mul_f32_e32 v111, 0x3d372713, v96
	v_mul_f32_e32 v111, v96, v111
	v_fma_f32 v111, v96, v111, v96
	v_mul_f32_e32 v111, 0x3f4c422a, v111
	v_mul_f32_e32 v111, 0xc038aa3b, v111
	v_exp_f32_e32 v112, v111
	v_mul_f32_e32 v111, 0x3d372713, v97
	v_mul_f32_e32 v111, v97, v111
	v_fma_f32 v111, v97, v111, v97
	v_mul_f32_e32 v111, 0x3f4c422a, v111
	v_mul_f32_e32 v111, 0xc038aa3b, v111
	v_exp_f32_e32 v113, v111
	v_rcp_f32_e32 v111, v109
	v_add_f32_e32 v109, 1.0, v112
	v_rcp_f32_e32 v112, v109
	v_add_f32_e32 v109, 1.0, v113
	v_rcp_f32_e32 v113, v109
	v_pk_mul_f32 v[94:95], v[94:95], v[110:111]
	s_nop 0
	v_pk_mul_f32 v[90:91], v[90:91], v[94:95]
	v_pk_mul_f32 v[94:95], v[96:97], v[112:113]
	v_cvt_pk_bf16_f32 v90, v90, v91
	v_pk_mul_f32 v[92:93], v[92:93], v[94:95]
	s_nop 0
	v_cvt_pk_bf16_f32 v91, v92, v93
	v_mad_i64_i32 v[92:93], s[52:53], v0, s85, v[106:107]
	global_store_dwordx2 v[92:93], v[90:91], off
.LBB0_106:
	s_or_b64 exec, exec, s[50:51]
	v_add_u32_e32 v91, s56, v105
	v_cmp_gt_i32_e32 vcc, s88, v91
	s_and_b64 s[50:51], s[40:41], vcc
	v_add_u32_e32 v90, s21, v91
	s_and_saveexec_b64 s[52:53], s[50:51]
	s_cbranch_execz .LBB0_108
	ds_read_b128 v[92:95], v172 offset:36608
	ds_read_b128 v[110:113], v173 offset:36352
	v_cmp_lt_i32_e32 vcc, 0, v91
	s_waitcnt lgkmcnt(0)
	s_nop 0
	v_cndmask_b32_e32 v93, 0, v93, vcc
	v_cndmask_b32_e32 v92, 0, v92, vcc
	v_cndmask_b32_e32 v95, 0, v95, vcc
	v_cndmask_b32_e32 v94, 0, v94, vcc
	v_cmp_lt_i32_e32 vcc, 1, v91
	v_pk_mul_f32 v[92:93], v[30:31], v[92:93]
	v_pk_mul_f32 v[94:95], v[32:33], v[94:95]
	v_cndmask_b32_e32 v111, 0, v111, vcc
	v_cndmask_b32_e32 v110, 0, v110, vcc
	v_pk_fma_f32 v[86:87], v[26:27], v[86:87], v[92:93]
	v_cndmask_b32_e32 v97, 0, v113, vcc
	v_cndmask_b32_e32 v96, 0, v112, vcc
	v_pk_fma_f32 v[88:89], v[28:29], v[88:89], v[94:95]
	v_pk_fma_f32 v[86:87], v[22:23], v[110:111], v[86:87]
	v_pk_fma_f32 v[88:89], v[24:25], v[96:97], v[88:89]
	v_pk_add_f32 v[86:87], v[18:19], v[86:87]
	v_pk_add_f32 v[88:89], v[20:21], v[88:89]
	v_mul_f32_e32 v92, 0x3d372713, v86
	v_mul_f32_e32 v93, 0x3d372713, v87
	v_mul_f32_e32 v92, v86, v92
	v_mul_f32_e32 v93, v87, v93
	v_mul_f32_e32 v94, 0x3d372713, v88
	v_mul_f32_e32 v95, 0x3d372713, v89
	v_fma_f32 v92, v86, v92, v86
	v_fma_f32 v93, v87, v93, v87
	v_mul_f32_e32 v94, v88, v94
	v_mul_f32_e32 v95, v89, v95
	v_mul_f32_e32 v92, 0x3f4c422a, v92
	v_mul_f32_e32 v93, 0x3f4c422a, v93
	v_fma_f32 v94, v88, v94, v88
	v_fma_f32 v95, v89, v95, v89
	v_mul_f32_e32 v92, 0xc038aa3b, v92
	v_mul_f32_e32 v93, 0xc038aa3b, v93
	v_mul_f32_e32 v94, 0x3f4c422a, v94
	v_mul_f32_e32 v95, 0x3f4c422a, v95
	v_exp_f32_e32 v92, v92
	v_exp_f32_e32 v93, v93
	v_mul_f32_e32 v94, 0xc038aa3b, v94
	v_mul_f32_e32 v95, 0xc038aa3b, v95
	v_exp_f32_e32 v94, v94
	v_exp_f32_e32 v95, v95
	v_add_f32_e32 v92, 1.0, v92
	v_add_f32_e32 v93, 1.0, v93
	v_rcp_f32_e32 v92, v92
	v_rcp_f32_e32 v93, v93
	v_add_f32_e32 v94, 1.0, v94
	v_add_f32_e32 v95, 1.0, v95
	v_rcp_f32_e32 v94, v94
	v_rcp_f32_e32 v95, v95
	v_pk_mul_f32 v[86:87], v[86:87], v[92:93]
	s_nop 0
	v_pk_mul_f32 v[82:83], v[82:83], v[86:87]
	v_pk_mul_f32 v[86:87], v[88:89], v[94:95]
	v_cvt_pk_bf16_f32 v82, v82, v83
	v_pk_mul_f32 v[84:85], v[84:85], v[86:87]
	s_nop 0
	v_cvt_pk_bf16_f32 v83, v84, v85
	v_mad_i64_i32 v[84:85], s[54:55], v90, s85, v[106:107]
	global_store_dwordx2 v[84:85], v[82:83], off
.LBB0_108:
	s_or_b64 exec, exec, s[52:53]
	v_add_u32_e32 v83, s56, v167
	v_cmp_gt_i32_e32 vcc, s88, v83
	s_and_b64 s[52:53], s[40:41], vcc
	v_add_u32_e32 v82, s21, v83
	s_and_saveexec_b64 s[54:55], s[52:53]
	s_cbranch_execz .LBB0_110
	ds_read_b128 v[84:87], v172 offset:40704
	ds_read_b128 v[92:95], v173 offset:40448
	v_cmp_lt_i32_e32 vcc, 0, v83
	s_waitcnt lgkmcnt(0)
	s_nop 0
	v_cndmask_b32_e32 v85, 0, v85, vcc
	v_cndmask_b32_e32 v84, 0, v84, vcc
	v_cndmask_b32_e32 v87, 0, v87, vcc
	v_cndmask_b32_e32 v86, 0, v86, vcc
	v_cmp_lt_i32_e32 vcc, 1, v83
	v_pk_mul_f32 v[84:85], v[30:31], v[84:85]
	v_pk_mul_f32 v[86:87], v[32:33], v[86:87]
	v_cndmask_b32_e32 v93, 0, v93, vcc
	v_cndmask_b32_e32 v92, 0, v92, vcc
	v_pk_fma_f32 v[78:79], v[26:27], v[78:79], v[84:85]
	v_cndmask_b32_e32 v89, 0, v95, vcc
	v_cndmask_b32_e32 v88, 0, v94, vcc
	v_pk_fma_f32 v[80:81], v[28:29], v[80:81], v[86:87]
	v_pk_fma_f32 v[78:79], v[22:23], v[92:93], v[78:79]
	v_pk_fma_f32 v[80:81], v[24:25], v[88:89], v[80:81]
	v_pk_add_f32 v[78:79], v[18:19], v[78:79]
	v_pk_add_f32 v[80:81], v[20:21], v[80:81]
	v_mul_f32_e32 v84, 0x3d372713, v78
	v_mul_f32_e32 v85, 0x3d372713, v79
	v_mul_f32_e32 v84, v78, v84
	v_mul_f32_e32 v85, v79, v85
	v_mul_f32_e32 v86, 0x3d372713, v80
	v_mul_f32_e32 v87, 0x3d372713, v81
	v_fma_f32 v84, v78, v84, v78
	v_fma_f32 v85, v79, v85, v79
	v_mul_f32_e32 v86, v80, v86
	v_mul_f32_e32 v87, v81, v87
	v_mul_f32_e32 v84, 0x3f4c422a, v84
	v_mul_f32_e32 v85, 0x3f4c422a, v85
	v_fma_f32 v86, v80, v86, v80
	v_fma_f32 v87, v81, v87, v81
	v_mul_f32_e32 v84, 0xc038aa3b, v84
	v_mul_f32_e32 v85, 0xc038aa3b, v85
	v_mul_f32_e32 v86, 0x3f4c422a, v86
	v_mul_f32_e32 v87, 0x3f4c422a, v87
	v_exp_f32_e32 v84, v84
	v_exp_f32_e32 v85, v85
	v_mul_f32_e32 v86, 0xc038aa3b, v86
	v_mul_f32_e32 v87, 0xc038aa3b, v87
	v_exp_f32_e32 v86, v86
	v_exp_f32_e32 v87, v87
	v_add_f32_e32 v84, 1.0, v84
	v_add_f32_e32 v85, 1.0, v85
	v_rcp_f32_e32 v84, v84
	v_rcp_f32_e32 v85, v85
	v_add_f32_e32 v86, 1.0, v86
	v_add_f32_e32 v87, 1.0, v87
	v_rcp_f32_e32 v86, v86
	v_rcp_f32_e32 v87, v87
	v_pk_mul_f32 v[78:79], v[78:79], v[84:85]
	s_nop 0
	v_pk_mul_f32 v[74:75], v[74:75], v[78:79]
	v_pk_mul_f32 v[78:79], v[80:81], v[86:87]
	v_cvt_pk_bf16_f32 v74, v74, v75
	v_pk_mul_f32 v[76:77], v[76:77], v[78:79]
	s_nop 0
	v_cvt_pk_bf16_f32 v75, v76, v77
	v_mad_i64_i32 v[76:77], s[58:59], v82, s85, v[106:107]
	global_store_dwordx2 v[76:77], v[74:75], off
.LBB0_110:
	s_or_b64 exec, exec, s[54:55]
	v_add_u32_e32 v75, s56, v168
	v_cmp_gt_i32_e32 vcc, s88, v75
	s_and_b64 s[54:55], s[40:41], vcc
	v_add_u32_e32 v74, s21, v75
	s_and_saveexec_b64 s[56:57], s[54:55]
	s_cbranch_execz .LBB0_112
	ds_read_b128 v[76:79], v172 offset:44800
	ds_read_b128 v[84:87], v173 offset:44544
	v_cmp_lt_i32_e32 vcc, 0, v75
	s_waitcnt lgkmcnt(0)
	s_nop 0
	v_cndmask_b32_e32 v79, 0, v79, vcc
	v_cndmask_b32_e32 v78, 0, v78, vcc
	v_cndmask_b32_e32 v77, 0, v77, vcc
	v_cndmask_b32_e32 v76, 0, v76, vcc
	v_cmp_lt_i32_e32 vcc, 1, v75
	v_pk_mul_f32 v[30:31], v[30:31], v[76:77]
	v_pk_mul_f32 v[32:33], v[32:33], v[78:79]
	v_cndmask_b32_e32 v81, 0, v87, vcc
	v_cndmask_b32_e32 v80, 0, v86, vcc
	v_cndmask_b32_e32 v85, 0, v85, vcc
	v_cndmask_b32_e32 v84, 0, v84, vcc
	v_pk_fma_f32 v[28:29], v[28:29], v[72:73], v[32:33]
	v_pk_fma_f32 v[26:27], v[26:27], v[70:71], v[30:31]
	v_pk_fma_f32 v[24:25], v[24:25], v[80:81], v[28:29]
	v_pk_fma_f32 v[22:23], v[22:23], v[84:85], v[26:27]
	v_pk_add_f32 v[20:21], v[20:21], v[24:25]
	v_pk_add_f32 v[18:19], v[18:19], v[22:23]
	v_mul_f32_e32 v24, 0x3d372713, v20
	v_mul_f32_e32 v22, 0x3d372713, v18
	v_mul_f32_e32 v23, 0x3d372713, v19
	v_mul_f32_e32 v25, 0x3d372713, v21
	v_mul_f32_e32 v22, v18, v22
	v_mul_f32_e32 v23, v19, v23
	v_mul_f32_e32 v24, v20, v24
	v_mul_f32_e32 v25, v21, v25
	v_fma_f32 v22, v18, v22, v18
	v_fma_f32 v23, v19, v23, v19
	v_fma_f32 v24, v20, v24, v20
	v_fma_f32 v25, v21, v25, v21
	v_mul_f32_e32 v22, 0x3f4c422a, v22
	v_mul_f32_e32 v23, 0x3f4c422a, v23
	v_mul_f32_e32 v24, 0x3f4c422a, v24
	v_mul_f32_e32 v25, 0x3f4c422a, v25
	v_mul_f32_e32 v22, 0xc038aa3b, v22
	v_mul_f32_e32 v23, 0xc038aa3b, v23
	v_mul_f32_e32 v24, 0xc038aa3b, v24
	v_mul_f32_e32 v25, 0xc038aa3b, v25
	v_exp_f32_e32 v22, v22
	v_exp_f32_e32 v23, v23
	v_exp_f32_e32 v24, v24
	v_exp_f32_e32 v25, v25
	v_add_f32_e32 v22, 1.0, v22
	v_add_f32_e32 v23, 1.0, v23
	v_add_f32_e32 v24, 1.0, v24
	v_add_f32_e32 v25, 1.0, v25
	v_rcp_f32_e32 v22, v22
	v_rcp_f32_e32 v23, v23
	v_rcp_f32_e32 v24, v24
	v_rcp_f32_e32 v25, v25
	v_pk_mul_f32 v[18:19], v[18:19], v[22:23]
	s_nop 0
	v_pk_mul_f32 v[18:19], v[62:63], v[18:19]
	v_pk_mul_f32 v[20:21], v[20:21], v[24:25]
	v_cvt_pk_bf16_f32 v18, v18, v19
	v_pk_mul_f32 v[20:21], v[64:65], v[20:21]
	s_nop 0
	v_cvt_pk_bf16_f32 v19, v20, v21
	v_mad_i64_i32 v[20:21], s[58:59], v74, s85, v[106:107]
	global_store_dwordx2 v[20:21], v[18:19], off
.LBB0_112:
	s_or_b64 exec, exec, s[56:57]
	v_or_b32_e32 v18, s20, v169
	v_ashrrev_i32_e32 v19, 31, v18
	v_lshl_add_u64 v[18:19], v[18:19], 1, s[36:37]
	s_and_saveexec_b64 s[56:57], s[48:49]
	s_cbranch_execz .LBB0_116
	ds_read_b128 v[20:23], v174 offset:32512
	ds_read_b128 v[24:27], v175 offset:32256
	v_cmp_lt_i32_e32 vcc, 0, v108
	s_waitcnt lgkmcnt(0)
	s_nop 0
	v_cndmask_b32_e32 v23, 0, v23, vcc
	v_cndmask_b32_e32 v22, 0, v22, vcc
	v_cndmask_b32_e32 v21, 0, v21, vcc
	v_cndmask_b32_e32 v20, 0, v20, vcc
	v_cmp_lt_i32_e32 vcc, 1, v108
	v_pk_mul_f32 v[20:21], v[14:15], v[20:21]
	v_pk_mul_f32 v[22:23], v[16:17], v[22:23]
	v_cndmask_b32_e32 v27, 0, v27, vcc
	v_cndmask_b32_e32 v26, 0, v26, vcc
	v_cndmask_b32_e32 v25, 0, v25, vcc
	v_cndmask_b32_e32 v24, 0, v24, vcc
	v_pk_fma_f32 v[22:23], v[12:13], v[68:69], v[22:23]
	v_pk_fma_f32 v[20:21], v[10:11], v[66:67], v[20:21]
	v_pk_fma_f32 v[22:23], v[8:9], v[26:27], v[22:23]
	v_pk_fma_f32 v[20:21], v[6:7], v[24:25], v[20:21]
	v_pk_add_f32 v[22:23], v[4:5], v[22:23]
	v_pk_add_f32 v[20:21], v[2:3], v[20:21]
	v_mul_f32_e32 v26, 0x3d372713, v22
	v_mul_f32_e32 v24, 0x3d372713, v20
	v_mul_f32_e32 v25, 0x3d372713, v21
	v_mul_f32_e32 v27, 0x3d372713, v23
	v_mul_f32_e32 v24, v20, v24
	v_mul_f32_e32 v25, v21, v25
	v_mul_f32_e32 v26, v22, v26
	v_mul_f32_e32 v27, v23, v27
	v_fma_f32 v24, v20, v24, v20
	v_fma_f32 v25, v21, v25, v21
	v_fma_f32 v26, v22, v26, v22
	v_fma_f32 v27, v23, v27, v23
	v_mul_f32_e32 v24, 0x3f4c422a, v24
	v_mul_f32_e32 v25, 0x3f4c422a, v25
	v_mul_f32_e32 v26, 0x3f4c422a, v26
	v_mul_f32_e32 v27, 0x3f4c422a, v27
	v_mul_f32_e32 v24, 0xc038aa3b, v24
	v_mul_f32_e32 v25, 0xc038aa3b, v25
	v_mul_f32_e32 v26, 0xc038aa3b, v26
	v_mul_f32_e32 v27, 0xc038aa3b, v27
	v_exp_f32_e32 v24, v24
	v_exp_f32_e32 v25, v25
	v_exp_f32_e32 v26, v26
	v_exp_f32_e32 v27, v27
	v_add_f32_e32 v24, 1.0, v24
	v_add_f32_e32 v25, 1.0, v25
	v_add_f32_e32 v26, 1.0, v26
	v_add_f32_e32 v27, 1.0, v27
	v_rcp_f32_e32 v24, v24
	v_rcp_f32_e32 v25, v25
	v_rcp_f32_e32 v26, v26
	v_rcp_f32_e32 v27, v27
	v_pk_mul_f32 v[20:21], v[20:21], v[24:25]
	s_nop 0
	v_pk_mul_f32 v[20:21], v[58:59], v[20:21]
	v_pk_mul_f32 v[22:23], v[22:23], v[26:27]
	v_cvt_pk_bf16_f32 v20, v20, v21
	v_pk_mul_f32 v[22:23], v[60:61], v[22:23]
	s_nop 0
	v_cvt_pk_bf16_f32 v21, v22, v23
	v_mad_i64_i32 v[22:23], s[20:21], v0, s85, v[18:19]
	global_store_dwordx2 v[22:23], v[20:21], off
	s_or_b64 exec, exec, s[56:57]
	s_and_saveexec_b64 s[48:49], s[50:51]
	s_cbranch_execnz .LBB0_117

.LBB0_115:
	ds_read_b128 v[20:23], v174 offset:40704
	ds_read_b128 v[24:27], v175 offset:40448
	v_cmp_lt_i32_e32 vcc, 0, v83
	s_waitcnt lgkmcnt(0)
	s_nop 0
	v_cndmask_b32_e32 v21, 0, v21, vcc
	v_cndmask_b32_e32 v20, 0, v20, vcc
	v_cndmask_b32_e32 v23, 0, v23, vcc
	v_cndmask_b32_e32 v22, 0, v22, vcc
	v_cmp_lt_i32_e32 vcc, 1, v83
	v_pk_mul_f32 v[20:21], v[14:15], v[20:21]
	v_pk_mul_f32 v[22:23], v[16:17], v[22:23]
	v_cndmask_b32_e32 v25, 0, v25, vcc
	v_cndmask_b32_e32 v24, 0, v24, vcc
	v_pk_fma_f32 v[20:21], v[10:11], v[46:47], v[20:21]
	v_cndmask_b32_e32 v27, 0, v27, vcc
	v_pk_fma_f32 v[20:21], v[6:7], v[24:25], v[20:21]
	v_cndmask_b32_e32 v26, 0, v26, vcc
	v_pk_add_f32 v[20:21], v[2:3], v[20:21]
	v_pk_fma_f32 v[22:23], v[12:13], v[48:49], v[22:23]
	v_mul_f32_e32 v0, 0x3d372713, v20
	v_mul_f32_e32 v0, v20, v0
	v_mul_f32_e32 v24, 0x3d372713, v21
	v_fma_f32 v0, v20, v0, v20
	v_mul_f32_e32 v24, v21, v24
	v_mul_f32_e32 v0, 0x3f4c422a, v0
	v_fma_f32 v24, v21, v24, v21
	v_mul_f32_e32 v0, 0xc038aa3b, v0
	v_mul_f32_e32 v24, 0x3f4c422a, v24
	v_exp_f32_e32 v0, v0
	v_mul_f32_e32 v24, 0xc038aa3b, v24
	v_exp_f32_e32 v25, v24
	v_pk_fma_f32 v[22:23], v[8:9], v[26:27], v[22:23]
	v_add_f32_e32 v0, 1.0, v0
	v_pk_add_f32 v[22:23], v[4:5], v[22:23]
	v_rcp_f32_e32 v24, v0
	v_add_f32_e32 v0, 1.0, v25
	v_mul_f32_e32 v25, 0x3d372713, v22
	v_mul_f32_e32 v25, v22, v25
	v_fma_f32 v25, v22, v25, v22
	v_mul_f32_e32 v25, 0x3f4c422a, v25
	v_mul_f32_e32 v25, 0xc038aa3b, v25
	v_exp_f32_e32 v26, v25
	v_mul_f32_e32 v25, 0x3d372713, v23
	v_mul_f32_e32 v25, v23, v25
	v_fma_f32 v25, v23, v25, v23
	v_mul_f32_e32 v25, 0x3f4c422a, v25
	v_mul_f32_e32 v25, 0xc038aa3b, v25
	v_exp_f32_e32 v27, v25
	v_rcp_f32_e32 v25, v0
	v_add_f32_e32 v0, 1.0, v26
	v_rcp_f32_e32 v26, v0
	v_add_f32_e32 v0, 1.0, v27
	v_rcp_f32_e32 v27, v0
	v_pk_mul_f32 v[20:21], v[20:21], v[24:25]
	v_pk_mul_f32 v[22:23], v[22:23], v[26:27]
	v_pk_mul_f32 v[20:21], v[42:43], v[20:21]
	v_pk_mul_f32 v[22:23], v[44:45], v[22:23]
	v_cvt_pk_bf16_f32 v20, v20, v21
	v_cvt_pk_bf16_f32 v21, v22, v23
	v_mad_i64_i32 v[22:23], s[20:21], v82, s85, v[18:19]
	global_store_dwordx2 v[22:23], v[20:21], off
	s_or_b64 exec, exec, s[48:49]
	s_and_saveexec_b64 s[48:49], s[54:55]
	s_cbranch_execz .LBB0_84
	s_branch .LBB0_119

.LBB0_117:
	ds_read_b128 v[20:23], v174 offset:36608
	ds_read_b128 v[24:27], v175 offset:36352
	v_cmp_lt_i32_e32 vcc, 0, v91
	s_waitcnt lgkmcnt(0)
	s_nop 0
	v_cndmask_b32_e32 v21, 0, v21, vcc
	v_cndmask_b32_e32 v20, 0, v20, vcc
	v_cndmask_b32_e32 v23, 0, v23, vcc
	v_cndmask_b32_e32 v22, 0, v22, vcc
	v_cmp_lt_i32_e32 vcc, 1, v91
	v_pk_mul_f32 v[20:21], v[14:15], v[20:21]
	v_pk_mul_f32 v[22:23], v[16:17], v[22:23]
	v_cndmask_b32_e32 v25, 0, v25, vcc
	v_cndmask_b32_e32 v24, 0, v24, vcc
	v_pk_fma_f32 v[20:21], v[10:11], v[54:55], v[20:21]
	v_cndmask_b32_e32 v27, 0, v27, vcc
	v_pk_fma_f32 v[20:21], v[6:7], v[24:25], v[20:21]
	v_cndmask_b32_e32 v26, 0, v26, vcc
	v_pk_add_f32 v[20:21], v[2:3], v[20:21]
	v_pk_fma_f32 v[22:23], v[12:13], v[56:57], v[22:23]
	v_mul_f32_e32 v0, 0x3d372713, v20
	v_mul_f32_e32 v0, v20, v0
	v_mul_f32_e32 v24, 0x3d372713, v21
	v_fma_f32 v0, v20, v0, v20
	v_mul_f32_e32 v24, v21, v24
	v_mul_f32_e32 v0, 0x3f4c422a, v0
	v_fma_f32 v24, v21, v24, v21
	v_mul_f32_e32 v0, 0xc038aa3b, v0
	v_mul_f32_e32 v24, 0x3f4c422a, v24
	v_exp_f32_e32 v0, v0
	v_mul_f32_e32 v24, 0xc038aa3b, v24
	v_exp_f32_e32 v25, v24
	v_pk_fma_f32 v[22:23], v[8:9], v[26:27], v[22:23]
	v_add_f32_e32 v0, 1.0, v0
	v_pk_add_f32 v[22:23], v[4:5], v[22:23]
	v_rcp_f32_e32 v24, v0
	v_add_f32_e32 v0, 1.0, v25
	v_mul_f32_e32 v25, 0x3d372713, v22
	v_mul_f32_e32 v25, v22, v25
	v_fma_f32 v25, v22, v25, v22
	v_mul_f32_e32 v25, 0x3f4c422a, v25
	v_mul_f32_e32 v25, 0xc038aa3b, v25
	v_exp_f32_e32 v26, v25
	v_mul_f32_e32 v25, 0x3d372713, v23
	v_mul_f32_e32 v25, v23, v25
	v_fma_f32 v25, v23, v25, v23
	v_mul_f32_e32 v25, 0x3f4c422a, v25
	v_mul_f32_e32 v25, 0xc038aa3b, v25
	v_exp_f32_e32 v27, v25
	v_rcp_f32_e32 v25, v0
	v_add_f32_e32 v0, 1.0, v26
	v_rcp_f32_e32 v26, v0
	v_add_f32_e32 v0, 1.0, v27
	v_rcp_f32_e32 v27, v0
	v_pk_mul_f32 v[20:21], v[20:21], v[24:25]
	v_pk_mul_f32 v[22:23], v[22:23], v[26:27]
	v_pk_mul_f32 v[20:21], v[50:51], v[20:21]
	v_pk_mul_f32 v[22:23], v[52:53], v[22:23]
	v_cvt_pk_bf16_f32 v20, v20, v21
	v_cvt_pk_bf16_f32 v21, v22, v23
	v_mad_i64_i32 v[22:23], s[20:21], v90, s85, v[18:19]
	global_store_dwordx2 v[22:23], v[20:21], off
	s_or_b64 exec, exec, s[48:49]
	s_and_saveexec_b64 s[48:49], s[52:53]
	s_cbranch_execnz .LBB0_115

.LBB0_119:
	ds_read_b128 v[20:23], v174 offset:44800
	ds_read_b128 v[24:27], v175 offset:44544
	v_cmp_lt_i32_e32 vcc, 0, v75
	s_waitcnt lgkmcnt(0)
	s_nop 0
	v_cndmask_b32_e32 v21, 0, v21, vcc
	v_cndmask_b32_e32 v20, 0, v20, vcc
	v_cndmask_b32_e32 v23, 0, v23, vcc
	v_cndmask_b32_e32 v22, 0, v22, vcc
	v_cmp_lt_i32_e32 vcc, 1, v75
	v_pk_mul_f32 v[14:15], v[14:15], v[20:21]
	v_pk_mul_f32 v[16:17], v[16:17], v[22:23]
	v_cndmask_b32_e32 v25, 0, v25, vcc
	v_cndmask_b32_e32 v24, 0, v24, vcc
	v_pk_fma_f32 v[10:11], v[10:11], v[38:39], v[14:15]
	v_cndmask_b32_e32 v27, 0, v27, vcc
	v_pk_fma_f32 v[6:7], v[6:7], v[24:25], v[10:11]
	v_cndmask_b32_e32 v26, 0, v26, vcc
	v_pk_add_f32 v[2:3], v[2:3], v[6:7]
	v_pk_fma_f32 v[12:13], v[12:13], v[40:41], v[16:17]
	v_mul_f32_e32 v0, 0x3d372713, v2
	v_mul_f32_e32 v0, v2, v0
	v_mul_f32_e32 v6, 0x3d372713, v3
	v_fma_f32 v0, v2, v0, v2
	v_mul_f32_e32 v6, v3, v6
	v_mul_f32_e32 v0, 0x3f4c422a, v0
	v_fma_f32 v6, v3, v6, v3
	v_mul_f32_e32 v0, 0xc038aa3b, v0
	v_mul_f32_e32 v6, 0x3f4c422a, v6
	v_exp_f32_e32 v0, v0
	v_mul_f32_e32 v6, 0xc038aa3b, v6
	v_exp_f32_e32 v7, v6
	v_pk_fma_f32 v[8:9], v[8:9], v[26:27], v[12:13]
	v_add_f32_e32 v0, 1.0, v0
	v_pk_add_f32 v[4:5], v[4:5], v[8:9]
	v_rcp_f32_e32 v6, v0
	v_add_f32_e32 v0, 1.0, v7
	v_mul_f32_e32 v7, 0x3d372713, v4
	v_mul_f32_e32 v7, v4, v7
	v_fma_f32 v7, v4, v7, v4
	v_mul_f32_e32 v7, 0x3f4c422a, v7
	v_mul_f32_e32 v7, 0xc038aa3b, v7
	v_exp_f32_e32 v8, v7
	v_mul_f32_e32 v7, 0x3d372713, v5
	v_mul_f32_e32 v7, v5, v7
	v_fma_f32 v7, v5, v7, v5
	v_mul_f32_e32 v7, 0x3f4c422a, v7
	v_mul_f32_e32 v7, 0xc038aa3b, v7
	v_exp_f32_e32 v9, v7
	v_rcp_f32_e32 v7, v0
	v_add_f32_e32 v0, 1.0, v8
	v_rcp_f32_e32 v8, v0
	v_add_f32_e32 v0, 1.0, v9
	v_rcp_f32_e32 v9, v0
	v_pk_mul_f32 v[2:3], v[2:3], v[6:7]
	v_pk_mul_f32 v[4:5], v[4:5], v[8:9]
	v_pk_mul_f32 v[2:3], v[34:35], v[2:3]
	v_pk_mul_f32 v[4:5], v[36:37], v[4:5]
	v_cvt_pk_bf16_f32 v2, v2, v3
	v_cvt_pk_bf16_f32 v3, v4, v5
	v_mad_i64_i32 v[4:5], s[20:21], v74, s85, v[18:19]
	global_store_dwordx2 v[4:5], v[2:3], off
	s_branch .LBB0_84

.LBB0_150:
	s_and_b64 vcc, exec, s[40:41]
	s_cbranch_vccnz .LBB0_152
	s_waitcnt vmcnt(2)
	v_mov_b32_e32 v150, v59
	v_mov_b32_e32 v151, v63
	v_mov_b32_e32 v148, v58
	v_mov_b32_e32 v149, v62
	v_pk_mul_f32 v[150:151], v[150:151], v[150:151]
	s_waitcnt vmcnt(0)
	v_mov_b32_e32 v152, v51
	v_pk_fma_f32 v[148:149], v[148:149], v[148:149], v[150:151]
	v_mov_b32_e32 v150, v60
	v_mov_b32_e32 v151, v64
	v_pk_fma_f32 v[148:149], v[150:151], v[150:151], v[148:149]
	v_mov_b32_e32 v150, v61
	v_mov_b32_e32 v151, v65
	v_mov_b32_e32 v153, v55
	v_pk_fma_f32 v[148:149], v[150:151], v[150:151], v[148:149]
	v_mov_b32_e32 v150, v50
	v_mov_b32_e32 v151, v54
	v_pk_mul_f32 v[152:153], v[152:153], v[152:153]
	v_and_b32_e32 v101, 64, v159
	v_pk_fma_f32 v[150:151], v[150:151], v[150:151], v[152:153]
	v_mov_b32_e32 v152, v52
	v_mov_b32_e32 v153, v56
	v_pk_fma_f32 v[150:151], v[152:153], v[152:153], v[150:151]
	v_mov_b32_e32 v152, v53
	v_mov_b32_e32 v153, v57
	v_add_u32_e32 v101, 64, v101
	v_xor_b32_e32 v103, 32, v159
	v_pk_fma_f32 v[150:151], v[152:153], v[152:153], v[150:151]
	v_add_f32_e32 v99, v148, v149
	v_cmp_lt_i32_e32 vcc, v103, v101
	v_add_f32_e32 v99, v151, v99
	v_add_f32_e32 v99, v150, v99
	v_cndmask_b32_e32 v103, v159, v103, vcc
	v_lshlrev_b32_e32 v103, 2, v103
	ds_bpermute_b32 v103, v103, v99
	v_lshl_add_u64 v[150:151], s[26:27], 0, v[130:131]
	s_waitcnt lgkmcnt(0)
	v_add_f32_e32 v99, v99, v103
	v_xor_b32_e32 v103, 16, v159
	v_cmp_lt_i32_e32 vcc, v103, v101
	s_nop 1
	v_cndmask_b32_e32 v103, v159, v103, vcc
	v_lshlrev_b32_e32 v103, 2, v103
	ds_bpermute_b32 v103, v103, v99
	s_waitcnt lgkmcnt(0)
	v_add_f32_e32 v99, v99, v103
	v_xor_b32_e32 v103, 8, v159
	v_cmp_lt_i32_e32 vcc, v103, v101
	s_nop 1
	v_cndmask_b32_e32 v103, v159, v103, vcc
	v_lshlrev_b32_e32 v103, 2, v103
	ds_bpermute_b32 v103, v103, v99
	s_waitcnt lgkmcnt(0)
	v_add_f32_e32 v99, v99, v103
	v_xor_b32_e32 v103, 4, v159
	v_cmp_lt_i32_e32 vcc, v103, v101
	s_nop 1
	v_cndmask_b32_e32 v103, v159, v103, vcc
	v_lshlrev_b32_e32 v103, 2, v103
	ds_bpermute_b32 v103, v103, v99
	s_waitcnt lgkmcnt(0)
	v_add_f32_e32 v99, v99, v103
	v_xor_b32_e32 v103, 2, v159
	v_cmp_lt_i32_e32 vcc, v103, v101
	s_nop 1
	v_cndmask_b32_e32 v103, v159, v103, vcc
	v_lshlrev_b32_e32 v103, 2, v103
	ds_bpermute_b32 v103, v103, v99
	s_waitcnt lgkmcnt(0)
	v_add_f32_e32 v99, v99, v103
	v_xor_b32_e32 v103, 1, v159
	v_cmp_lt_i32_e32 vcc, v103, v101
	s_nop 1
	v_cndmask_b32_e32 v101, v159, v103, vcc
	v_lshlrev_b32_e32 v101, 2, v101
	ds_bpermute_b32 v101, v101, v99
	s_waitcnt lgkmcnt(0)
	v_add_f32_e32 v99, v99, v101
	v_fmamk_f32 v99, v99, 0x3a800000, v155
	v_mul_f32_e32 v101, 0x4b800000, v99
	v_cmp_gt_f32_e32 vcc, s84, v99
	s_nop 1
	v_cndmask_b32_e32 v99, v99, v101, vcc
	v_rsq_f32_e32 v99, v99
	s_nop 0
	v_mul_f32_e32 v101, 0x45800000, v99
	v_cndmask_b32_e32 v148, v99, v101, vcc
	v_pk_mul_f32 v[64:65], v[64:65], v[148:149] op_sel_hi:[1,0]
	v_pk_mul_f32 v[62:63], v[62:63], v[148:149] op_sel_hi:[1,0]
	v_pk_mul_f32 v[60:61], v[60:61], v[148:149] op_sel_hi:[1,0]
	v_pk_mul_f32 v[58:59], v[58:59], v[148:149] op_sel_hi:[1,0]
	v_pk_mul_f32 v[56:57], v[56:57], v[148:149] op_sel_hi:[1,0]
	v_pk_mul_f32 v[54:55], v[54:55], v[148:149] op_sel_hi:[1,0]
	v_pk_mul_f32 v[52:53], v[52:53], v[148:149] op_sel_hi:[1,0]
	v_pk_mul_f32 v[50:51], v[50:51], v[148:149] op_sel_hi:[1,0]
	v_pk_mul_f32 v[62:63], v[6:7], v[62:63]
	v_pk_mul_f32 v[64:65], v[8:9], v[64:65]
	v_pk_mul_f32 v[58:59], v[14:15], v[58:59]
	v_pk_mul_f32 v[60:61], v[16:17], v[60:61]
	v_pk_mul_f32 v[54:55], v[22:23], v[54:55]
	v_pk_mul_f32 v[56:57], v[24:25], v[56:57]
	v_pk_mul_f32 v[50:51], v[30:31], v[50:51]
	v_pk_mul_f32 v[52:53], v[32:33], v[52:53]
	v_pk_fma_f32 v[64:65], v[72:73], v[64:65], v[76:77]
	v_pk_fma_f32 v[62:63], v[70:71], v[62:63], v[74:75]
	v_pk_fma_f32 v[60:61], v[84:85], v[60:61], v[88:89]
	v_pk_fma_f32 v[58:59], v[82:83], v[58:59], v[86:87]
	v_pk_fma_f32 v[56:57], v[96:97], v[56:57], v[108:109]
	v_pk_fma_f32 v[54:55], v[94:95], v[54:55], v[106:107]
	v_pk_fma_f32 v[52:53], v[116:117], v[52:53], v[120:121]
	v_pk_fma_f32 v[50:51], v[114:115], v[50:51], v[118:119]
	v_cvt_pk_bf16_f32 v62, v62, v63
	v_cvt_pk_bf16_f32 v63, v64, v65
	v_cvt_pk_bf16_f32 v58, v58, v59
	v_cvt_pk_bf16_f32 v59, v60, v61
	v_cvt_pk_bf16_f32 v54, v54, v55
	v_cvt_pk_bf16_f32 v55, v56, v57
	v_cvt_pk_bf16_f32 v50, v50, v51
	v_cvt_pk_bf16_f32 v51, v52, v53
	v_readlane_b32 vcc_lo, v244, 60
	v_readlane_b32 vcc_hi, v244, 61
	s_nop 3
	v_subrev_u32_e32 v64, vcc_lo, v150
	v_and_b32_e32 v60, 0x7ff, v64
	v_lshrrev_b32_e32 v64, 11, v64
	v_lshlrev_b32_e32 v64, 6, v64
	v_lshrrev_b32_e32 v61, 6, v60
	v_lshl_or_b32 v64, v61, 20, v64
	v_and_or_b32 v64, v60, 63, v64
	v_mov_b32_e32 v65, 0
	v_lshl_add_u64 v[64:65], vcc, 0, v[64:65]
	global_store_dwordx2 v[64:65], v[62:63], off
	v_subrev_u32_e32 v64, vcc_lo, v150
	v_add_u32_e32 v64, 0x200, v64
	v_and_b32_e32 v60, 0x7ff, v64
	v_lshrrev_b32_e32 v64, 11, v64
	v_lshlrev_b32_e32 v64, 6, v64
	v_lshrrev_b32_e32 v61, 6, v60
	v_lshl_or_b32 v64, v61, 20, v64
	v_and_or_b32 v64, v60, 63, v64
	v_mov_b32_e32 v65, 0
	v_lshl_add_u64 v[64:65], vcc, 0, v[64:65]
	global_store_dwordx2 v[64:65], v[58:59], off
	v_subrev_u32_e32 v64, vcc_lo, v150
	v_add_u32_e32 v64, 0x400, v64
	v_and_b32_e32 v60, 0x7ff, v64
	v_lshrrev_b32_e32 v64, 11, v64
	v_lshlrev_b32_e32 v64, 6, v64
	v_lshrrev_b32_e32 v61, 6, v60
	v_lshl_or_b32 v64, v61, 20, v64
	v_and_or_b32 v64, v60, 63, v64
	v_mov_b32_e32 v65, 0
	v_lshl_add_u64 v[64:65], vcc, 0, v[64:65]
	global_store_dwordx2 v[64:65], v[54:55], off
	v_subrev_u32_e32 v64, vcc_lo, v150
	v_add_u32_e32 v64, 0x600, v64
	v_and_b32_e32 v60, 0x7ff, v64
	v_lshrrev_b32_e32 v64, 11, v64
	v_lshlrev_b32_e32 v64, 6, v64
	v_lshrrev_b32_e32 v61, 6, v60
	v_lshl_or_b32 v64, v61, 20, v64
	v_and_or_b32 v64, v60, 63, v64
	v_mov_b32_e32 v65, 0
	v_lshl_add_u64 v[64:65], vcc, 0, v[64:65]
	global_store_dwordx2 v[64:65], v[50:51], off

.LBB0_155:
	s_and_b64 vcc, exec, s[40:41]
	s_cbranch_vccnz .LBB0_142
	s_waitcnt vmcnt(0)
	v_mov_b32_e32 v52, v39
	v_mov_b32_e32 v53, v35
	v_mov_b32_e32 v50, v38
	v_mov_b32_e32 v51, v34
	v_pk_mul_f32 v[52:53], v[52:53], v[52:53]
	v_mov_b32_e32 v54, v47
	v_pk_fma_f32 v[50:51], v[50:51], v[50:51], v[52:53]
	v_mov_b32_e32 v52, v40
	v_mov_b32_e32 v53, v36
	v_pk_fma_f32 v[50:51], v[52:53], v[52:53], v[50:51]
	v_mov_b32_e32 v52, v41
	v_mov_b32_e32 v53, v37
	v_mov_b32_e32 v55, v43
	v_pk_fma_f32 v[50:51], v[52:53], v[52:53], v[50:51]
	v_mov_b32_e32 v52, v46
	v_mov_b32_e32 v53, v42
	v_pk_mul_f32 v[54:55], v[54:55], v[54:55]
	v_add_f32_e32 v50, v50, v51
	v_pk_fma_f32 v[52:53], v[52:53], v[52:53], v[54:55]
	v_mov_b32_e32 v54, v48
	v_mov_b32_e32 v55, v44
	v_pk_fma_f32 v[52:53], v[54:55], v[54:55], v[52:53]
	v_mov_b32_e32 v54, v49
	v_mov_b32_e32 v55, v45
	v_pk_fma_f32 v[52:53], v[54:55], v[54:55], v[52:53]
	v_and_b32_e32 v51, 64, v159
	v_add_f32_e32 v50, v53, v50
	v_add_f32_e32 v50, v52, v50
	v_add_u32_e32 v51, 64, v51
	v_xor_b32_e32 v52, 32, v159
	v_cmp_lt_i32_e32 vcc, v52, v51
	s_ashr_i32 s35, s34, 31
	s_lshl_b64 s[20:21], s[34:35], 11
	v_cndmask_b32_e32 v52, v159, v52, vcc
	v_lshlrev_b32_e32 v52, 2, v52
	ds_bpermute_b32 v52, v52, v50
	s_waitcnt lgkmcnt(0)
	v_add_f32_e32 v50, v50, v52
	v_xor_b32_e32 v52, 16, v159
	v_cmp_lt_i32_e32 vcc, v52, v51
	s_nop 1
	v_cndmask_b32_e32 v52, v159, v52, vcc
	v_lshlrev_b32_e32 v52, 2, v52
	ds_bpermute_b32 v52, v52, v50
	s_waitcnt lgkmcnt(0)
	v_add_f32_e32 v50, v50, v52
	v_xor_b32_e32 v52, 8, v159
	v_cmp_lt_i32_e32 vcc, v52, v51
	s_nop 1
	v_cndmask_b32_e32 v52, v159, v52, vcc
	v_lshlrev_b32_e32 v52, 2, v52
	ds_bpermute_b32 v52, v52, v50
	s_waitcnt lgkmcnt(0)
	v_add_f32_e32 v50, v50, v52
	v_xor_b32_e32 v52, 4, v159
	v_cmp_lt_i32_e32 vcc, v52, v51
	s_nop 1
	v_cndmask_b32_e32 v52, v159, v52, vcc
	v_lshlrev_b32_e32 v52, 2, v52
	ds_bpermute_b32 v52, v52, v50
	s_waitcnt lgkmcnt(0)
	v_add_f32_e32 v50, v50, v52
	v_xor_b32_e32 v52, 2, v159
	v_cmp_lt_i32_e32 vcc, v52, v51
	s_nop 1
	v_cndmask_b32_e32 v52, v159, v52, vcc
	v_lshlrev_b32_e32 v52, 2, v52
	ds_bpermute_b32 v52, v52, v50
	s_waitcnt lgkmcnt(0)
	v_add_f32_e32 v50, v50, v52
	v_xor_b32_e32 v52, 1, v159
	v_cmp_lt_i32_e32 vcc, v52, v51
	s_nop 1
	v_cndmask_b32_e32 v51, v159, v52, vcc
	v_lshlrev_b32_e32 v51, 2, v51
	ds_bpermute_b32 v51, v51, v50
	v_lshl_add_u64 v[52:53], v[128:129], 0, s[20:21]
	s_waitcnt lgkmcnt(0)
	v_add_f32_e32 v50, v50, v51
	v_fmamk_f32 v50, v50, 0x3a800000, v155
	v_mul_f32_e32 v51, 0x4b800000, v50
	v_cmp_gt_f32_e32 vcc, s84, v50
	s_nop 1
	v_cndmask_b32_e32 v50, v50, v51, vcc
	v_rsq_f32_e32 v50, v50
	s_nop 0
	v_mul_f32_e32 v51, 0x45800000, v50
	v_cndmask_b32_e32 v50, v50, v51, vcc
	v_pk_mul_f32 v[54:55], v[36:37], v[50:51] op_sel_hi:[1,0]
	v_pk_mul_f32 v[56:57], v[34:35], v[50:51] op_sel_hi:[1,0]
	v_pk_mul_f32 v[54:55], v[8:9], v[54:55]
	v_pk_mul_f32 v[56:57], v[6:7], v[56:57]
	v_pk_fma_f32 v[54:55], v[72:73], v[54:55], v[76:77]
	v_pk_fma_f32 v[56:57], v[70:71], v[56:57], v[74:75]
	s_nop 0
	v_cvt_pk_bf16_f32 v56, v56, v57
	v_cvt_pk_bf16_f32 v57, v54, v55
	v_readlane_b32 vcc_lo, v244, 60
	v_readlane_b32 vcc_hi, v244, 61
	s_nop 3
	v_subrev_u32_e32 v34, vcc_lo, v52
	v_and_b32_e32 v36, 0x7ff, v34
	v_lshrrev_b32_e32 v34, 11, v34
	v_lshlrev_b32_e32 v34, 6, v34
	v_lshrrev_b32_e32 v37, 6, v36
	v_lshl_or_b32 v34, v37, 20, v34
	v_and_or_b32 v34, v36, 63, v34
	v_mov_b32_e32 v35, 0
	v_lshl_add_u64 v[34:35], vcc, 0, v[34:35]
	global_store_dwordx2 v[34:35], v[56:57], off
	v_pk_mul_f32 v[54:55], v[40:41], v[50:51] op_sel_hi:[1,0]
	v_pk_mul_f32 v[56:57], v[38:39], v[50:51] op_sel_hi:[1,0]
	v_pk_mul_f32 v[54:55], v[16:17], v[54:55]
	v_pk_mul_f32 v[56:57], v[14:15], v[56:57]
	v_pk_fma_f32 v[54:55], v[84:85], v[54:55], v[88:89]
	v_pk_fma_f32 v[56:57], v[82:83], v[56:57], v[86:87]
	s_nop 0
	v_cvt_pk_bf16_f32 v56, v56, v57
	v_cvt_pk_bf16_f32 v57, v54, v55
	v_subrev_u32_e32 v34, vcc_lo, v52
	v_add_u32_e32 v34, 0x200, v34
	v_and_b32_e32 v36, 0x7ff, v34
	v_lshrrev_b32_e32 v34, 11, v34
	v_lshlrev_b32_e32 v34, 6, v34
	v_lshrrev_b32_e32 v37, 6, v36
	v_lshl_or_b32 v34, v37, 20, v34
	v_and_or_b32 v34, v36, 63, v34
	v_mov_b32_e32 v35, 0
	v_lshl_add_u64 v[34:35], vcc, 0, v[34:35]
	global_store_dwordx2 v[34:35], v[56:57], off
	v_pk_mul_f32 v[54:55], v[44:45], v[50:51] op_sel_hi:[1,0]
	v_pk_mul_f32 v[56:57], v[42:43], v[50:51] op_sel_hi:[1,0]
	v_pk_mul_f32 v[54:55], v[24:25], v[54:55]
	v_pk_mul_f32 v[56:57], v[22:23], v[56:57]
	v_pk_fma_f32 v[54:55], v[96:97], v[54:55], v[108:109]
	v_pk_fma_f32 v[56:57], v[94:95], v[56:57], v[106:107]
	s_nop 0
	v_cvt_pk_bf16_f32 v56, v56, v57
	v_cvt_pk_bf16_f32 v57, v54, v55
	v_pk_mul_f32 v[54:55], v[48:49], v[50:51] op_sel_hi:[1,0]
	v_pk_mul_f32 v[50:51], v[46:47], v[50:51] op_sel_hi:[1,0]
	v_pk_mul_f32 v[54:55], v[32:33], v[54:55]
	v_pk_mul_f32 v[50:51], v[30:31], v[50:51]
	v_pk_fma_f32 v[54:55], v[116:117], v[54:55], v[120:121]
	v_pk_fma_f32 v[50:51], v[114:115], v[50:51], v[118:119]
	v_subrev_u32_e32 v34, vcc_lo, v52
	v_add_u32_e32 v34, 0x400, v34
	v_and_b32_e32 v36, 0x7ff, v34
	v_lshrrev_b32_e32 v34, 11, v34
	v_lshlrev_b32_e32 v34, 6, v34
	v_lshrrev_b32_e32 v37, 6, v36
	v_lshl_or_b32 v34, v37, 20, v34
	v_and_or_b32 v34, v36, 63, v34
	v_mov_b32_e32 v35, 0
	v_lshl_add_u64 v[34:35], vcc, 0, v[34:35]
	global_store_dwordx2 v[34:35], v[56:57], off
	v_cvt_pk_bf16_f32 v50, v50, v51
	v_cvt_pk_bf16_f32 v51, v54, v55
	v_subrev_u32_e32 v34, vcc_lo, v52
	v_add_u32_e32 v34, 0x600, v34
	v_and_b32_e32 v36, 0x7ff, v34
	v_lshrrev_b32_e32 v34, 11, v34
	v_lshlrev_b32_e32 v34, 6, v34
	v_lshrrev_b32_e32 v37, 6, v36
	v_lshl_or_b32 v34, v37, 20, v34
	v_and_or_b32 v34, v36, 63, v34
	v_mov_b32_e32 v35, 0
	v_lshl_add_u64 v[34:35], vcc, 0, v[34:35]
	global_store_dwordx2 v[34:35], v[50:51], off
	s_branch .LBB0_142

.LBB0_355:
	v_lshlrev_b32_e32 v0, 2, v31
	v_add3_u32 v19, s59, v0, v33
	v_add3_u32 v0, s59, v33, v0
	ds_read2_b32 v[24:25], v19 offset1:130
	ds_read2_b32 v[34:35], v0 offset0:65 offset1:195
	v_add_u32_e32 v36, 0x400, v0
	ds_read2_b32 v[36:37], v36 offset0:69 offset1:199
	v_add_u32_e32 v38, 0x800, v0
	ds_read2_b32 v[38:39], v38 offset0:73 offset1:203
	s_waitcnt lgkmcnt(2)
	v_cvt_pk_bf16_f32 v34, v24, v34
	v_add_u32_e32 v24, 0x400, v19
	v_cvt_pk_bf16_f32 v35, v25, v35
	ds_read2_b32 v[24:25], v24 offset0:4 offset1:134
	v_add_u32_e32 v0, 0xc00, v0
	ds_read2_b32 v[40:41], v0 offset0:77 offset1:207
	v_add_u32_e32 v0, s21, v31
	s_add_i32 s19, s43, s19
	s_waitcnt lgkmcnt(1)
	v_cvt_pk_bf16_f32 v36, v24, v36
	v_add_u32_e32 v24, 0x800, v19
	v_cvt_pk_bf16_f32 v37, v25, v37
	ds_read2_b32 v[24:25], v24 offset0:8 offset1:138
	v_add_u32_e32 v19, 0xc00, v19
	s_xor_b32 s55, s55, 1
	s_add_i32 s48, s48, s43
	s_add_i32 s49, s49, s50
	s_waitcnt lgkmcnt(0)
	v_cvt_pk_bf16_f32 v38, v24, v38
	v_cvt_pk_bf16_f32 v39, v25, v39
	ds_read2_b32 v[24:25], v19 offset0:12 offset1:142
	v_ashrrev_i32_e32 v19, 31, v0
	s_add_i32 s51, s51, s52
	s_add_i32 s53, s53, s54
	s_cmp_ge_i32 s19, s20
	s_waitcnt lgkmcnt(0)
	v_cvt_pk_bf16_f32 v40, v24, v40
	v_cvt_pk_bf16_f32 v41, v25, v41
	v_readlane_b32 s30, v244, 59
	s_nop 3
	v_cmp_eq_u32_e32 vcc, s30, v20
	s_nop 3
	s_cbranch_vccnz .Lcvt_dn_0
	v_readlane_b32 s30, v244, 58
	s_nop 3
	v_cmp_eq_u32_e32 vcc, s30, v20
	s_nop 3
	s_cbranch_vccnz .Lcvt_up_0
	v_mad_u64_u32 v[24:25], s[30:31], v0, s42, 0
	v_mov_b32_e32 v0, v25
	v_mad_u64_u32 v[42:43], s[30:31], v19, s42, v[0:1]
	v_mov_b32_e32 v25, v42
	v_lshl_add_u64 v[20:21], v[24:25], 1, v[20:21]
	v_lshl_add_u64 v[20:21], s[66:67], 1, v[20:21]
	v_mov_b32_e32 v19, v1
	v_lshl_add_u64 v[20:21], v[20:21], 0, v[18:19]
	s_branch .Lcvt_st_0
.Lcvt_dn_0:
	v_lshrrev_b32_e64 v24, 5, s66
	v_lshrrev_b32_e32 v25, 6, v18
	v_add_u32_e32 v24, v24, v25
	v_lshlrev_b32_e32 v24, 16, v24
	v_lshl_add_u32 v24, v0, 6, v24
	v_and_b32_e32 v25, 63, v18
	v_add_u32_e32 v24, v24, v25
	v_mov_b32_e32 v25, 0
	v_mov_b32_e32 v19, v1
	v_lshl_add_u64 v[20:21], v[24:25], 0, v[20:21]
	s_branch .Lcvt_st_0
.Lcvt_up_0:
	v_lshrrev_b32_e64 v24, 5, s66
	v_lshrrev_b32_e32 v25, 6, v18
	v_add_u32_e32 v24, v24, v25
	v_mul_u32_u24_e32 v24, 0x58000, v24
	v_lshl_add_u32 v24, v0, 6, v24
	v_and_b32_e32 v25, 63, v18
	v_add_u32_e32 v24, v24, v25
	v_mov_b32_e32 v25, 0
	v_mov_b32_e32 v19, v1
	v_lshl_add_u64 v[20:21], v[24:25], 0, v[20:21]

.LBB0_413:
	v_lshlrev_b32_e32 v0, 2, v31
	v_add3_u32 v19, s61, v0, v33
	v_add3_u32 v0, s61, v33, v0
	ds_read2_b32 v[24:25], v19 offset1:130
	ds_read2_b32 v[34:35], v0 offset0:65 offset1:195
	v_add_u32_e32 v36, 0x400, v0
	ds_read2_b32 v[36:37], v36 offset0:69 offset1:199
	v_add_u32_e32 v38, 0x800, v0
	ds_read2_b32 v[38:39], v38 offset0:73 offset1:203
	s_waitcnt lgkmcnt(2)
	v_cvt_pk_bf16_f32 v34, v24, v34
	v_add_u32_e32 v24, 0x400, v19
	v_cvt_pk_bf16_f32 v35, v25, v35
	ds_read2_b32 v[24:25], v24 offset0:4 offset1:134
	v_add_u32_e32 v0, 0xc00, v0
	ds_read2_b32 v[40:41], v0 offset0:77 offset1:207
	v_add_u32_e32 v0, s3, v31
	s_xor_b32 s57, s57, 1
	s_waitcnt lgkmcnt(1)
	v_cvt_pk_bf16_f32 v36, v24, v36
	v_add_u32_e32 v24, 0x800, v19
	v_cvt_pk_bf16_f32 v37, v25, v37
	ds_read2_b32 v[24:25], v24 offset0:8 offset1:138
	v_add_u32_e32 v19, 0xc00, v19
	s_add_i32 s51, s51, s52
	s_add_i32 s53, s53, s54
	s_add_i32 s55, s55, s56
	s_waitcnt lgkmcnt(0)
	v_cvt_pk_bf16_f32 v38, v24, v38
	v_cvt_pk_bf16_f32 v39, v25, v39
	ds_read2_b32 v[24:25], v19 offset0:12 offset1:142
	v_ashrrev_i32_e32 v19, 31, v0
	s_and_b64 vcc, exec, s[34:35]
	s_mov_b32 s3, s58
	s_waitcnt lgkmcnt(0)
	v_cvt_pk_bf16_f32 v40, v24, v40
	v_cvt_pk_bf16_f32 v41, v25, v41
	v_readfirstlane_b32 s36, v20
	v_readlane_b32 s37, v244, 59
	s_nop 3
	s_cmp_eq_u32 s36, s37
	s_cbranch_scc1 .Lcvt_dn_1
	v_readlane_b32 s37, v244, 58
	s_nop 3
	s_cmp_eq_u32 s36, s37
	s_cbranch_scc1 .Lcvt_up_1
	v_mad_u64_u32 v[24:25], s[36:37], v0, s7, 0
	v_mov_b32_e32 v0, v25
	v_mad_u64_u32 v[42:43], s[36:37], v19, s7, v[0:1]
	v_mov_b32_e32 v25, v42
	v_lshl_add_u64 v[20:21], v[24:25], 1, v[20:21]
	s_ashr_i32 s7, s6, 31
	v_lshl_add_u64 v[20:21], s[6:7], 1, v[20:21]
	v_mov_b32_e32 v19, v1
	v_lshl_add_u64 v[20:21], v[20:21], 0, v[18:19]
	s_branch .Lcvt_st_1
.Lcvt_dn_1:
	v_lshrrev_b32_e64 v24, 5, s6
	v_lshrrev_b32_e32 v25, 6, v18
	v_add_u32_e32 v24, v24, v25
	v_lshlrev_b32_e32 v24, 16, v24
	v_lshl_add_u32 v24, v0, 6, v24
	v_and_b32_e32 v25, 63, v18
	v_add_u32_e32 v24, v24, v25
	v_mov_b32_e32 v25, 0
	v_mov_b32_e32 v19, v1
	v_lshl_add_u64 v[20:21], v[24:25], 0, v[20:21]
	s_ashr_i32 s7, s6, 31
	s_branch .Lcvt_st_1
.Lcvt_up_1:
	v_lshrrev_b32_e64 v24, 5, s6
	v_lshrrev_b32_e32 v25, 6, v18
	v_add_u32_e32 v24, v24, v25
	v_mul_u32_u24_e32 v24, 0x58000, v24
	v_lshl_add_u32 v24, v0, 6, v24
	v_and_b32_e32 v25, 63, v18
	v_add_u32_e32 v24, v24, v25
	v_mov_b32_e32 v25, 0
	v_mov_b32_e32 v19, v1
	v_lshl_add_u64 v[20:21], v[24:25], 0, v[20:21]
	s_ashr_i32 s7, s6, 31

.LBB0_498:
	v_lshlrev_b32_e32 v0, 2, v31
	v_add3_u32 v19, s29, v0, v33
	v_add3_u32 v0, s29, v33, v0
	ds_read2_b32 v[24:25], v19 offset1:130
	ds_read2_b32 v[34:35], v0 offset0:65 offset1:195
	v_add_u32_e32 v36, 0x400, v0
	ds_read2_b32 v[36:37], v36 offset0:69 offset1:199
	v_add_u32_e32 v38, 0x800, v0
	ds_read2_b32 v[38:39], v38 offset0:73 offset1:203
	s_waitcnt lgkmcnt(2)
	v_cvt_pk_bf16_f32 v34, v24, v34
	v_add_u32_e32 v24, 0x400, v19
	v_cvt_pk_bf16_f32 v35, v25, v35
	ds_read2_b32 v[24:25], v24 offset0:4 offset1:134
	v_add_u32_e32 v0, 0xc00, v0
	ds_read2_b32 v[40:41], v0 offset0:77 offset1:207
	v_add_u32_e32 v0, s21, v31
	s_ashr_i32 s21, s20, 31
	s_waitcnt lgkmcnt(1)
	v_cvt_pk_bf16_f32 v36, v24, v36
	v_add_u32_e32 v24, 0x800, v19
	v_cvt_pk_bf16_f32 v37, v25, v37
	ds_read2_b32 v[24:25], v24 offset0:8 offset1:138
	v_add_u32_e32 v19, 0xc00, v19
	s_add_i32 s93, s93, s71
	s_xor_b32 s92, s92, 1
	s_add_i32 s73, s73, s71
	s_waitcnt lgkmcnt(0)
	v_cvt_pk_bf16_f32 v38, v24, v38
	v_cvt_pk_bf16_f32 v39, v25, v39
	ds_read2_b32 v[24:25], v19 offset0:12 offset1:142
	v_ashrrev_i32_e32 v19, 31, v0
	s_add_i32 s81, s81, s82
	s_add_i32 s83, s83, s89
	s_add_i32 s90, s90, s18
	s_waitcnt lgkmcnt(0)
	v_cvt_pk_bf16_f32 v40, v24, v40
	v_cvt_pk_bf16_f32 v41, v25, v41
	v_readfirstlane_b32 s26, v20
	v_readlane_b32 s27, v244, 59
	s_nop 3
	s_cmp_eq_u32 s26, s27
	s_cbranch_scc1 .Lcvt_dn_2
	v_readlane_b32 s27, v244, 58
	s_nop 3
	s_cmp_eq_u32 s26, s27
	s_cbranch_scc1 .Lcvt_up_2
	v_mad_u64_u32 v[24:25], s[26:27], v0, s72, 0
	v_mov_b32_e32 v0, v25
	v_mad_u64_u32 v[42:43], s[26:27], v19, s72, v[0:1]
	v_mov_b32_e32 v25, v42
	v_lshl_add_u64 v[20:21], v[24:25], 1, v[20:21]
	v_lshl_add_u64 v[20:21], s[20:21], 1, v[20:21]
	v_mov_b32_e32 v19, v1
	v_lshl_add_u64 v[20:21], v[20:21], 0, v[18:19]
	s_branch .Lcvt_st_2
.Lcvt_dn_2:
	v_lshrrev_b32_e64 v24, 5, s20
	v_lshrrev_b32_e32 v25, 6, v18
	v_add_u32_e32 v24, v24, v25
	v_lshlrev_b32_e32 v24, 16, v24
	v_lshl_add_u32 v24, v0, 6, v24
	v_and_b32_e32 v25, 63, v18
	v_add_u32_e32 v24, v24, v25
	v_mov_b32_e32 v25, 0
	v_mov_b32_e32 v19, v1
	v_lshl_add_u64 v[20:21], v[24:25], 0, v[20:21]
	s_branch .Lcvt_st_2
.Lcvt_up_2:
	v_lshrrev_b32_e64 v24, 5, s20
	v_lshrrev_b32_e32 v25, 6, v18
	v_add_u32_e32 v24, v24, v25
	v_mul_u32_u24_e32 v24, 0x58000, v24
	v_lshl_add_u32 v24, v0, 6, v24
	v_and_b32_e32 v25, 63, v18
	v_add_u32_e32 v24, v24, v25
	v_mov_b32_e32 v25, 0
	v_mov_b32_e32 v19, v1
	v_lshl_add_u64 v[20:21], v[24:25], 0, v[20:21]

.Lgy_entry:
	s_waitcnt lgkmcnt(0)
	s_load_dwordx2 s[48:49], s[0:1], 0x108
	s_load_dwordx2 s[50:51], s[0:1], 0xb0
	s_load_dwordx2 s[52:53], s[0:1], 0x110
	s_mov_b32 s59, 88
	s_mov_b32 s72, 0x100000
	s_mov_b32 s73, 0x10000
	s_movk_i32 s32, 0x200
	v_and_b32_e32 v0, 63, v154
	v_lshrrev_b32_e32 v131, 6, v154
	v_lshrrev_b32_e32 v243, 2, v0
	v_readfirstlane_b32 s41, v131
	v_and_b32_e32 v130, 3, v0
	v_mov_b32_e32 v134, 0x1320
	s_nop 1
	s_lshr_b32 s42, s41, 1
	s_and_b32 s43, s41, 1
	v_bfe_u32 v132, v0, 4, 2
	v_lshlrev_b32_e32 v132, 2, v132
	v_lshrrev_b32_e32 v132, v132, v134
	v_and_b32_e32 v132, 3, v132
	v_xor_b32_e32 v132, v132, v130
	v_lshlrev_b32_e32 v245, 4, v132
	v_bfe_u32 v132, v0, 2, 2
	v_lshlrev_b32_e32 v132, 2, v132
	v_lshrrev_b32_e32 v132, v132, v134
	v_and_b32_e32 v132, 3, v132
	v_lshrrev_b32_e32 v133, 4, v0
	v_xor_b32_e32 v132, v132, v133
	v_lshlrev_b32_e32 v132, 4, v132
	v_and_b32_e32 v131, 15, v0
	s_lshl_b32 s26, s42, 13
	v_lshl_add_u32 v238, v131, 6, v132
	v_add_u32_e32 v238, s26, v238
	s_lshl_b32 s62, s41, 12
	s_lshl_b32 s63, s41, 11
	s_add_i32 s63, s63, 0x4000
	s_lshl_b32 s26, s43, 12
	s_add_i32 s26, s26, 0x4000
	v_lshrrev_b32_e32 v134, 2, v131
	v_lshl_add_u32 v239, v134, 10, v132
	v_and_b32_e32 v134, 3, v131
	v_lshl_add_u32 v239, v134, 6, v239
	v_add_u32_e32 v239, s26, v239
	s_lshl_b32 s26, s41, 1
	s_and_b32 s26, s26, 3
	s_lshl_b32 s26, s26, 2
	s_lshr_b32 s26, 0x1320, s26
	s_and_b32 s26, s26, 3
	v_xor_b32_e32 v246, s26, v130
	v_lshlrev_b32_e32 v246, 4, v246
	s_lshl_b32 s26, s41, 1
	s_add_i32 s26, s26, 1
	s_and_b32 s26, s26, 3
	s_lshl_b32 s26, s26, 2
	s_lshr_b32 s26, 0x1320, s26
	s_and_b32 s26, s26, 3
	v_xor_b32_e32 v247, s26, v130
	v_lshlrev_b32_e32 v247, 4, v247
	v_lshlrev_b32_e32 v133, 5, v133
	v_lshl_add_u32 v242, v131, 11, v133
	s_lshl_b32 s26, s42, 18
	s_lshl_b32 s27, s43, 7
	s_add_i32 s26, s26, s27
	v_add_u32_e32 v242, s26, v242
	s_mov_b32 s34, s3
	s_cmp_lt_i32 s34, s32
	s_cbranch_scc0 .Lgy_done
	s_and_b32 s26, s34, 7
	s_lshr_b32 s27, s34, 3
	s_lshr_b32 s36, s27, 3
	s_and_b32 s27, s27, 7
	s_lshl_b32 s27, s27, 3
	s_add_i32 s35, s27, s26
	s_lshl_b32 s35, s35, 8
	s_lshl_b32 s36, s36, 7
	s_lshl_b32 s26, s41, 6
	s_add_i32 s26, s26, s35
	v_add_u32_e32 v0, s26, v243
	v_lshl_add_u32 v226, v0, 6, v245
	s_lshl_b32 s26, s41, 5
	s_add_i32 s26, s26, s36
	v_add_u32_e32 v0, s26, v243
	v_lshl_add_u32 v230, v0, 6, v246
	v_lshl_add_u32 v231, v0, 6, v247
	s_mov_b32 s60, 0
	s_mov_b32 s61, 0
	s_waitcnt lgkmcnt(0)
	s_mov_b64 s[54:55], s[48:49]
	s_mov_b64 s[56:57], s[50:51]
	s_add_i32 m0, s60, s62
	s_nop 0
	global_load_lds_dwordx4 v226, s[54:55]
	global_load_lds_dwordx4 v226, s[54:55] offset:1024
	global_load_lds_dwordx4 v226, s[54:55] offset:2048
	global_load_lds_dwordx4 v226, s[54:55] offset:3072
	s_add_i32 m0, s60, s63
	s_nop 0
	global_load_lds_dwordx4 v230, s[56:57]
	global_load_lds_dwordx4 v231, s[56:57] offset:1024
	s_add_i32 s60, s60, 0x6000
	s_cmp_eq_u32 s60, 0x12000
	s_cselect_b32 s60, 0, s60
	s_add_u32 s54, s54, s72
	s_addc_u32 s55, s55, 0
	s_add_u32 s56, s56, s73
	s_addc_u32 s57, s57, 0
	s_add_i32 m0, s60, s62
	s_nop 0
	global_load_lds_dwordx4 v226, s[54:55]
	global_load_lds_dwordx4 v226, s[54:55] offset:1024
	global_load_lds_dwordx4 v226, s[54:55] offset:2048
	global_load_lds_dwordx4 v226, s[54:55] offset:3072
	s_add_i32 m0, s60, s63
	s_nop 0
	global_load_lds_dwordx4 v230, s[56:57]
	global_load_lds_dwordx4 v231, s[56:57] offset:1024
	s_add_i32 s60, s60, 0x6000
	s_cmp_eq_u32 s60, 0x12000
	s_cselect_b32 s60, 0, s60
	s_add_u32 s54, s54, s72
	s_addc_u32 s55, s55, 0
	s_add_u32 s56, s56, s73
	s_addc_u32 s57, s57, 0
	s_add_i32 m0, s60, s62
	s_nop 0
	global_load_lds_dwordx4 v226, s[54:55]
	global_load_lds_dwordx4 v226, s[54:55] offset:1024
	global_load_lds_dwordx4 v226, s[54:55] offset:2048
	global_load_lds_dwordx4 v226, s[54:55] offset:3072
	s_add_i32 m0, s60, s63
	s_nop 0
	global_load_lds_dwordx4 v230, s[56:57]
	global_load_lds_dwordx4 v231, s[56:57] offset:1024
	s_add_i32 s60, s60, 0x6000
	s_cmp_eq_u32 s60, 0x12000
	s_cselect_b32 s60, 0, s60
	s_add_u32 s54, s54, s72
	s_addc_u32 s55, s55, 0
	s_add_u32 s56, s56, s73
	s_addc_u32 s57, s57, 0
	s_waitcnt vmcnt(12)
	s_barrier
	v_add_u32_e32 v240, s61, v238
	v_add_u32_e32 v241, s61, v239
	ds_read_b128 v[162:165], v241 offset:0
	ds_read_b128 v[166:169], v241 offset:256
	ds_read_b128 v[170:173], v241 offset:512
	ds_read_b128 v[174:177], v241 offset:768
	ds_read_b128 v[130:133], v240 offset:0
	ds_read_b128 v[134:137], v240 offset:1024
	ds_read_b128 v[138:141], v240 offset:2048
	ds_read_b128 v[142:145], v240 offset:3072
	ds_read_b128 v[146:149], v240 offset:4096
	ds_read_b128 v[150:153], v240 offset:5120
	ds_read_b128 v[154:157], v240 offset:6144
	ds_read_b128 v[158:161], v240 offset:7168
	s_add_i32 s61, s61, 0x6000
	s_cmp_eq_u32 s61, 0x12000
	s_cselect_b32 s61, 0, s61
	s_add_i32 s38, s34, s71
	s_cmp_lt_i32 s38, s32
	s_cselect_b32 s37, 1, 0
	s_cbranch_scc0 .Lgy_nn_a
	s_and_b32 s26, s38, 7
	s_lshr_b32 s27, s38, 3
	s_lshr_b32 s31, s27, 3
	s_and_b32 s27, s27, 7
	s_lshl_b32 s27, s27, 3
	s_add_i32 s30, s27, s26
	s_lshl_b32 s30, s30, 8
	s_lshl_b32 s31, s31, 7
	s_lshl_b32 s26, s41, 6
	s_add_i32 s26, s26, s30
	v_add_u32_e32 v0, s26, v243
	v_lshl_add_u32 v232, v0, 6, v245
	s_lshl_b32 s26, s41, 5
	s_add_i32 s26, s26, s31
	v_add_u32_e32 v0, s26, v243
	v_lshl_add_u32 v236, v0, 6, v246
	v_lshl_add_u32 v237, v0, 6, v247

.Lgy_tile:
	s_add_i32 s38, s34, s71
	s_cmp_lt_i32 s38, s32
	s_cselect_b32 s37, 1, 0
	s_cbranch_scc0 .Lgy_nn_b
	s_and_b32 s26, s38, 7
	s_lshr_b32 s27, s38, 3
	s_lshr_b32 s31, s27, 3
	s_and_b32 s27, s27, 7
	s_lshl_b32 s27, s27, 3
	s_add_i32 s30, s27, s26
	s_lshl_b32 s30, s30, 8
	s_lshl_b32 s31, s31, 7
	s_lshl_b32 s26, s41, 6
	s_add_i32 s26, s26, s30
	v_add_u32_e32 v0, s26, v243
	v_lshl_add_u32 v232, v0, 6, v245
	s_lshl_b32 s26, s41, 5
	s_add_i32 s26, s26, s31
	v_add_u32_e32 v0, s26, v243
	v_lshl_add_u32 v236, v0, 6, v246
	v_lshl_add_u32 v237, v0, 6, v247

.Lup_entry:
	s_waitcnt lgkmcnt(0)
	s_load_dwordx2 s[48:49], s[0:1], 0xc0
	s_load_dwordx2 s[50:51], s[0:1], 0xa8
	s_load_dwordx2 s[52:53], s[0:1], 0x108
	s_load_dwordx2 s[82:83], s[0:1], 0x78
	s_load_dwordx2 s[28:29], s[0:1], 0x80
	s_mov_b32 s59, 32
	s_mov_b32 s72, 0x100000
	s_mov_b32 s73, 0x58000
	s_movk_i32 s32, 0xbb0
	v_and_b32_e32 v0, 63, v154
	v_lshrrev_b32_e32 v131, 6, v154
	v_lshrrev_b32_e32 v243, 2, v0
	v_readfirstlane_b32 s41, v131
	v_and_b32_e32 v130, 3, v0
	v_mov_b32_e32 v134, 0x1320
	s_nop 1
	s_lshr_b32 s42, s41, 1
	s_and_b32 s43, s41, 1
	v_bfe_u32 v132, v0, 4, 2
	v_lshlrev_b32_e32 v132, 2, v132
	v_lshrrev_b32_e32 v132, v132, v134
	v_and_b32_e32 v132, 3, v132
	v_xor_b32_e32 v132, v132, v130
	v_lshlrev_b32_e32 v245, 4, v132
	v_bfe_u32 v132, v0, 2, 2
	v_lshlrev_b32_e32 v132, 2, v132
	v_lshrrev_b32_e32 v132, v132, v134
	v_and_b32_e32 v132, 3, v132
	v_lshrrev_b32_e32 v133, 4, v0
	v_xor_b32_e32 v132, v132, v133
	v_lshlrev_b32_e32 v132, 4, v132
	v_and_b32_e32 v131, 15, v0
	s_lshl_b32 s26, s42, 13
	v_lshl_add_u32 v238, v131, 6, v132
	v_add_u32_e32 v238, s26, v238
	s_lshl_b32 s62, s41, 12
	s_lshl_b32 s63, s41, 11
	s_add_i32 s63, s63, 0x4000
	s_lshl_b32 s26, s43, 12
	s_add_i32 s26, s26, 0x4000
	v_lshrrev_b32_e32 v134, 2, v131
	v_lshl_add_u32 v239, v134, 9, v132
	v_and_b32_e32 v134, 3, v131
	v_lshl_add_u32 v239, v134, 6, v239
	v_add_u32_e32 v239, s26, v239
	v_mov_b32_e32 v134, 0x1320
	v_lshrrev_b32_e32 v246, 3, v243
	v_and_b32_e32 v246, 3, v246
	v_lshlrev_b32_e32 v246, 2, v246
	v_lshrrev_b32_e32 v246, v246, v134
	v_and_b32_e32 v246, 3, v246
	v_xor_b32_e32 v246, v246, v130
	v_lshlrev_b32_e32 v246, 4, v246
	v_lshrrev_b32_e32 v247, 3, v243
	v_add_u32_e32 v247, 2, v247
	v_and_b32_e32 v247, 3, v247
	v_lshlrev_b32_e32 v247, 2, v247
	v_lshrrev_b32_e32 v247, v247, v134
	v_and_b32_e32 v247, 3, v247
	v_xor_b32_e32 v247, v247, v130
	v_lshlrev_b32_e32 v247, 4, v247
	s_lshl_b32 s26, s42, 7
	v_add_u32_e32 v227, s26, v131
	v_lshlrev_b32_e32 v134, 4, v133
	v_lshl_add_u32 v242, v227, 6, v134
	s_lshl_b32 s26, s43, 7
	v_lshl_add_u32 v228, v133, 5, s26
	s_mov_b32 s34, s3
	s_cmp_lt_i32 s34, s32
	s_cbranch_scc0 .Lup_done
	s_cmpk_lt_i32 s34, 0xb00
	s_cbranch_scc0 .Lup_lo_f
	s_and_b32 s26, s34, 7
	s_lshr_b32 s27, s34, 3
	s_lshr_b32 s36, s27, 3
	s_and_b32 s27, s27, 7
	s_lshl_b32 s27, s27, 3
	s_add_i32 s35, s27, s26
	s_branch .Lup_go_f
.Lup_lo_f:
	s_add_i32 s36, s34, 0xfffff500
	s_movk_i32 s35, 64
	s_cmpk_lt_i32 s36, 44
	s_cbranch_scc1 .Lup_go_f
	s_add_i32 s36, s36, -44
	s_add_i32 s35, s35, 1
	s_cmpk_lt_i32 s36, 44
	s_cbranch_scc1 .Lup_go_f
	s_add_i32 s36, s36, -44
	s_add_i32 s35, s35, 1
	s_cmpk_lt_i32 s36, 44
	s_cbranch_scc1 .Lup_go_f
	s_add_i32 s36, s36, -44
	s_add_i32 s35, s35, 1
.Lup_go_f:
	s_mov_b32 s26, 0
	s_cmpk_lt_i32 s35, 17
	s_cbranch_scc1 .Lup_b_f
	s_add_i32 s35, s35, -17
	s_add_i32 s26, s26, 0x1000
	s_cmpk_lt_i32 s35, 17
	s_cbranch_scc1 .Lup_b_f
	s_add_i32 s35, s35, -17
	s_add_i32 s26, s26, 0x1000
	s_cmpk_lt_i32 s35, 17
	s_cbranch_scc1 .Lup_b_f
	s_add_i32 s35, s35, -17
	s_add_i32 s26, s26, 0x1000
.Lup_b_f:
	s_mulk_i32 s35, 254
	s_add_i32 s35, s35, s26
	s_lshl_b32 s36, s36, 7
	s_lshl_b32 s26, s41, 6
	s_add_i32 s26, s26, s35
	v_add_u32_e32 v0, s26, v243
	v_lshl_add_u32 v226, v0, 6, v245
	s_lshl_b32 s26, s41, 5
	s_add_i32 s26, s26, s36
	v_add_u32_e32 v0, s26, v243
	v_lshl_add_u32 v230, v0, 6, v246
	v_lshl_add_u32 v231, v0, 6, v247
	s_mov_b32 s60, 0
	s_mov_b32 s61, 0
	s_waitcnt lgkmcnt(0)
	s_sub_u32 s48, s48, 0x80
	s_subb_u32 s49, s49, 0
	s_and_b64 s[26:27], s[22:23], exec
	s_cselect_b32 s26, 0x8400, 0
	s_cselect_b32 s27, 0x2c00, 0
	s_add_u32 s82, s82, s26
	s_addc_u32 s83, s83, 0
	s_add_u32 s92, s82, 0x2c00
	s_addc_u32 s93, s83, 0
	s_add_u32 s96, s92, 0x2c00
	s_addc_u32 s97, s93, 0
	s_add_u32 s28, s28, s27
	s_addc_u32 s29, s29, 0
	s_mov_b64 s[54:55], s[48:49]
	s_mov_b64 s[56:57], s[50:51]
	s_add_i32 m0, s60, s62
	s_nop 0
	global_load_lds_dwordx4 v226, s[54:55]
	global_load_lds_dwordx4 v226, s[54:55] offset:1024
	global_load_lds_dwordx4 v226, s[54:55] offset:2048
	global_load_lds_dwordx4 v226, s[54:55] offset:3072
	s_add_i32 m0, s60, s63
	s_nop 0
	global_load_lds_dwordx4 v230, s[56:57]
	global_load_lds_dwordx4 v231, s[56:57] offset:1024
	s_add_i32 s60, s60, 0x6000
	s_cmp_eq_u32 s60, 0x12000
	s_cselect_b32 s60, 0, s60
	s_add_u32 s54, s54, s72
	s_addc_u32 s55, s55, 0
	s_add_u32 s56, s56, s73
	s_addc_u32 s57, s57, 0
	s_add_i32 m0, s60, s62
	s_nop 0
	global_load_lds_dwordx4 v226, s[54:55]
	global_load_lds_dwordx4 v226, s[54:55] offset:1024
	global_load_lds_dwordx4 v226, s[54:55] offset:2048
	global_load_lds_dwordx4 v226, s[54:55] offset:3072
	s_add_i32 m0, s60, s63
	s_nop 0
	global_load_lds_dwordx4 v230, s[56:57]
	global_load_lds_dwordx4 v231, s[56:57] offset:1024
	s_add_i32 s60, s60, 0x6000
	s_cmp_eq_u32 s60, 0x12000
	s_cselect_b32 s60, 0, s60
	s_add_u32 s54, s54, s72
	s_addc_u32 s55, s55, 0
	s_add_u32 s56, s56, s73
	s_addc_u32 s57, s57, 0
	s_add_i32 m0, s60, s62
	s_nop 0
	global_load_lds_dwordx4 v226, s[54:55]
	global_load_lds_dwordx4 v226, s[54:55] offset:1024
	global_load_lds_dwordx4 v226, s[54:55] offset:2048
	global_load_lds_dwordx4 v226, s[54:55] offset:3072
	s_add_i32 m0, s60, s63
	s_nop 0
	global_load_lds_dwordx4 v230, s[56:57]
	global_load_lds_dwordx4 v231, s[56:57] offset:1024
	s_add_i32 s60, s60, 0x6000
	s_cmp_eq_u32 s60, 0x12000
	s_cselect_b32 s60, 0, s60
	s_add_u32 s54, s54, s72
	s_addc_u32 s55, s55, 0
	s_add_u32 s56, s56, s73
	s_addc_u32 s57, s57, 0
	s_waitcnt vmcnt(12)
	s_barrier
	v_add_u32_e32 v240, s61, v238
	v_add_u32_e32 v241, s61, v239
	ds_read_b128 v[162:165], v241 offset:0
	ds_read_b128 v[166:169], v241 offset:256
	ds_read_b128 v[170:173], v241 offset:2048
	ds_read_b128 v[174:177], v241 offset:2304
	ds_read_b128 v[130:133], v240 offset:0
	ds_read_b128 v[134:137], v240 offset:1024
	ds_read_b128 v[138:141], v240 offset:2048
	ds_read_b128 v[142:145], v240 offset:3072
	ds_read_b128 v[146:149], v240 offset:4096
	ds_read_b128 v[150:153], v240 offset:5120
	ds_read_b128 v[154:157], v240 offset:6144
	ds_read_b128 v[158:161], v240 offset:7168
	s_add_i32 s61, s61, 0x6000
	s_cmp_eq_u32 s61, 0x12000
	s_cselect_b32 s61, 0, s61
	s_add_i32 s38, s34, s71
	s_cmp_lt_i32 s38, s32
	s_cselect_b32 s37, 1, 0
	s_cbranch_scc0 .Lup_nn_a
	s_cmpk_lt_i32 s38, 0xb00
	s_cbranch_scc0 .Lup_lo_a
	s_and_b32 s26, s38, 7
	s_lshr_b32 s27, s38, 3
	s_lshr_b32 s31, s27, 3
	s_and_b32 s27, s27, 7
	s_lshl_b32 s27, s27, 3
	s_add_i32 s30, s27, s26
	s_branch .Lup_go_a
.Lup_lo_a:
	s_add_i32 s31, s38, 0xfffff500
	s_movk_i32 s30, 64
	s_cmpk_lt_i32 s31, 44
	s_cbranch_scc1 .Lup_go_a
	s_add_i32 s31, s31, -44
	s_add_i32 s30, s30, 1
	s_cmpk_lt_i32 s31, 44
	s_cbranch_scc1 .Lup_go_a
	s_add_i32 s31, s31, -44
	s_add_i32 s30, s30, 1
	s_cmpk_lt_i32 s31, 44
	s_cbranch_scc1 .Lup_go_a
	s_add_i32 s31, s31, -44
	s_add_i32 s30, s30, 1
.Lup_go_a:
	s_mov_b32 s26, 0
	s_cmpk_lt_i32 s30, 17
	s_cbranch_scc1 .Lup_b_a
	s_add_i32 s30, s30, -17
	s_add_i32 s26, s26, 0x1000
	s_cmpk_lt_i32 s30, 17
	s_cbranch_scc1 .Lup_b_a
	s_add_i32 s30, s30, -17
	s_add_i32 s26, s26, 0x1000
	s_cmpk_lt_i32 s30, 17
	s_cbranch_scc1 .Lup_b_a
	s_add_i32 s30, s30, -17
	s_add_i32 s26, s26, 0x1000
.Lup_b_a:
	s_mulk_i32 s30, 254
	s_add_i32 s30, s30, s26
	s_lshl_b32 s31, s31, 7
	s_lshl_b32 s26, s41, 6
	s_add_i32 s26, s26, s30
	v_add_u32_e32 v0, s26, v243
	v_lshl_add_u32 v232, v0, 6, v245
	s_lshl_b32 s26, s41, 5
	s_add_i32 s26, s26, s31
	v_add_u32_e32 v0, s26, v243
	v_lshl_add_u32 v236, v0, 6, v246
	v_lshl_add_u32 v237, v0, 6, v247
.Lup_nn_a:
	v_mov_b32_e32 v2, 0
	v_mov_b32_e32 v3, 0
	v_mov_b32_e32 v4, 0
	v_mov_b32_e32 v5, 0
	v_mov_b32_e32 v6, 0
	v_mov_b32_e32 v7, 0
	v_mov_b32_e32 v8, 0
	v_mov_b32_e32 v9, 0
	v_mov_b32_e32 v10, 0
	v_mov_b32_e32 v11, 0
	v_mov_b32_e32 v12, 0
	v_mov_b32_e32 v13, 0
	v_mov_b32_e32 v14, 0
	v_mov_b32_e32 v15, 0
	v_mov_b32_e32 v16, 0
	v_mov_b32_e32 v17, 0
	v_mov_b32_e32 v18, 0
	v_mov_b32_e32 v19, 0
	v_mov_b32_e32 v20, 0
	v_mov_b32_e32 v21, 0
	v_mov_b32_e32 v22, 0
	v_mov_b32_e32 v23, 0
	v_mov_b32_e32 v24, 0
	v_mov_b32_e32 v25, 0
	v_mov_b32_e32 v26, 0
	v_mov_b32_e32 v27, 0
	v_mov_b32_e32 v28, 0
	v_mov_b32_e32 v29, 0
	v_mov_b32_e32 v30, 0
	v_mov_b32_e32 v31, 0
	v_mov_b32_e32 v32, 0
	v_mov_b32_e32 v33, 0
	v_mov_b32_e32 v34, 0
	v_mov_b32_e32 v35, 0
	v_mov_b32_e32 v36, 0
	v_mov_b32_e32 v37, 0
	v_mov_b32_e32 v38, 0
	v_mov_b32_e32 v39, 0
	v_mov_b32_e32 v40, 0
	v_mov_b32_e32 v41, 0
	v_mov_b32_e32 v42, 0
	v_mov_b32_e32 v43, 0
	v_mov_b32_e32 v44, 0
	v_mov_b32_e32 v45, 0
	v_mov_b32_e32 v46, 0
	v_mov_b32_e32 v47, 0
	v_mov_b32_e32 v48, 0
	v_mov_b32_e32 v49, 0
	v_mov_b32_e32 v50, 0
	v_mov_b32_e32 v51, 0
	v_mov_b32_e32 v52, 0
	v_mov_b32_e32 v53, 0
	v_mov_b32_e32 v54, 0
	v_mov_b32_e32 v55, 0
	v_mov_b32_e32 v56, 0
	v_mov_b32_e32 v57, 0
	v_mov_b32_e32 v58, 0
	v_mov_b32_e32 v59, 0
	v_mov_b32_e32 v60, 0
	v_mov_b32_e32 v61, 0
	v_mov_b32_e32 v62, 0
	v_mov_b32_e32 v63, 0
	v_mov_b32_e32 v64, 0
	v_mov_b32_e32 v65, 0
	v_mov_b32_e32 v66, 0
	v_mov_b32_e32 v67, 0
	v_mov_b32_e32 v68, 0
	v_mov_b32_e32 v69, 0
	v_mov_b32_e32 v70, 0
	v_mov_b32_e32 v71, 0
	v_mov_b32_e32 v72, 0
	v_mov_b32_e32 v73, 0
	v_mov_b32_e32 v74, 0
	v_mov_b32_e32 v75, 0
	v_mov_b32_e32 v76, 0
	v_mov_b32_e32 v77, 0
	v_mov_b32_e32 v78, 0
	v_mov_b32_e32 v79, 0
	v_mov_b32_e32 v80, 0
	v_mov_b32_e32 v81, 0
	v_mov_b32_e32 v82, 0
	v_mov_b32_e32 v83, 0
	v_mov_b32_e32 v84, 0
	v_mov_b32_e32 v85, 0
	v_mov_b32_e32 v86, 0
	v_mov_b32_e32 v87, 0
	v_mov_b32_e32 v88, 0
	v_mov_b32_e32 v89, 0
	v_mov_b32_e32 v90, 0
	v_mov_b32_e32 v91, 0
	v_mov_b32_e32 v92, 0
	v_mov_b32_e32 v93, 0
	v_mov_b32_e32 v94, 0
	v_mov_b32_e32 v95, 0
	v_mov_b32_e32 v96, 0
	v_mov_b32_e32 v97, 0
	v_mov_b32_e32 v98, 0
	v_mov_b32_e32 v99, 0
	v_mov_b32_e32 v100, 0
	v_mov_b32_e32 v101, 0
	v_mov_b32_e32 v102, 0
	v_mov_b32_e32 v103, 0
	v_mov_b32_e32 v104, 0
	v_mov_b32_e32 v105, 0
	v_mov_b32_e32 v106, 0
	v_mov_b32_e32 v107, 0
	v_mov_b32_e32 v108, 0
	v_mov_b32_e32 v109, 0
	v_mov_b32_e32 v110, 0
	v_mov_b32_e32 v111, 0
	v_mov_b32_e32 v112, 0
	v_mov_b32_e32 v113, 0
	v_mov_b32_e32 v114, 0
	v_mov_b32_e32 v115, 0
	v_mov_b32_e32 v116, 0
	v_mov_b32_e32 v117, 0
	v_mov_b32_e32 v118, 0
	v_mov_b32_e32 v119, 0
	v_mov_b32_e32 v120, 0
	v_mov_b32_e32 v121, 0
	v_mov_b32_e32 v122, 0
	v_mov_b32_e32 v123, 0
	v_mov_b32_e32 v124, 0
	v_mov_b32_e32 v125, 0
	v_mov_b32_e32 v126, 0
	v_mov_b32_e32 v127, 0
	v_mov_b32_e32 v128, 0
	v_mov_b32_e32 v129, 0
	s_waitcnt vmcnt(6) lgkmcnt(0)
	s_barrier
	v_add_u32_e32 v240, s61, v238
	v_add_u32_e32 v241, s61, v239
	s_add_i32 m0, s60, s62
	v_mfma_f32_16x16x32_bf16 v[2:5], v[162:165], v[130:133], v[2:5]
	global_load_lds_dwordx4 v226, s[54:55]
	v_mfma_f32_16x16x32_bf16 v[6:9], v[166:169], v[130:133], v[6:9]
	global_load_lds_dwordx4 v226, s[54:55] offset:1024
	v_mfma_f32_16x16x32_bf16 v[10:13], v[170:173], v[130:133], v[10:13]
	global_load_lds_dwordx4 v226, s[54:55] offset:2048
	v_mfma_f32_16x16x32_bf16 v[14:17], v[174:177], v[130:133], v[14:17]
	global_load_lds_dwordx4 v226, s[54:55] offset:3072
	s_add_i32 m0, s60, s63
	v_mfma_f32_16x16x32_bf16 v[18:21], v[162:165], v[134:137], v[18:21]
	global_load_lds_dwordx4 v230, s[56:57]
	v_mfma_f32_16x16x32_bf16 v[22:25], v[166:169], v[134:137], v[22:25]
	global_load_lds_dwordx4 v231, s[56:57] offset:1024
	v_mfma_f32_16x16x32_bf16 v[26:29], v[170:173], v[134:137], v[26:29]
	v_mfma_f32_16x16x32_bf16 v[30:33], v[174:177], v[134:137], v[30:33]
	v_mfma_f32_16x16x32_bf16 v[34:37], v[162:165], v[138:141], v[34:37]
	ds_read_b128 v[210:213], v241 offset:0
	v_mfma_f32_16x16x32_bf16 v[38:41], v[166:169], v[138:141], v[38:41]
	ds_read_b128 v[214:217], v241 offset:256
	v_mfma_f32_16x16x32_bf16 v[42:45], v[170:173], v[138:141], v[42:45]
	ds_read_b128 v[218:221], v241 offset:2048
	v_mfma_f32_16x16x32_bf16 v[46:49], v[174:177], v[138:141], v[46:49]
	ds_read_b128 v[222:225], v241 offset:2304
	v_mfma_f32_16x16x32_bf16 v[50:53], v[162:165], v[142:145], v[50:53]
	ds_read_b128 v[178:181], v240 offset:0
	v_mfma_f32_16x16x32_bf16 v[54:57], v[166:169], v[142:145], v[54:57]
	ds_read_b128 v[182:185], v240 offset:1024
	v_mfma_f32_16x16x32_bf16 v[58:61], v[170:173], v[142:145], v[58:61]
	ds_read_b128 v[186:189], v240 offset:2048
	v_mfma_f32_16x16x32_bf16 v[62:65], v[174:177], v[142:145], v[62:65]
	ds_read_b128 v[190:193], v240 offset:3072
	v_mfma_f32_16x16x32_bf16 v[66:69], v[162:165], v[146:149], v[66:69]
	ds_read_b128 v[194:197], v240 offset:4096
	v_mfma_f32_16x16x32_bf16 v[70:73], v[166:169], v[146:149], v[70:73]
	ds_read_b128 v[198:201], v240 offset:5120
	v_mfma_f32_16x16x32_bf16 v[74:77], v[170:173], v[146:149], v[74:77]
	ds_read_b128 v[202:205], v240 offset:6144
	v_mfma_f32_16x16x32_bf16 v[78:81], v[174:177], v[146:149], v[78:81]
	ds_read_b128 v[206:209], v240 offset:7168
	v_mfma_f32_16x16x32_bf16 v[82:85], v[162:165], v[150:153], v[82:85]
	v_mfma_f32_16x16x32_bf16 v[86:89], v[166:169], v[150:153], v[86:89]
	v_mfma_f32_16x16x32_bf16 v[90:93], v[170:173], v[150:153], v[90:93]
	v_mfma_f32_16x16x32_bf16 v[94:97], v[174:177], v[150:153], v[94:97]
	v_mfma_f32_16x16x32_bf16 v[98:101], v[162:165], v[154:157], v[98:101]
	v_mfma_f32_16x16x32_bf16 v[102:105], v[166:169], v[154:157], v[102:105]
	v_mfma_f32_16x16x32_bf16 v[106:109], v[170:173], v[154:157], v[106:109]
	v_mfma_f32_16x16x32_bf16 v[110:113], v[174:177], v[154:157], v[110:113]
	v_mfma_f32_16x16x32_bf16 v[114:117], v[162:165], v[158:161], v[114:117]
	v_mfma_f32_16x16x32_bf16 v[118:121], v[166:169], v[158:161], v[118:121]
	v_mfma_f32_16x16x32_bf16 v[122:125], v[170:173], v[158:161], v[122:125]
	v_mfma_f32_16x16x32_bf16 v[126:129], v[174:177], v[158:161], v[126:129]
	s_add_i32 s60, s60, 0x6000
	s_cmp_eq_u32 s60, 0x12000
	s_cselect_b32 s60, 0, s60
	s_add_u32 s54, s54, s72
	s_addc_u32 s55, s55, 0
	s_add_u32 s56, s56, s73
	s_addc_u32 s57, s57, 0
	s_add_i32 s61, s61, 0x6000
	s_cmp_eq_u32 s61, 0x12000
	s_cselect_b32 s61, 0, s61
	s_waitcnt vmcnt(6) lgkmcnt(0)
	s_barrier
	v_add_u32_e32 v240, s61, v238
	v_add_u32_e32 v241, s61, v239
	s_add_i32 m0, s60, s62
	v_mfma_f32_16x16x32_bf16 v[2:5], v[210:213], v[178:181], v[2:5]
	global_load_lds_dwordx4 v226, s[54:55]
	v_mfma_f32_16x16x32_bf16 v[6:9], v[214:217], v[178:181], v[6:9]
	global_load_lds_dwordx4 v226, s[54:55] offset:1024
	v_mfma_f32_16x16x32_bf16 v[10:13], v[218:221], v[178:181], v[10:13]
	global_load_lds_dwordx4 v226, s[54:55] offset:2048
	v_mfma_f32_16x16x32_bf16 v[14:17], v[222:225], v[178:181], v[14:17]
	global_load_lds_dwordx4 v226, s[54:55] offset:3072
	s_add_i32 m0, s60, s63
	v_mfma_f32_16x16x32_bf16 v[18:21], v[210:213], v[182:185], v[18:21]
	global_load_lds_dwordx4 v230, s[56:57]
	v_mfma_f32_16x16x32_bf16 v[22:25], v[214:217], v[182:185], v[22:25]
	global_load_lds_dwordx4 v231, s[56:57] offset:1024
	v_mfma_f32_16x16x32_bf16 v[26:29], v[218:221], v[182:185], v[26:29]
	v_mfma_f32_16x16x32_bf16 v[30:33], v[222:225], v[182:185], v[30:33]
	v_mfma_f32_16x16x32_bf16 v[34:37], v[210:213], v[186:189], v[34:37]
	ds_read_b128 v[162:165], v241 offset:0
	v_mfma_f32_16x16x32_bf16 v[38:41], v[214:217], v[186:189], v[38:41]
	ds_read_b128 v[166:169], v241 offset:256
	v_mfma_f32_16x16x32_bf16 v[42:45], v[218:221], v[186:189], v[42:45]
	ds_read_b128 v[170:173], v241 offset:2048
	v_mfma_f32_16x16x32_bf16 v[46:49], v[222:225], v[186:189], v[46:49]
	ds_read_b128 v[174:177], v241 offset:2304
	v_mfma_f32_16x16x32_bf16 v[50:53], v[210:213], v[190:193], v[50:53]
	ds_read_b128 v[130:133], v240 offset:0
	v_mfma_f32_16x16x32_bf16 v[54:57], v[214:217], v[190:193], v[54:57]
	ds_read_b128 v[134:137], v240 offset:1024
	v_mfma_f32_16x16x32_bf16 v[58:61], v[218:221], v[190:193], v[58:61]
	ds_read_b128 v[138:141], v240 offset:2048
	v_mfma_f32_16x16x32_bf16 v[62:65], v[222:225], v[190:193], v[62:65]
	ds_read_b128 v[142:145], v240 offset:3072
	v_mfma_f32_16x16x32_bf16 v[66:69], v[210:213], v[194:197], v[66:69]
	ds_read_b128 v[146:149], v240 offset:4096
	v_mfma_f32_16x16x32_bf16 v[70:73], v[214:217], v[194:197], v[70:73]
	ds_read_b128 v[150:153], v240 offset:5120
	v_mfma_f32_16x16x32_bf16 v[74:77], v[218:221], v[194:197], v[74:77]
	ds_read_b128 v[154:157], v240 offset:6144
	v_mfma_f32_16x16x32_bf16 v[78:81], v[222:225], v[194:197], v[78:81]
	ds_read_b128 v[158:161], v240 offset:7168
	v_mfma_f32_16x16x32_bf16 v[82:85], v[210:213], v[198:201], v[82:85]
	v_mfma_f32_16x16x32_bf16 v[86:89], v[214:217], v[198:201], v[86:89]
	v_mfma_f32_16x16x32_bf16 v[90:93], v[218:221], v[198:201], v[90:93]
	v_mfma_f32_16x16x32_bf16 v[94:97], v[222:225], v[198:201], v[94:97]
	v_mfma_f32_16x16x32_bf16 v[98:101], v[210:213], v[202:205], v[98:101]
	v_mfma_f32_16x16x32_bf16 v[102:105], v[214:217], v[202:205], v[102:105]
	v_mfma_f32_16x16x32_bf16 v[106:109], v[218:221], v[202:205], v[106:109]
	v_mfma_f32_16x16x32_bf16 v[110:113], v[222:225], v[202:205], v[110:113]
	v_mfma_f32_16x16x32_bf16 v[114:117], v[210:213], v[206:209], v[114:117]
	v_mfma_f32_16x16x32_bf16 v[118:121], v[214:217], v[206:209], v[118:121]
	v_mfma_f32_16x16x32_bf16 v[122:125], v[218:221], v[206:209], v[122:125]
	v_mfma_f32_16x16x32_bf16 v[126:129], v[222:225], v[206:209], v[126:129]
	s_add_i32 s60, s60, 0x6000
	s_cmp_eq_u32 s60, 0x12000
	s_cselect_b32 s60, 0, s60
	s_add_u32 s54, s54, s72
	s_addc_u32 s55, s55, 0
	s_add_u32 s56, s56, s73
	s_addc_u32 s57, s57, 0
	s_add_i32 s61, s61, 0x6000
	s_cmp_eq_u32 s61, 0x12000
	s_cselect_b32 s61, 0, s61
	s_branch .Lup_main
.Lup_tile:
	s_add_i32 s38, s34, s71
	s_cmp_lt_i32 s38, s32
	s_cselect_b32 s37, 1, 0
	s_cbranch_scc0 .Lup_nn_b
	s_cmpk_lt_i32 s38, 0xb00
	s_cbranch_scc0 .Lup_lo_b
	s_and_b32 s26, s38, 7
	s_lshr_b32 s27, s38, 3
	s_lshr_b32 s31, s27, 3
	s_and_b32 s27, s27, 7
	s_lshl_b32 s27, s27, 3
	s_add_i32 s30, s27, s26
	s_branch .Lup_go_b

.Lup_nn_b:
	v_mov_b32_e32 v2, 0
	v_mov_b32_e32 v3, 0
	v_mov_b32_e32 v4, 0
	v_mov_b32_e32 v5, 0
	v_mov_b32_e32 v6, 0
	v_mov_b32_e32 v7, 0
	v_mov_b32_e32 v8, 0
	v_mov_b32_e32 v9, 0
	v_mov_b32_e32 v10, 0
	v_mov_b32_e32 v11, 0
	v_mov_b32_e32 v12, 0
	v_mov_b32_e32 v13, 0
	v_mov_b32_e32 v14, 0
	v_mov_b32_e32 v15, 0
	v_mov_b32_e32 v16, 0
	v_mov_b32_e32 v17, 0
	v_mov_b32_e32 v18, 0
	v_mov_b32_e32 v19, 0
	v_mov_b32_e32 v20, 0
	v_mov_b32_e32 v21, 0
	v_mov_b32_e32 v22, 0
	v_mov_b32_e32 v23, 0
	v_mov_b32_e32 v24, 0
	v_mov_b32_e32 v25, 0
	v_mov_b32_e32 v26, 0
	v_mov_b32_e32 v27, 0
	v_mov_b32_e32 v28, 0
	v_mov_b32_e32 v29, 0
	v_mov_b32_e32 v30, 0
	v_mov_b32_e32 v31, 0
	v_mov_b32_e32 v32, 0
	v_mov_b32_e32 v33, 0
	v_mov_b32_e32 v34, 0
	v_mov_b32_e32 v35, 0
	v_mov_b32_e32 v36, 0
	v_mov_b32_e32 v37, 0
	v_mov_b32_e32 v38, 0
	v_mov_b32_e32 v39, 0
	v_mov_b32_e32 v40, 0
	v_mov_b32_e32 v41, 0
	v_mov_b32_e32 v42, 0
	v_mov_b32_e32 v43, 0
	v_mov_b32_e32 v44, 0
	v_mov_b32_e32 v45, 0
	v_mov_b32_e32 v46, 0
	v_mov_b32_e32 v47, 0
	v_mov_b32_e32 v48, 0
	v_mov_b32_e32 v49, 0
	v_mov_b32_e32 v50, 0
	v_mov_b32_e32 v51, 0
	v_mov_b32_e32 v52, 0
	v_mov_b32_e32 v53, 0
	v_mov_b32_e32 v54, 0
	v_mov_b32_e32 v55, 0
	v_mov_b32_e32 v56, 0
	v_mov_b32_e32 v57, 0
	v_mov_b32_e32 v58, 0
	v_mov_b32_e32 v59, 0
	v_mov_b32_e32 v60, 0
	v_mov_b32_e32 v61, 0
	v_mov_b32_e32 v62, 0
	v_mov_b32_e32 v63, 0
	v_mov_b32_e32 v64, 0
	v_mov_b32_e32 v65, 0
	v_mov_b32_e32 v66, 0
	v_mov_b32_e32 v67, 0
	v_mov_b32_e32 v68, 0
	v_mov_b32_e32 v69, 0
	v_mov_b32_e32 v70, 0
	v_mov_b32_e32 v71, 0
	v_mov_b32_e32 v72, 0
	v_mov_b32_e32 v73, 0
	v_mov_b32_e32 v74, 0
	v_mov_b32_e32 v75, 0
	v_mov_b32_e32 v76, 0
	v_mov_b32_e32 v77, 0
	v_mov_b32_e32 v78, 0
	v_mov_b32_e32 v79, 0
	v_mov_b32_e32 v80, 0
	v_mov_b32_e32 v81, 0
	v_mov_b32_e32 v82, 0
	v_mov_b32_e32 v83, 0
	v_mov_b32_e32 v84, 0
	v_mov_b32_e32 v85, 0
	v_mov_b32_e32 v86, 0
	v_mov_b32_e32 v87, 0
	v_mov_b32_e32 v88, 0
	v_mov_b32_e32 v89, 0
	v_mov_b32_e32 v90, 0
	v_mov_b32_e32 v91, 0
	v_mov_b32_e32 v92, 0
	v_mov_b32_e32 v93, 0
	v_mov_b32_e32 v94, 0
	v_mov_b32_e32 v95, 0
	v_mov_b32_e32 v96, 0
	v_mov_b32_e32 v97, 0
	v_mov_b32_e32 v98, 0
	v_mov_b32_e32 v99, 0
	v_mov_b32_e32 v100, 0
	v_mov_b32_e32 v101, 0
	v_mov_b32_e32 v102, 0
	v_mov_b32_e32 v103, 0
	v_mov_b32_e32 v104, 0
	v_mov_b32_e32 v105, 0
	v_mov_b32_e32 v106, 0
	v_mov_b32_e32 v107, 0
	v_mov_b32_e32 v108, 0
	v_mov_b32_e32 v109, 0
	v_mov_b32_e32 v110, 0
	v_mov_b32_e32 v111, 0
	v_mov_b32_e32 v112, 0
	v_mov_b32_e32 v113, 0
	v_mov_b32_e32 v114, 0
	v_mov_b32_e32 v115, 0
	v_mov_b32_e32 v116, 0
	v_mov_b32_e32 v117, 0
	v_mov_b32_e32 v118, 0
	v_mov_b32_e32 v119, 0
	v_mov_b32_e32 v120, 0
	v_mov_b32_e32 v121, 0
	v_mov_b32_e32 v122, 0
	v_mov_b32_e32 v123, 0
	v_mov_b32_e32 v124, 0
	v_mov_b32_e32 v125, 0
	v_mov_b32_e32 v126, 0
	v_mov_b32_e32 v127, 0
	v_mov_b32_e32 v128, 0
	v_mov_b32_e32 v129, 0
	s_waitcnt vmcnt(14) lgkmcnt(0)
	s_barrier
	v_add_u32_e32 v240, s61, v238
	v_add_u32_e32 v241, s61, v239
	s_add_i32 m0, s60, s62
	v_mfma_f32_16x16x32_bf16 v[2:5], v[162:165], v[130:133], v[2:5]
	global_load_lds_dwordx4 v226, s[54:55]
	v_mfma_f32_16x16x32_bf16 v[6:9], v[166:169], v[130:133], v[6:9]
	global_load_lds_dwordx4 v226, s[54:55] offset:1024
	v_mfma_f32_16x16x32_bf16 v[10:13], v[170:173], v[130:133], v[10:13]
	global_load_lds_dwordx4 v226, s[54:55] offset:2048
	v_mfma_f32_16x16x32_bf16 v[14:17], v[174:177], v[130:133], v[14:17]
	global_load_lds_dwordx4 v226, s[54:55] offset:3072
	s_add_i32 m0, s60, s63
	v_mfma_f32_16x16x32_bf16 v[18:21], v[162:165], v[134:137], v[18:21]
	global_load_lds_dwordx4 v230, s[56:57]
	v_mfma_f32_16x16x32_bf16 v[22:25], v[166:169], v[134:137], v[22:25]
	global_load_lds_dwordx4 v231, s[56:57] offset:1024
	v_mfma_f32_16x16x32_bf16 v[26:29], v[170:173], v[134:137], v[26:29]
	v_mfma_f32_16x16x32_bf16 v[30:33], v[174:177], v[134:137], v[30:33]
	v_mfma_f32_16x16x32_bf16 v[34:37], v[162:165], v[138:141], v[34:37]
	ds_read_b128 v[210:213], v241 offset:0
	v_mfma_f32_16x16x32_bf16 v[38:41], v[166:169], v[138:141], v[38:41]
	ds_read_b128 v[214:217], v241 offset:256
	v_mfma_f32_16x16x32_bf16 v[42:45], v[170:173], v[138:141], v[42:45]
	ds_read_b128 v[218:221], v241 offset:2048
	v_mfma_f32_16x16x32_bf16 v[46:49], v[174:177], v[138:141], v[46:49]
	ds_read_b128 v[222:225], v241 offset:2304
	v_mfma_f32_16x16x32_bf16 v[50:53], v[162:165], v[142:145], v[50:53]
	ds_read_b128 v[178:181], v240 offset:0
	v_mfma_f32_16x16x32_bf16 v[54:57], v[166:169], v[142:145], v[54:57]
	ds_read_b128 v[182:185], v240 offset:1024
	v_mfma_f32_16x16x32_bf16 v[58:61], v[170:173], v[142:145], v[58:61]
	ds_read_b128 v[186:189], v240 offset:2048
	v_mfma_f32_16x16x32_bf16 v[62:65], v[174:177], v[142:145], v[62:65]
	ds_read_b128 v[190:193], v240 offset:3072
	v_mfma_f32_16x16x32_bf16 v[66:69], v[162:165], v[146:149], v[66:69]
	ds_read_b128 v[194:197], v240 offset:4096
	v_mfma_f32_16x16x32_bf16 v[70:73], v[166:169], v[146:149], v[70:73]
	ds_read_b128 v[198:201], v240 offset:5120
	v_mfma_f32_16x16x32_bf16 v[74:77], v[170:173], v[146:149], v[74:77]
	ds_read_b128 v[202:205], v240 offset:6144
	v_mfma_f32_16x16x32_bf16 v[78:81], v[174:177], v[146:149], v[78:81]
	ds_read_b128 v[206:209], v240 offset:7168
	v_mfma_f32_16x16x32_bf16 v[82:85], v[162:165], v[150:153], v[82:85]
	v_mfma_f32_16x16x32_bf16 v[86:89], v[166:169], v[150:153], v[86:89]
	v_mfma_f32_16x16x32_bf16 v[90:93], v[170:173], v[150:153], v[90:93]
	v_mfma_f32_16x16x32_bf16 v[94:97], v[174:177], v[150:153], v[94:97]
	v_mfma_f32_16x16x32_bf16 v[98:101], v[162:165], v[154:157], v[98:101]
	v_mfma_f32_16x16x32_bf16 v[102:105], v[166:169], v[154:157], v[102:105]
	v_mfma_f32_16x16x32_bf16 v[106:109], v[170:173], v[154:157], v[106:109]
	v_mfma_f32_16x16x32_bf16 v[110:113], v[174:177], v[154:157], v[110:113]
	v_mfma_f32_16x16x32_bf16 v[114:117], v[162:165], v[158:161], v[114:117]
	v_mfma_f32_16x16x32_bf16 v[118:121], v[166:169], v[158:161], v[118:121]
	v_mfma_f32_16x16x32_bf16 v[122:125], v[170:173], v[158:161], v[122:125]
	v_mfma_f32_16x16x32_bf16 v[126:129], v[174:177], v[158:161], v[126:129]
	s_add_i32 s60, s60, 0x6000
	s_cmp_eq_u32 s60, 0x12000
	s_cselect_b32 s60, 0, s60
	s_add_u32 s54, s54, s72
	s_addc_u32 s55, s55, 0
	s_add_u32 s56, s56, s73
	s_addc_u32 s57, s57, 0
	s_add_i32 s61, s61, 0x6000
	s_cmp_eq_u32 s61, 0x12000
	s_cselect_b32 s61, 0, s61
	s_waitcnt vmcnt(14) lgkmcnt(0)
	s_barrier
	v_add_u32_e32 v240, s61, v238
	v_add_u32_e32 v241, s61, v239
	s_add_i32 m0, s60, s62
	v_mfma_f32_16x16x32_bf16 v[2:5], v[210:213], v[178:181], v[2:5]
	global_load_lds_dwordx4 v226, s[54:55]
	v_mfma_f32_16x16x32_bf16 v[6:9], v[214:217], v[178:181], v[6:9]
	global_load_lds_dwordx4 v226, s[54:55] offset:1024
	v_mfma_f32_16x16x32_bf16 v[10:13], v[218:221], v[178:181], v[10:13]
	global_load_lds_dwordx4 v226, s[54:55] offset:2048
	v_mfma_f32_16x16x32_bf16 v[14:17], v[222:225], v[178:181], v[14:17]
	global_load_lds_dwordx4 v226, s[54:55] offset:3072
	s_add_i32 m0, s60, s63
	v_mfma_f32_16x16x32_bf16 v[18:21], v[210:213], v[182:185], v[18:21]
	global_load_lds_dwordx4 v230, s[56:57]
	v_mfma_f32_16x16x32_bf16 v[22:25], v[214:217], v[182:185], v[22:25]
	global_load_lds_dwordx4 v231, s[56:57] offset:1024
	v_mfma_f32_16x16x32_bf16 v[26:29], v[218:221], v[182:185], v[26:29]
	v_mfma_f32_16x16x32_bf16 v[30:33], v[222:225], v[182:185], v[30:33]
	v_mfma_f32_16x16x32_bf16 v[34:37], v[210:213], v[186:189], v[34:37]
	ds_read_b128 v[162:165], v241 offset:0
	v_mfma_f32_16x16x32_bf16 v[38:41], v[214:217], v[186:189], v[38:41]
	ds_read_b128 v[166:169], v241 offset:256
	v_mfma_f32_16x16x32_bf16 v[42:45], v[218:221], v[186:189], v[42:45]
	ds_read_b128 v[170:173], v241 offset:2048
	v_mfma_f32_16x16x32_bf16 v[46:49], v[222:225], v[186:189], v[46:49]
	ds_read_b128 v[174:177], v241 offset:2304
	v_mfma_f32_16x16x32_bf16 v[50:53], v[210:213], v[190:193], v[50:53]
	ds_read_b128 v[130:133], v240 offset:0
	v_mfma_f32_16x16x32_bf16 v[54:57], v[214:217], v[190:193], v[54:57]
	ds_read_b128 v[134:137], v240 offset:1024
	v_mfma_f32_16x16x32_bf16 v[58:61], v[218:221], v[190:193], v[58:61]
	ds_read_b128 v[138:141], v240 offset:2048
	v_mfma_f32_16x16x32_bf16 v[62:65], v[222:225], v[190:193], v[62:65]
	ds_read_b128 v[142:145], v240 offset:3072
	v_mfma_f32_16x16x32_bf16 v[66:69], v[210:213], v[194:197], v[66:69]
	ds_read_b128 v[146:149], v240 offset:4096
	v_mfma_f32_16x16x32_bf16 v[70:73], v[214:217], v[194:197], v[70:73]
	ds_read_b128 v[150:153], v240 offset:5120
	v_mfma_f32_16x16x32_bf16 v[74:77], v[218:221], v[194:197], v[74:77]
	ds_read_b128 v[154:157], v240 offset:6144
	v_mfma_f32_16x16x32_bf16 v[78:81], v[222:225], v[194:197], v[78:81]
	ds_read_b128 v[158:161], v240 offset:7168
	v_mfma_f32_16x16x32_bf16 v[82:85], v[210:213], v[198:201], v[82:85]
	v_mfma_f32_16x16x32_bf16 v[86:89], v[214:217], v[198:201], v[86:89]
	v_mfma_f32_16x16x32_bf16 v[90:93], v[218:221], v[198:201], v[90:93]
	v_mfma_f32_16x16x32_bf16 v[94:97], v[222:225], v[198:201], v[94:97]
	v_mfma_f32_16x16x32_bf16 v[98:101], v[210:213], v[202:205], v[98:101]
	v_mfma_f32_16x16x32_bf16 v[102:105], v[214:217], v[202:205], v[102:105]
	v_mfma_f32_16x16x32_bf16 v[106:109], v[218:221], v[202:205], v[106:109]
	v_mfma_f32_16x16x32_bf16 v[110:113], v[222:225], v[202:205], v[110:113]
	v_mfma_f32_16x16x32_bf16 v[114:117], v[210:213], v[206:209], v[114:117]
	v_mfma_f32_16x16x32_bf16 v[118:121], v[214:217], v[206:209], v[118:121]
	v_mfma_f32_16x16x32_bf16 v[122:125], v[218:221], v[206:209], v[122:125]
	v_mfma_f32_16x16x32_bf16 v[126:129], v[222:225], v[206:209], v[126:129]
	s_add_i32 s60, s60, 0x6000
	s_cmp_eq_u32 s60, 0x12000
	s_cselect_b32 s60, 0, s60
	s_add_u32 s54, s54, s72
	s_addc_u32 s55, s55, 0
	s_add_u32 s56, s56, s73
	s_addc_u32 s57, s57, 0
	s_add_i32 s61, s61, 0x6000
	s_cmp_eq_u32 s61, 0x12000
	s_cselect_b32 s61, 0, s61

.Lup_kloop:
	s_waitcnt vmcnt(6) lgkmcnt(0)
	s_barrier
	v_add_u32_e32 v240, s61, v238
	v_add_u32_e32 v241, s61, v239
	s_add_i32 m0, s60, s62
	v_mfma_f32_16x16x32_bf16 v[2:5], v[162:165], v[130:133], v[2:5]
	global_load_lds_dwordx4 v226, s[54:55]
	v_mfma_f32_16x16x32_bf16 v[6:9], v[166:169], v[130:133], v[6:9]
	global_load_lds_dwordx4 v226, s[54:55] offset:1024
	v_mfma_f32_16x16x32_bf16 v[10:13], v[170:173], v[130:133], v[10:13]
	global_load_lds_dwordx4 v226, s[54:55] offset:2048
	v_mfma_f32_16x16x32_bf16 v[14:17], v[174:177], v[130:133], v[14:17]
	global_load_lds_dwordx4 v226, s[54:55] offset:3072
	s_add_i32 m0, s60, s63
	v_mfma_f32_16x16x32_bf16 v[18:21], v[162:165], v[134:137], v[18:21]
	global_load_lds_dwordx4 v230, s[56:57]
	v_mfma_f32_16x16x32_bf16 v[22:25], v[166:169], v[134:137], v[22:25]
	global_load_lds_dwordx4 v231, s[56:57] offset:1024
	v_mfma_f32_16x16x32_bf16 v[26:29], v[170:173], v[134:137], v[26:29]
	v_mfma_f32_16x16x32_bf16 v[30:33], v[174:177], v[134:137], v[30:33]
	v_mfma_f32_16x16x32_bf16 v[34:37], v[162:165], v[138:141], v[34:37]
	ds_read_b128 v[210:213], v241 offset:0
	v_mfma_f32_16x16x32_bf16 v[38:41], v[166:169], v[138:141], v[38:41]
	ds_read_b128 v[214:217], v241 offset:256
	v_mfma_f32_16x16x32_bf16 v[42:45], v[170:173], v[138:141], v[42:45]
	ds_read_b128 v[218:221], v241 offset:2048
	v_mfma_f32_16x16x32_bf16 v[46:49], v[174:177], v[138:141], v[46:49]
	ds_read_b128 v[222:225], v241 offset:2304
	v_mfma_f32_16x16x32_bf16 v[50:53], v[162:165], v[142:145], v[50:53]
	ds_read_b128 v[178:181], v240 offset:0
	v_mfma_f32_16x16x32_bf16 v[54:57], v[166:169], v[142:145], v[54:57]
	ds_read_b128 v[182:185], v240 offset:1024
	v_mfma_f32_16x16x32_bf16 v[58:61], v[170:173], v[142:145], v[58:61]
	ds_read_b128 v[186:189], v240 offset:2048
	v_mfma_f32_16x16x32_bf16 v[62:65], v[174:177], v[142:145], v[62:65]
	ds_read_b128 v[190:193], v240 offset:3072
	v_mfma_f32_16x16x32_bf16 v[66:69], v[162:165], v[146:149], v[66:69]
	ds_read_b128 v[194:197], v240 offset:4096
	v_mfma_f32_16x16x32_bf16 v[70:73], v[166:169], v[146:149], v[70:73]
	ds_read_b128 v[198:201], v240 offset:5120
	v_mfma_f32_16x16x32_bf16 v[74:77], v[170:173], v[146:149], v[74:77]
	ds_read_b128 v[202:205], v240 offset:6144
	v_mfma_f32_16x16x32_bf16 v[78:81], v[174:177], v[146:149], v[78:81]
	ds_read_b128 v[206:209], v240 offset:7168
	v_mfma_f32_16x16x32_bf16 v[82:85], v[162:165], v[150:153], v[82:85]
	v_mfma_f32_16x16x32_bf16 v[86:89], v[166:169], v[150:153], v[86:89]
	v_mfma_f32_16x16x32_bf16 v[90:93], v[170:173], v[150:153], v[90:93]
	v_mfma_f32_16x16x32_bf16 v[94:97], v[174:177], v[150:153], v[94:97]
	v_mfma_f32_16x16x32_bf16 v[98:101], v[162:165], v[154:157], v[98:101]
	v_mfma_f32_16x16x32_bf16 v[102:105], v[166:169], v[154:157], v[102:105]
	v_mfma_f32_16x16x32_bf16 v[106:109], v[170:173], v[154:157], v[106:109]
	v_mfma_f32_16x16x32_bf16 v[110:113], v[174:177], v[154:157], v[110:113]
	v_mfma_f32_16x16x32_bf16 v[114:117], v[162:165], v[158:161], v[114:117]
	v_mfma_f32_16x16x32_bf16 v[118:121], v[166:169], v[158:161], v[118:121]
	v_mfma_f32_16x16x32_bf16 v[122:125], v[170:173], v[158:161], v[122:125]
	v_mfma_f32_16x16x32_bf16 v[126:129], v[174:177], v[158:161], v[126:129]
	s_add_i32 s60, s60, 0x6000
	s_cmp_eq_u32 s60, 0x12000
	s_cselect_b32 s60, 0, s60
	s_add_u32 s54, s54, s72
	s_addc_u32 s55, s55, 0
	s_add_u32 s56, s56, s73
	s_addc_u32 s57, s57, 0
	s_add_i32 s61, s61, 0x6000
	s_cmp_eq_u32 s61, 0x12000
	s_cselect_b32 s61, 0, s61
	s_waitcnt vmcnt(6) lgkmcnt(0)
	s_barrier
	v_add_u32_e32 v240, s61, v238
	v_add_u32_e32 v241, s61, v239
	s_add_i32 m0, s60, s62
	v_mfma_f32_16x16x32_bf16 v[2:5], v[210:213], v[178:181], v[2:5]
	global_load_lds_dwordx4 v226, s[54:55]
	v_mfma_f32_16x16x32_bf16 v[6:9], v[214:217], v[178:181], v[6:9]
	global_load_lds_dwordx4 v226, s[54:55] offset:1024
	v_mfma_f32_16x16x32_bf16 v[10:13], v[218:221], v[178:181], v[10:13]
	global_load_lds_dwordx4 v226, s[54:55] offset:2048
	v_mfma_f32_16x16x32_bf16 v[14:17], v[222:225], v[178:181], v[14:17]
	global_load_lds_dwordx4 v226, s[54:55] offset:3072
	s_add_i32 m0, s60, s63
	v_mfma_f32_16x16x32_bf16 v[18:21], v[210:213], v[182:185], v[18:21]
	global_load_lds_dwordx4 v230, s[56:57]
	v_mfma_f32_16x16x32_bf16 v[22:25], v[214:217], v[182:185], v[22:25]
	global_load_lds_dwordx4 v231, s[56:57] offset:1024
	v_mfma_f32_16x16x32_bf16 v[26:29], v[218:221], v[182:185], v[26:29]
	v_mfma_f32_16x16x32_bf16 v[30:33], v[222:225], v[182:185], v[30:33]
	v_mfma_f32_16x16x32_bf16 v[34:37], v[210:213], v[186:189], v[34:37]
	ds_read_b128 v[162:165], v241 offset:0
	v_mfma_f32_16x16x32_bf16 v[38:41], v[214:217], v[186:189], v[38:41]
	ds_read_b128 v[166:169], v241 offset:256
	v_mfma_f32_16x16x32_bf16 v[42:45], v[218:221], v[186:189], v[42:45]
	ds_read_b128 v[170:173], v241 offset:2048
	v_mfma_f32_16x16x32_bf16 v[46:49], v[222:225], v[186:189], v[46:49]
	ds_read_b128 v[174:177], v241 offset:2304
	v_mfma_f32_16x16x32_bf16 v[50:53], v[210:213], v[190:193], v[50:53]
	ds_read_b128 v[130:133], v240 offset:0
	v_mfma_f32_16x16x32_bf16 v[54:57], v[214:217], v[190:193], v[54:57]
	ds_read_b128 v[134:137], v240 offset:1024
	v_mfma_f32_16x16x32_bf16 v[58:61], v[218:221], v[190:193], v[58:61]
	ds_read_b128 v[138:141], v240 offset:2048
	v_mfma_f32_16x16x32_bf16 v[62:65], v[222:225], v[190:193], v[62:65]
	ds_read_b128 v[142:145], v240 offset:3072
	v_mfma_f32_16x16x32_bf16 v[66:69], v[210:213], v[194:197], v[66:69]
	ds_read_b128 v[146:149], v240 offset:4096
	v_mfma_f32_16x16x32_bf16 v[70:73], v[214:217], v[194:197], v[70:73]
	ds_read_b128 v[150:153], v240 offset:5120
	v_mfma_f32_16x16x32_bf16 v[74:77], v[218:221], v[194:197], v[74:77]
	ds_read_b128 v[154:157], v240 offset:6144
	v_mfma_f32_16x16x32_bf16 v[78:81], v[222:225], v[194:197], v[78:81]
	ds_read_b128 v[158:161], v240 offset:7168
	v_mfma_f32_16x16x32_bf16 v[82:85], v[210:213], v[198:201], v[82:85]
	v_mfma_f32_16x16x32_bf16 v[86:89], v[214:217], v[198:201], v[86:89]
	v_mfma_f32_16x16x32_bf16 v[90:93], v[218:221], v[198:201], v[90:93]
	v_mfma_f32_16x16x32_bf16 v[94:97], v[222:225], v[198:201], v[94:97]
	v_mfma_f32_16x16x32_bf16 v[98:101], v[210:213], v[202:205], v[98:101]
	v_mfma_f32_16x16x32_bf16 v[102:105], v[214:217], v[202:205], v[102:105]
	v_mfma_f32_16x16x32_bf16 v[106:109], v[218:221], v[202:205], v[106:109]
	v_mfma_f32_16x16x32_bf16 v[110:113], v[222:225], v[202:205], v[110:113]
	v_mfma_f32_16x16x32_bf16 v[114:117], v[210:213], v[206:209], v[114:117]
	v_mfma_f32_16x16x32_bf16 v[118:121], v[214:217], v[206:209], v[118:121]
	v_mfma_f32_16x16x32_bf16 v[122:125], v[218:221], v[206:209], v[122:125]
	v_mfma_f32_16x16x32_bf16 v[126:129], v[222:225], v[206:209], v[126:129]
	s_add_i32 s60, s60, 0x6000
	s_cmp_eq_u32 s60, 0x12000
	s_cselect_b32 s60, 0, s60
	s_add_u32 s54, s54, s72
	s_addc_u32 s55, s55, 0
	s_add_u32 s56, s56, s73
	s_addc_u32 s57, s57, 0
	s_add_i32 s61, s61, 0x6000
	s_cmp_eq_u32 s61, 0x12000
	s_cselect_b32 s61, 0, s61
	s_add_i32 s40, s40, -1
	s_cmp_lg_u32 s40, 0
	s_cbranch_scc1 .Lup_kloop
	s_cmp_eq_u32 s37, 0
	s_cbranch_scc1 .Lup_tail_last
	s_waitcnt vmcnt(6) lgkmcnt(0)
	s_barrier
	v_add_u32_e32 v240, s61, v238
	v_add_u32_e32 v241, s61, v239
	s_add_i32 m0, s60, s62
	v_mfma_f32_16x16x32_bf16 v[2:5], v[162:165], v[130:133], v[2:5]
	global_load_lds_dwordx4 v226, s[54:55]
	v_mfma_f32_16x16x32_bf16 v[6:9], v[166:169], v[130:133], v[6:9]
	global_load_lds_dwordx4 v226, s[54:55] offset:1024
	v_mfma_f32_16x16x32_bf16 v[10:13], v[170:173], v[130:133], v[10:13]
	global_load_lds_dwordx4 v226, s[54:55] offset:2048
	v_mfma_f32_16x16x32_bf16 v[14:17], v[174:177], v[130:133], v[14:17]
	global_load_lds_dwordx4 v226, s[54:55] offset:3072
	s_add_i32 m0, s60, s63
	v_mfma_f32_16x16x32_bf16 v[18:21], v[162:165], v[134:137], v[18:21]
	global_load_lds_dwordx4 v230, s[56:57]
	v_mfma_f32_16x16x32_bf16 v[22:25], v[166:169], v[134:137], v[22:25]
	global_load_lds_dwordx4 v231, s[56:57] offset:1024
	v_mfma_f32_16x16x32_bf16 v[26:29], v[170:173], v[134:137], v[26:29]
	v_mfma_f32_16x16x32_bf16 v[30:33], v[174:177], v[134:137], v[30:33]
	v_mfma_f32_16x16x32_bf16 v[34:37], v[162:165], v[138:141], v[34:37]
	ds_read_b128 v[210:213], v241 offset:0
	v_mfma_f32_16x16x32_bf16 v[38:41], v[166:169], v[138:141], v[38:41]
	ds_read_b128 v[214:217], v241 offset:256
	v_mfma_f32_16x16x32_bf16 v[42:45], v[170:173], v[138:141], v[42:45]
	ds_read_b128 v[218:221], v241 offset:2048
	v_mfma_f32_16x16x32_bf16 v[46:49], v[174:177], v[138:141], v[46:49]
	ds_read_b128 v[222:225], v241 offset:2304
	v_mfma_f32_16x16x32_bf16 v[50:53], v[162:165], v[142:145], v[50:53]
	ds_read_b128 v[178:181], v240 offset:0
	v_mfma_f32_16x16x32_bf16 v[54:57], v[166:169], v[142:145], v[54:57]
	ds_read_b128 v[182:185], v240 offset:1024
	v_mfma_f32_16x16x32_bf16 v[58:61], v[170:173], v[142:145], v[58:61]
	ds_read_b128 v[186:189], v240 offset:2048
	v_mfma_f32_16x16x32_bf16 v[62:65], v[174:177], v[142:145], v[62:65]
	ds_read_b128 v[190:193], v240 offset:3072
	v_mfma_f32_16x16x32_bf16 v[66:69], v[162:165], v[146:149], v[66:69]
	ds_read_b128 v[194:197], v240 offset:4096
	v_mfma_f32_16x16x32_bf16 v[70:73], v[166:169], v[146:149], v[70:73]
	ds_read_b128 v[198:201], v240 offset:5120
	v_mfma_f32_16x16x32_bf16 v[74:77], v[170:173], v[146:149], v[74:77]
	ds_read_b128 v[202:205], v240 offset:6144
	v_mfma_f32_16x16x32_bf16 v[78:81], v[174:177], v[146:149], v[78:81]
	ds_read_b128 v[206:209], v240 offset:7168
	v_mfma_f32_16x16x32_bf16 v[82:85], v[162:165], v[150:153], v[82:85]
	v_mfma_f32_16x16x32_bf16 v[86:89], v[166:169], v[150:153], v[86:89]
	v_mfma_f32_16x16x32_bf16 v[90:93], v[170:173], v[150:153], v[90:93]
	v_mfma_f32_16x16x32_bf16 v[94:97], v[174:177], v[150:153], v[94:97]
	v_mfma_f32_16x16x32_bf16 v[98:101], v[162:165], v[154:157], v[98:101]
	v_mfma_f32_16x16x32_bf16 v[102:105], v[166:169], v[154:157], v[102:105]
	v_mfma_f32_16x16x32_bf16 v[106:109], v[170:173], v[154:157], v[106:109]
	v_mfma_f32_16x16x32_bf16 v[110:113], v[174:177], v[154:157], v[110:113]
	v_mfma_f32_16x16x32_bf16 v[114:117], v[162:165], v[158:161], v[114:117]
	v_mfma_f32_16x16x32_bf16 v[118:121], v[166:169], v[158:161], v[118:121]
	v_mfma_f32_16x16x32_bf16 v[122:125], v[170:173], v[158:161], v[122:125]
	v_mfma_f32_16x16x32_bf16 v[126:129], v[174:177], v[158:161], v[126:129]
	s_add_i32 s60, s60, 0x6000
	s_cmp_eq_u32 s60, 0x12000
	s_cselect_b32 s60, 0, s60
	s_add_u32 s54, s54, s72
	s_addc_u32 s55, s55, 0
	s_add_u32 s56, s56, s73
	s_addc_u32 s57, s57, 0
	s_add_i32 s61, s61, 0x6000
	s_cmp_eq_u32 s61, 0x12000
	s_cselect_b32 s61, 0, s61
	v_mov_b32_e32 v226, v232
	v_mov_b32_e32 v230, v236
	v_mov_b32_e32 v231, v237
	s_mov_b64 s[54:55], s[48:49]
	s_mov_b64 s[56:57], s[50:51]
	s_waitcnt vmcnt(6) lgkmcnt(0)
	s_barrier
	v_add_u32_e32 v240, s61, v238
	v_add_u32_e32 v241, s61, v239
	s_add_i32 m0, s60, s62
	v_mfma_f32_16x16x32_bf16 v[2:5], v[210:213], v[178:181], v[2:5]
	global_load_lds_dwordx4 v226, s[54:55]
	v_mfma_f32_16x16x32_bf16 v[6:9], v[214:217], v[178:181], v[6:9]
	global_load_lds_dwordx4 v226, s[54:55] offset:1024
	v_mfma_f32_16x16x32_bf16 v[10:13], v[218:221], v[178:181], v[10:13]
	global_load_lds_dwordx4 v226, s[54:55] offset:2048
	v_mfma_f32_16x16x32_bf16 v[14:17], v[222:225], v[178:181], v[14:17]
	global_load_lds_dwordx4 v226, s[54:55] offset:3072
	s_add_i32 m0, s60, s63
	v_mfma_f32_16x16x32_bf16 v[18:21], v[210:213], v[182:185], v[18:21]
	global_load_lds_dwordx4 v230, s[56:57]
	v_mfma_f32_16x16x32_bf16 v[22:25], v[214:217], v[182:185], v[22:25]
	global_load_lds_dwordx4 v231, s[56:57] offset:1024
	v_mfma_f32_16x16x32_bf16 v[26:29], v[218:221], v[182:185], v[26:29]
	v_mfma_f32_16x16x32_bf16 v[30:33], v[222:225], v[182:185], v[30:33]
	v_mfma_f32_16x16x32_bf16 v[34:37], v[210:213], v[186:189], v[34:37]
	ds_read_b128 v[162:165], v241 offset:0
	v_mfma_f32_16x16x32_bf16 v[38:41], v[214:217], v[186:189], v[38:41]
	ds_read_b128 v[166:169], v241 offset:256
	v_mfma_f32_16x16x32_bf16 v[42:45], v[218:221], v[186:189], v[42:45]
	ds_read_b128 v[170:173], v241 offset:2048
	v_mfma_f32_16x16x32_bf16 v[46:49], v[222:225], v[186:189], v[46:49]
	ds_read_b128 v[174:177], v241 offset:2304
	v_mfma_f32_16x16x32_bf16 v[50:53], v[210:213], v[190:193], v[50:53]
	ds_read_b128 v[130:133], v240 offset:0
	v_mfma_f32_16x16x32_bf16 v[54:57], v[214:217], v[190:193], v[54:57]
	ds_read_b128 v[134:137], v240 offset:1024
	v_mfma_f32_16x16x32_bf16 v[58:61], v[218:221], v[190:193], v[58:61]
	ds_read_b128 v[138:141], v240 offset:2048
	v_mfma_f32_16x16x32_bf16 v[62:65], v[222:225], v[190:193], v[62:65]
	ds_read_b128 v[142:145], v240 offset:3072
	v_mfma_f32_16x16x32_bf16 v[66:69], v[210:213], v[194:197], v[66:69]
	ds_read_b128 v[146:149], v240 offset:4096
	v_mfma_f32_16x16x32_bf16 v[70:73], v[214:217], v[194:197], v[70:73]
	ds_read_b128 v[150:153], v240 offset:5120
	v_mfma_f32_16x16x32_bf16 v[74:77], v[218:221], v[194:197], v[74:77]
	ds_read_b128 v[154:157], v240 offset:6144
	v_mfma_f32_16x16x32_bf16 v[78:81], v[222:225], v[194:197], v[78:81]
	ds_read_b128 v[158:161], v240 offset:7168
	v_mfma_f32_16x16x32_bf16 v[82:85], v[210:213], v[198:201], v[82:85]
	v_mfma_f32_16x16x32_bf16 v[86:89], v[214:217], v[198:201], v[86:89]
	v_mfma_f32_16x16x32_bf16 v[90:93], v[218:221], v[198:201], v[90:93]
	v_mfma_f32_16x16x32_bf16 v[94:97], v[222:225], v[198:201], v[94:97]
	v_mfma_f32_16x16x32_bf16 v[98:101], v[210:213], v[202:205], v[98:101]
	v_mfma_f32_16x16x32_bf16 v[102:105], v[214:217], v[202:205], v[102:105]
	v_mfma_f32_16x16x32_bf16 v[106:109], v[218:221], v[202:205], v[106:109]
	v_mfma_f32_16x16x32_bf16 v[110:113], v[222:225], v[202:205], v[110:113]
	v_mfma_f32_16x16x32_bf16 v[114:117], v[210:213], v[206:209], v[114:117]
	v_mfma_f32_16x16x32_bf16 v[118:121], v[214:217], v[206:209], v[118:121]
	v_mfma_f32_16x16x32_bf16 v[122:125], v[218:221], v[206:209], v[122:125]
	v_mfma_f32_16x16x32_bf16 v[126:129], v[222:225], v[206:209], v[126:129]
	s_add_i32 s60, s60, 0x6000
	s_cmp_eq_u32 s60, 0x12000
	s_cselect_b32 s60, 0, s60
	s_add_u32 s54, s54, s72
	s_addc_u32 s55, s55, 0
	s_add_u32 s56, s56, s73
	s_addc_u32 s57, s57, 0
	s_add_i32 s61, s61, 0x6000
	s_cmp_eq_u32 s61, 0x12000
	s_cselect_b32 s61, 0, s61
	s_waitcnt vmcnt(6) lgkmcnt(0)
	s_barrier
	v_add_u32_e32 v240, s61, v238
	v_add_u32_e32 v241, s61, v239
	s_add_i32 m0, s60, s62
	v_mfma_f32_16x16x32_bf16 v[2:5], v[162:165], v[130:133], v[2:5]
	global_load_lds_dwordx4 v226, s[54:55]
	v_mfma_f32_16x16x32_bf16 v[6:9], v[166:169], v[130:133], v[6:9]
	global_load_lds_dwordx4 v226, s[54:55] offset:1024
	v_mfma_f32_16x16x32_bf16 v[10:13], v[170:173], v[130:133], v[10:13]
	global_load_lds_dwordx4 v226, s[54:55] offset:2048
	v_mfma_f32_16x16x32_bf16 v[14:17], v[174:177], v[130:133], v[14:17]
	global_load_lds_dwordx4 v226, s[54:55] offset:3072
	s_add_i32 m0, s60, s63
	v_mfma_f32_16x16x32_bf16 v[18:21], v[162:165], v[134:137], v[18:21]
	global_load_lds_dwordx4 v230, s[56:57]
	v_mfma_f32_16x16x32_bf16 v[22:25], v[166:169], v[134:137], v[22:25]
	global_load_lds_dwordx4 v231, s[56:57] offset:1024
	v_mfma_f32_16x16x32_bf16 v[26:29], v[170:173], v[134:137], v[26:29]
	v_mfma_f32_16x16x32_bf16 v[30:33], v[174:177], v[134:137], v[30:33]
	v_mfma_f32_16x16x32_bf16 v[34:37], v[162:165], v[138:141], v[34:37]
	ds_read_b128 v[210:213], v241 offset:0
	v_mfma_f32_16x16x32_bf16 v[38:41], v[166:169], v[138:141], v[38:41]
	ds_read_b128 v[214:217], v241 offset:256
	v_mfma_f32_16x16x32_bf16 v[42:45], v[170:173], v[138:141], v[42:45]
	ds_read_b128 v[218:221], v241 offset:2048
	v_mfma_f32_16x16x32_bf16 v[46:49], v[174:177], v[138:141], v[46:49]
	ds_read_b128 v[222:225], v241 offset:2304
	v_mfma_f32_16x16x32_bf16 v[50:53], v[162:165], v[142:145], v[50:53]
	ds_read_b128 v[178:181], v240 offset:0
	v_mfma_f32_16x16x32_bf16 v[54:57], v[166:169], v[142:145], v[54:57]
	ds_read_b128 v[182:185], v240 offset:1024
	v_mfma_f32_16x16x32_bf16 v[58:61], v[170:173], v[142:145], v[58:61]
	ds_read_b128 v[186:189], v240 offset:2048
	v_mfma_f32_16x16x32_bf16 v[62:65], v[174:177], v[142:145], v[62:65]
	ds_read_b128 v[190:193], v240 offset:3072
	v_mfma_f32_16x16x32_bf16 v[66:69], v[162:165], v[146:149], v[66:69]
	ds_read_b128 v[194:197], v240 offset:4096
	v_mfma_f32_16x16x32_bf16 v[70:73], v[166:169], v[146:149], v[70:73]
	ds_read_b128 v[198:201], v240 offset:5120
	v_mfma_f32_16x16x32_bf16 v[74:77], v[170:173], v[146:149], v[74:77]
	ds_read_b128 v[202:205], v240 offset:6144
	v_mfma_f32_16x16x32_bf16 v[78:81], v[174:177], v[146:149], v[78:81]
	ds_read_b128 v[206:209], v240 offset:7168
	v_mfma_f32_16x16x32_bf16 v[82:85], v[162:165], v[150:153], v[82:85]
	v_mfma_f32_16x16x32_bf16 v[86:89], v[166:169], v[150:153], v[86:89]
	v_mfma_f32_16x16x32_bf16 v[90:93], v[170:173], v[150:153], v[90:93]
	v_mfma_f32_16x16x32_bf16 v[94:97], v[174:177], v[150:153], v[94:97]
	v_mfma_f32_16x16x32_bf16 v[98:101], v[162:165], v[154:157], v[98:101]
	v_mfma_f32_16x16x32_bf16 v[102:105], v[166:169], v[154:157], v[102:105]
	v_mfma_f32_16x16x32_bf16 v[106:109], v[170:173], v[154:157], v[106:109]
	v_mfma_f32_16x16x32_bf16 v[110:113], v[174:177], v[154:157], v[110:113]
	v_mfma_f32_16x16x32_bf16 v[114:117], v[162:165], v[158:161], v[114:117]
	v_mfma_f32_16x16x32_bf16 v[118:121], v[166:169], v[158:161], v[118:121]
	v_mfma_f32_16x16x32_bf16 v[122:125], v[170:173], v[158:161], v[122:125]
	v_mfma_f32_16x16x32_bf16 v[126:129], v[174:177], v[158:161], v[126:129]
	s_add_i32 s60, s60, 0x6000
	s_cmp_eq_u32 s60, 0x12000
	s_cselect_b32 s60, 0, s60
	s_add_u32 s54, s54, s72
	s_addc_u32 s55, s55, 0
	s_add_u32 s56, s56, s73
	s_addc_u32 s57, s57, 0
	s_add_i32 s61, s61, 0x6000
	s_cmp_eq_u32 s61, 0x12000
	s_cselect_b32 s61, 0, s61
	s_waitcnt vmcnt(6) lgkmcnt(0)
	s_barrier
	v_add_u32_e32 v240, s61, v238
	v_add_u32_e32 v241, s61, v239
	s_add_i32 m0, s60, s62
	v_mfma_f32_16x16x32_bf16 v[2:5], v[210:213], v[178:181], v[2:5]
	global_load_lds_dwordx4 v226, s[54:55]
	v_mfma_f32_16x16x32_bf16 v[6:9], v[214:217], v[178:181], v[6:9]
	global_load_lds_dwordx4 v226, s[54:55] offset:1024
	v_mfma_f32_16x16x32_bf16 v[10:13], v[218:221], v[178:181], v[10:13]
	global_load_lds_dwordx4 v226, s[54:55] offset:2048
	v_mfma_f32_16x16x32_bf16 v[14:17], v[222:225], v[178:181], v[14:17]
	global_load_lds_dwordx4 v226, s[54:55] offset:3072
	s_add_i32 m0, s60, s63
	v_mfma_f32_16x16x32_bf16 v[18:21], v[210:213], v[182:185], v[18:21]
	global_load_lds_dwordx4 v230, s[56:57]
	v_mfma_f32_16x16x32_bf16 v[22:25], v[214:217], v[182:185], v[22:25]
	global_load_lds_dwordx4 v231, s[56:57] offset:1024
	v_mfma_f32_16x16x32_bf16 v[26:29], v[218:221], v[182:185], v[26:29]
	v_mfma_f32_16x16x32_bf16 v[30:33], v[222:225], v[182:185], v[30:33]
	v_mfma_f32_16x16x32_bf16 v[34:37], v[210:213], v[186:189], v[34:37]
	ds_read_b128 v[162:165], v241 offset:0
	v_mfma_f32_16x16x32_bf16 v[38:41], v[214:217], v[186:189], v[38:41]
	ds_read_b128 v[166:169], v241 offset:256
	v_mfma_f32_16x16x32_bf16 v[42:45], v[218:221], v[186:189], v[42:45]
	ds_read_b128 v[170:173], v241 offset:2048
	v_mfma_f32_16x16x32_bf16 v[46:49], v[222:225], v[186:189], v[46:49]
	ds_read_b128 v[174:177], v241 offset:2304
	v_mfma_f32_16x16x32_bf16 v[50:53], v[210:213], v[190:193], v[50:53]
	ds_read_b128 v[130:133], v240 offset:0
	v_mfma_f32_16x16x32_bf16 v[54:57], v[214:217], v[190:193], v[54:57]
	ds_read_b128 v[134:137], v240 offset:1024
	v_mfma_f32_16x16x32_bf16 v[58:61], v[218:221], v[190:193], v[58:61]
	ds_read_b128 v[138:141], v240 offset:2048
	v_mfma_f32_16x16x32_bf16 v[62:65], v[222:225], v[190:193], v[62:65]
	ds_read_b128 v[142:145], v240 offset:3072
	v_mfma_f32_16x16x32_bf16 v[66:69], v[210:213], v[194:197], v[66:69]
	ds_read_b128 v[146:149], v240 offset:4096
	v_mfma_f32_16x16x32_bf16 v[70:73], v[214:217], v[194:197], v[70:73]
	ds_read_b128 v[150:153], v240 offset:5120
	v_mfma_f32_16x16x32_bf16 v[74:77], v[218:221], v[194:197], v[74:77]
	ds_read_b128 v[154:157], v240 offset:6144
	v_mfma_f32_16x16x32_bf16 v[78:81], v[222:225], v[194:197], v[78:81]
	ds_read_b128 v[158:161], v240 offset:7168
	v_mfma_f32_16x16x32_bf16 v[82:85], v[210:213], v[198:201], v[82:85]
	v_mfma_f32_16x16x32_bf16 v[86:89], v[214:217], v[198:201], v[86:89]
	v_mfma_f32_16x16x32_bf16 v[90:93], v[218:221], v[198:201], v[90:93]
	v_mfma_f32_16x16x32_bf16 v[94:97], v[222:225], v[198:201], v[94:97]
	v_mfma_f32_16x16x32_bf16 v[98:101], v[210:213], v[202:205], v[98:101]
	v_mfma_f32_16x16x32_bf16 v[102:105], v[214:217], v[202:205], v[102:105]
	v_mfma_f32_16x16x32_bf16 v[106:109], v[218:221], v[202:205], v[106:109]
	v_mfma_f32_16x16x32_bf16 v[110:113], v[222:225], v[202:205], v[110:113]
	v_mfma_f32_16x16x32_bf16 v[114:117], v[210:213], v[206:209], v[114:117]
	v_mfma_f32_16x16x32_bf16 v[118:121], v[214:217], v[206:209], v[118:121]
	v_mfma_f32_16x16x32_bf16 v[122:125], v[218:221], v[206:209], v[122:125]
	v_mfma_f32_16x16x32_bf16 v[126:129], v[222:225], v[206:209], v[126:129]
	s_add_i32 s60, s60, 0x6000
	s_cmp_eq_u32 s60, 0x12000
	s_cselect_b32 s60, 0, s60
	s_add_u32 s54, s54, s72
	s_addc_u32 s55, s55, 0
	s_add_u32 s56, s56, s73
	s_addc_u32 s57, s57, 0
	s_add_i32 s61, s61, 0x6000
	s_cmp_eq_u32 s61, 0x12000
	s_cselect_b32 s61, 0, s61
	s_and_b32 s39, s35, 0xfff
	s_lshr_b32 s21, s36, 7
	s_lshl_b32 s26, s21, 8
	v_add_u32_e32 v216, s26, v228
	global_load_dwordx4 v[178:181], v216, s[82:83]
	global_load_dwordx4 v[182:185], v216, s[82:83] offset:16
	global_load_dwordx4 v[186:189], v216, s[92:93]
	global_load_dwordx4 v[190:193], v216, s[92:93] offset:16
	global_load_dwordx4 v[194:197], v216, s[96:97]
	global_load_dwordx4 v[198:201], v216, s[96:97] offset:16
	global_load_dwordx4 v[202:205], v216, s[28:29]
	global_load_dwordx4 v[206:209], v216, s[28:29] offset:16
	v_mbcnt_lo_u32_b32 v217, -1, 0
	v_mbcnt_hi_u32_b32 v217, -1, v217
	v_lshlrev_b32_e32 v217, 5, v217
	s_lshl_b32 s26, s43, 11
	s_add_i32 s26, s26, 0x12010
	v_add_u32_e32 v217, s26, v217
	s_cmp_eq_u32 s42, 0
	s_cbranch_scc0 .Lup_en_nowr
	ds_write_b128 v217, v[114:117]
	ds_write_b128 v217, v[118:121] offset:16
.Lup_en_nowr:
	s_waitcnt lgkmcnt(0)
	s_barrier
	s_cmp_eq_u32 s42, 0
	s_cbranch_scc1 .Lup_en_top
	ds_read_b128 v[218:221], v217
	ds_read_b128 v[222:225], v217 offset:16
	s_branch .Lup_en_cont
.Lup_en_top:
	v_mov_b32_e32 v218, 0
	v_mov_b32_e32 v219, 0
	v_mov_b32_e32 v220, 0
	v_mov_b32_e32 v221, 0
	v_mov_b32_e32 v222, 0
	v_mov_b32_e32 v223, 0
	v_mov_b32_e32 v224, 0
	v_mov_b32_e32 v225, 0
	s_cmp_eq_u32 s39, 0
	s_cbranch_scc0 .Lup_en_cont
	v_cmp_gt_u32_e64 s[24:25], 2, v227
	s_nop 1
	v_cndmask_b32_e64 v2, v2, 0, s[24:25]
	v_cndmask_b32_e64 v3, v3, 0, s[24:25]
	v_cndmask_b32_e64 v4, v4, 0, s[24:25]
	v_cndmask_b32_e64 v5, v5, 0, s[24:25]
	v_cndmask_b32_e64 v6, v6, 0, s[24:25]
	v_cndmask_b32_e64 v7, v7, 0, s[24:25]
	v_cndmask_b32_e64 v8, v8, 0, s[24:25]
	v_cndmask_b32_e64 v9, v9, 0, s[24:25]
.Lup_en_cont:
	s_lshl_b32 s26, s21, 1
	s_add_i32 s26, s26, s43
	s_lshl_b32 s26, s26, 20
	s_lshl_b32 s27, s35, 6
	s_add_u32 s18, s52, s26
	s_addc_u32 s19, s53, 0
	s_add_u32 s18, s18, s27
	s_addc_u32 s19, s19, 0
	s_sub_u32 s18, s18, 0x80
	s_subb_u32 s19, s19, 0
	s_add_u32 s6, s18, 0x1000
	s_addc_u32 s7, s19, 0
	s_sub_i32 s66, 0x1002, s39
	s_waitcnt vmcnt(0) lgkmcnt(0)
	v_mov_b32_dpp v210, v98 row_ror:1 row_mask:0xf bank_mask:0xf
	v_mov_b32_dpp v212, v98 row_ror:2 row_mask:0xf bank_mask:0xf
	v_mov_b32_dpp v211, v99 row_ror:1 row_mask:0xf bank_mask:0xf
	v_mov_b32_dpp v213, v99 row_ror:2 row_mask:0xf bank_mask:0xf
	s_nop 1
	v_mov_b32_dpp v210, v114 row_shr:1 row_mask:0xf bank_mask:0xf
	v_mov_b32_dpp v212, v114 row_shr:2 row_mask:0xf bank_mask:0xf
	v_mov_b32_dpp v211, v115 row_shr:1 row_mask:0xf bank_mask:0xf
	v_mov_b32_dpp v213, v115 row_shr:2 row_mask:0xf bank_mask:0xf
	s_nop 1
	v_pk_mul_f32 v[210:211], v[186:187], v[210:211]
	v_pk_fma_f32 v[214:215], v[194:195], v[114:115], v[210:211]
	v_pk_fma_f32 v[214:215], v[178:179], v[212:213], v[214:215]
	v_pk_add_f32 v[214:215], v[202:203], v[214:215]
	v_mul_f32_e32 v216, 0x3d372713, v214
	v_mul_f32_e32 v216, v214, v216
	v_fma_f32 v216, v214, v216, v214
	v_mul_f32_e32 v216, 0x3f4c422a, v216
	v_mul_f32_e32 v216, 0xc038aa3b, v216
	v_exp_f32_e32 v216, v216
	s_nop 0
	v_add_f32_e32 v216, 1.0, v216
	v_rcp_f32_e32 v216, v216
	s_nop 0
	v_mul_f32_e32 v214, v214, v216
	v_mul_f32_e32 v214, v122, v214
	v_mul_f32_e32 v216, 0x3d372713, v215
	v_mul_f32_e32 v216, v215, v216
	v_fma_f32 v216, v215, v216, v215
	v_mul_f32_e32 v216, 0x3f4c422a, v216
	v_mul_f32_e32 v216, 0xc038aa3b, v216
	v_exp_f32_e32 v216, v216
	s_nop 0
	v_add_f32_e32 v216, 1.0, v216
	v_rcp_f32_e32 v216, v216
	s_nop 0
	v_mul_f32_e32 v215, v215, v216
	v_mul_f32_e32 v215, v123, v215
	v_cvt_pk_bf16_f32 v122, v214, v215
	v_mov_b32_dpp v210, v100 row_ror:1 row_mask:0xf bank_mask:0xf
	v_mov_b32_dpp v212, v100 row_ror:2 row_mask:0xf bank_mask:0xf
	v_mov_b32_dpp v211, v101 row_ror:1 row_mask:0xf bank_mask:0xf
	v_mov_b32_dpp v213, v101 row_ror:2 row_mask:0xf bank_mask:0xf
	s_nop 1
	v_mov_b32_dpp v210, v116 row_shr:1 row_mask:0xf bank_mask:0xf
	v_mov_b32_dpp v212, v116 row_shr:2 row_mask:0xf bank_mask:0xf
	v_mov_b32_dpp v211, v117 row_shr:1 row_mask:0xf bank_mask:0xf
	v_mov_b32_dpp v213, v117 row_shr:2 row_mask:0xf bank_mask:0xf
	s_nop 1
	v_pk_mul_f32 v[210:211], v[188:189], v[210:211]
	v_pk_fma_f32 v[214:215], v[196:197], v[116:117], v[210:211]
	v_pk_fma_f32 v[214:215], v[180:181], v[212:213], v[214:215]
	v_pk_add_f32 v[214:215], v[204:205], v[214:215]
	v_mul_f32_e32 v216, 0x3d372713, v214
	v_mul_f32_e32 v216, v214, v216
	v_fma_f32 v216, v214, v216, v214
	v_mul_f32_e32 v216, 0x3f4c422a, v216
	v_mul_f32_e32 v216, 0xc038aa3b, v216
	v_exp_f32_e32 v216, v216
	s_nop 0
	v_add_f32_e32 v216, 1.0, v216
	v_rcp_f32_e32 v216, v216
	s_nop 0
	v_mul_f32_e32 v214, v214, v216
	v_mul_f32_e32 v214, v124, v214
	v_mul_f32_e32 v216, 0x3d372713, v215
	v_mul_f32_e32 v216, v215, v216
	v_fma_f32 v216, v215, v216, v215
	v_mul_f32_e32 v216, 0x3f4c422a, v216
	v_mul_f32_e32 v216, 0xc038aa3b, v216
	v_exp_f32_e32 v216, v216
	s_nop 0
	v_add_f32_e32 v216, 1.0, v216
	v_rcp_f32_e32 v216, v216
	s_nop 0
	v_mul_f32_e32 v215, v215, v216
	v_mul_f32_e32 v215, v125, v215
	v_cvt_pk_bf16_f32 v123, v214, v215
	v_mov_b32_dpp v210, v102 row_ror:1 row_mask:0xf bank_mask:0xf
	v_mov_b32_dpp v212, v102 row_ror:2 row_mask:0xf bank_mask:0xf
	v_mov_b32_dpp v211, v103 row_ror:1 row_mask:0xf bank_mask:0xf
	v_mov_b32_dpp v213, v103 row_ror:2 row_mask:0xf bank_mask:0xf
	s_nop 1
	v_mov_b32_dpp v210, v118 row_shr:1 row_mask:0xf bank_mask:0xf
	v_mov_b32_dpp v212, v118 row_shr:2 row_mask:0xf bank_mask:0xf
	v_mov_b32_dpp v211, v119 row_shr:1 row_mask:0xf bank_mask:0xf
	v_mov_b32_dpp v213, v119 row_shr:2 row_mask:0xf bank_mask:0xf
	s_nop 1
	v_pk_mul_f32 v[210:211], v[190:191], v[210:211]
	v_pk_fma_f32 v[214:215], v[198:199], v[118:119], v[210:211]
	v_pk_fma_f32 v[214:215], v[182:183], v[212:213], v[214:215]
	v_pk_add_f32 v[214:215], v[206:207], v[214:215]
	v_mul_f32_e32 v216, 0x3d372713, v214
	v_mul_f32_e32 v216, v214, v216
	v_fma_f32 v216, v214, v216, v214
	v_mul_f32_e32 v216, 0x3f4c422a, v216
	v_mul_f32_e32 v216, 0xc038aa3b, v216
	v_exp_f32_e32 v216, v216
	s_nop 0
	v_add_f32_e32 v216, 1.0, v216
	v_rcp_f32_e32 v216, v216
	s_nop 0
	v_mul_f32_e32 v214, v214, v216
	v_mul_f32_e32 v214, v126, v214
	v_mul_f32_e32 v216, 0x3d372713, v215
	v_mul_f32_e32 v216, v215, v216
	v_fma_f32 v216, v215, v216, v215
	v_mul_f32_e32 v216, 0x3f4c422a, v216
	v_mul_f32_e32 v216, 0xc038aa3b, v216
	v_exp_f32_e32 v216, v216
	s_nop 0
	v_add_f32_e32 v216, 1.0, v216
	v_rcp_f32_e32 v216, v216
	s_nop 0
	v_mul_f32_e32 v215, v215, v216
	v_mul_f32_e32 v215, v127, v215
	v_cvt_pk_bf16_f32 v124, v214, v215
	v_mov_b32_dpp v210, v104 row_ror:1 row_mask:0xf bank_mask:0xf
	v_mov_b32_dpp v212, v104 row_ror:2 row_mask:0xf bank_mask:0xf
	v_mov_b32_dpp v211, v105 row_ror:1 row_mask:0xf bank_mask:0xf
	v_mov_b32_dpp v213, v105 row_ror:2 row_mask:0xf bank_mask:0xf
	s_nop 1
	v_mov_b32_dpp v210, v120 row_shr:1 row_mask:0xf bank_mask:0xf
	v_mov_b32_dpp v212, v120 row_shr:2 row_mask:0xf bank_mask:0xf
	v_mov_b32_dpp v211, v121 row_shr:1 row_mask:0xf bank_mask:0xf
	v_mov_b32_dpp v213, v121 row_shr:2 row_mask:0xf bank_mask:0xf
	s_nop 1
	v_pk_mul_f32 v[210:211], v[192:193], v[210:211]
	v_pk_fma_f32 v[214:215], v[200:201], v[120:121], v[210:211]
	v_pk_fma_f32 v[214:215], v[184:185], v[212:213], v[214:215]
	v_pk_add_f32 v[214:215], v[208:209], v[214:215]
	v_mul_f32_e32 v216, 0x3d372713, v214
	v_mul_f32_e32 v216, v214, v216
	v_fma_f32 v216, v214, v216, v214
	v_mul_f32_e32 v216, 0x3f4c422a, v216
	v_mul_f32_e32 v216, 0xc038aa3b, v216
	v_exp_f32_e32 v216, v216
	s_nop 0
	v_add_f32_e32 v216, 1.0, v216
	v_rcp_f32_e32 v216, v216
	s_nop 0
	v_mul_f32_e32 v214, v214, v216
	v_mul_f32_e32 v214, v128, v214
	v_mul_f32_e32 v216, 0x3d372713, v215
	v_mul_f32_e32 v216, v215, v216
	v_fma_f32 v216, v215, v216, v215
	v_mul_f32_e32 v216, 0x3f4c422a, v216
	v_mul_f32_e32 v216, 0xc038aa3b, v216
	v_exp_f32_e32 v216, v216
	s_nop 0
	v_add_f32_e32 v216, 1.0, v216
	v_rcp_f32_e32 v216, v216
	s_nop 0
	v_mul_f32_e32 v215, v215, v216
	v_mul_f32_e32 v215, v129, v215
	v_cvt_pk_bf16_f32 v125, v214, v215
	s_add_i32 s26, s66, -112
	v_cmp_gt_i32_e64 s[24:25], s26, v227
	s_nop 1
	s_and_saveexec_b64 s[26:27], s[24:25]
	global_store_dwordx4 v242, v[122:125], s[6:7] offset:3072
	s_mov_b64 exec, s[26:27]
	s_nop 4
	v_mov_b32_dpp v210, v82 row_ror:1 row_mask:0xf bank_mask:0xf
	v_mov_b32_dpp v212, v82 row_ror:2 row_mask:0xf bank_mask:0xf
	v_mov_b32_dpp v211, v83 row_ror:1 row_mask:0xf bank_mask:0xf
	v_mov_b32_dpp v213, v83 row_ror:2 row_mask:0xf bank_mask:0xf
	s_nop 1
	v_mov_b32_dpp v210, v98 row_shr:1 row_mask:0xf bank_mask:0xf
	v_mov_b32_dpp v212, v98 row_shr:2 row_mask:0xf bank_mask:0xf
	v_mov_b32_dpp v211, v99 row_shr:1 row_mask:0xf bank_mask:0xf
	v_mov_b32_dpp v213, v99 row_shr:2 row_mask:0xf bank_mask:0xf
	s_nop 1
	v_pk_mul_f32 v[210:211], v[186:187], v[210:211]
	v_pk_fma_f32 v[214:215], v[194:195], v[98:99], v[210:211]
	v_pk_fma_f32 v[214:215], v[178:179], v[212:213], v[214:215]
	v_pk_add_f32 v[214:215], v[202:203], v[214:215]
	v_mul_f32_e32 v216, 0x3d372713, v214
	v_mul_f32_e32 v216, v214, v216
	v_fma_f32 v216, v214, v216, v214
	v_mul_f32_e32 v216, 0x3f4c422a, v216
	v_mul_f32_e32 v216, 0xc038aa3b, v216
	v_exp_f32_e32 v216, v216
	s_nop 0
	v_add_f32_e32 v216, 1.0, v216
	v_rcp_f32_e32 v216, v216
	s_nop 0
	v_mul_f32_e32 v214, v214, v216
	v_mul_f32_e32 v214, v106, v214
	v_mul_f32_e32 v216, 0x3d372713, v215
	v_mul_f32_e32 v216, v215, v216
	v_fma_f32 v216, v215, v216, v215
	v_mul_f32_e32 v216, 0x3f4c422a, v216
	v_mul_f32_e32 v216, 0xc038aa3b, v216
	v_exp_f32_e32 v216, v216
	s_nop 0
	v_add_f32_e32 v216, 1.0, v216
	v_rcp_f32_e32 v216, v216
	s_nop 0
	v_mul_f32_e32 v215, v215, v216
	v_mul_f32_e32 v215, v107, v215
	v_cvt_pk_bf16_f32 v106, v214, v215
	v_mov_b32_dpp v210, v84 row_ror:1 row_mask:0xf bank_mask:0xf
	v_mov_b32_dpp v212, v84 row_ror:2 row_mask:0xf bank_mask:0xf
	v_mov_b32_dpp v211, v85 row_ror:1 row_mask:0xf bank_mask:0xf
	v_mov_b32_dpp v213, v85 row_ror:2 row_mask:0xf bank_mask:0xf
	s_nop 1
	v_mov_b32_dpp v210, v100 row_shr:1 row_mask:0xf bank_mask:0xf
	v_mov_b32_dpp v212, v100 row_shr:2 row_mask:0xf bank_mask:0xf
	v_mov_b32_dpp v211, v101 row_shr:1 row_mask:0xf bank_mask:0xf
	v_mov_b32_dpp v213, v101 row_shr:2 row_mask:0xf bank_mask:0xf
	s_nop 1
	v_pk_mul_f32 v[210:211], v[188:189], v[210:211]
	v_pk_fma_f32 v[214:215], v[196:197], v[100:101], v[210:211]
	v_pk_fma_f32 v[214:215], v[180:181], v[212:213], v[214:215]
	v_pk_add_f32 v[214:215], v[204:205], v[214:215]
	v_mul_f32_e32 v216, 0x3d372713, v214
	v_mul_f32_e32 v216, v214, v216
	v_fma_f32 v216, v214, v216, v214
	v_mul_f32_e32 v216, 0x3f4c422a, v216
	v_mul_f32_e32 v216, 0xc038aa3b, v216
	v_exp_f32_e32 v216, v216
	s_nop 0
	v_add_f32_e32 v216, 1.0, v216
	v_rcp_f32_e32 v216, v216
	s_nop 0
	v_mul_f32_e32 v214, v214, v216
	v_mul_f32_e32 v214, v108, v214
	v_mul_f32_e32 v216, 0x3d372713, v215
	v_mul_f32_e32 v216, v215, v216
	v_fma_f32 v216, v215, v216, v215
	v_mul_f32_e32 v216, 0x3f4c422a, v216
	v_mul_f32_e32 v216, 0xc038aa3b, v216
	v_exp_f32_e32 v216, v216
	s_nop 0
	v_add_f32_e32 v216, 1.0, v216
	v_rcp_f32_e32 v216, v216
	s_nop 0
	v_mul_f32_e32 v215, v215, v216
	v_mul_f32_e32 v215, v109, v215
	v_cvt_pk_bf16_f32 v107, v214, v215
	v_mov_b32_dpp v210, v86 row_ror:1 row_mask:0xf bank_mask:0xf
	v_mov_b32_dpp v212, v86 row_ror:2 row_mask:0xf bank_mask:0xf
	v_mov_b32_dpp v211, v87 row_ror:1 row_mask:0xf bank_mask:0xf
	v_mov_b32_dpp v213, v87 row_ror:2 row_mask:0xf bank_mask:0xf
	s_nop 1
	v_mov_b32_dpp v210, v102 row_shr:1 row_mask:0xf bank_mask:0xf
	v_mov_b32_dpp v212, v102 row_shr:2 row_mask:0xf bank_mask:0xf
	v_mov_b32_dpp v211, v103 row_shr:1 row_mask:0xf bank_mask:0xf
	v_mov_b32_dpp v213, v103 row_shr:2 row_mask:0xf bank_mask:0xf
	s_nop 1
	v_pk_mul_f32 v[210:211], v[190:191], v[210:211]
	v_pk_fma_f32 v[214:215], v[198:199], v[102:103], v[210:211]
	v_pk_fma_f32 v[214:215], v[182:183], v[212:213], v[214:215]
	v_pk_add_f32 v[214:215], v[206:207], v[214:215]
	v_mul_f32_e32 v216, 0x3d372713, v214
	v_mul_f32_e32 v216, v214, v216
	v_fma_f32 v216, v214, v216, v214
	v_mul_f32_e32 v216, 0x3f4c422a, v216
	v_mul_f32_e32 v216, 0xc038aa3b, v216
	v_exp_f32_e32 v216, v216
	s_nop 0
	v_add_f32_e32 v216, 1.0, v216
	v_rcp_f32_e32 v216, v216
	s_nop 0
	v_mul_f32_e32 v214, v214, v216
	v_mul_f32_e32 v214, v110, v214
	v_mul_f32_e32 v216, 0x3d372713, v215
	v_mul_f32_e32 v216, v215, v216
	v_fma_f32 v216, v215, v216, v215
	v_mul_f32_e32 v216, 0x3f4c422a, v216
	v_mul_f32_e32 v216, 0xc038aa3b, v216
	v_exp_f32_e32 v216, v216
	s_nop 0
	v_add_f32_e32 v216, 1.0, v216
	v_rcp_f32_e32 v216, v216
	s_nop 0
	v_mul_f32_e32 v215, v215, v216
	v_mul_f32_e32 v215, v111, v215
	v_cvt_pk_bf16_f32 v108, v214, v215
	v_mov_b32_dpp v210, v88 row_ror:1 row_mask:0xf bank_mask:0xf
	v_mov_b32_dpp v212, v88 row_ror:2 row_mask:0xf bank_mask:0xf
	v_mov_b32_dpp v211, v89 row_ror:1 row_mask:0xf bank_mask:0xf
	v_mov_b32_dpp v213, v89 row_ror:2 row_mask:0xf bank_mask:0xf
	s_nop 1
	v_mov_b32_dpp v210, v104 row_shr:1 row_mask:0xf bank_mask:0xf
	v_mov_b32_dpp v212, v104 row_shr:2 row_mask:0xf bank_mask:0xf
	v_mov_b32_dpp v211, v105 row_shr:1 row_mask:0xf bank_mask:0xf
	v_mov_b32_dpp v213, v105 row_shr:2 row_mask:0xf bank_mask:0xf
	s_nop 1
	v_pk_mul_f32 v[210:211], v[192:193], v[210:211]
	v_pk_fma_f32 v[214:215], v[200:201], v[104:105], v[210:211]
	v_pk_fma_f32 v[214:215], v[184:185], v[212:213], v[214:215]
	v_pk_add_f32 v[214:215], v[208:209], v[214:215]
	v_mul_f32_e32 v216, 0x3d372713, v214
	v_mul_f32_e32 v216, v214, v216
	v_fma_f32 v216, v214, v216, v214
	v_mul_f32_e32 v216, 0x3f4c422a, v216
	v_mul_f32_e32 v216, 0xc038aa3b, v216
	v_exp_f32_e32 v216, v216
	s_nop 0
	v_add_f32_e32 v216, 1.0, v216
	v_rcp_f32_e32 v216, v216
	s_nop 0
	v_mul_f32_e32 v214, v214, v216
	v_mul_f32_e32 v214, v112, v214
	v_mul_f32_e32 v216, 0x3d372713, v215
	v_mul_f32_e32 v216, v215, v216
	v_fma_f32 v216, v215, v216, v215
	v_mul_f32_e32 v216, 0x3f4c422a, v216
	v_mul_f32_e32 v216, 0xc038aa3b, v216
	v_exp_f32_e32 v216, v216
	s_nop 0
	v_add_f32_e32 v216, 1.0, v216
	v_rcp_f32_e32 v216, v216
	s_nop 0
	v_mul_f32_e32 v215, v215, v216
	v_mul_f32_e32 v215, v113, v215
	v_cvt_pk_bf16_f32 v109, v214, v215
	s_add_i32 s26, s66, -96
	v_cmp_gt_i32_e64 s[24:25], s26, v227
	s_nop 1
	s_and_saveexec_b64 s[26:27], s[24:25]
	global_store_dwordx4 v242, v[106:109], s[6:7] offset:2048
	s_mov_b64 exec, s[26:27]
	s_nop 4
	v_mov_b32_dpp v210, v66 row_ror:1 row_mask:0xf bank_mask:0xf
	v_mov_b32_dpp v212, v66 row_ror:2 row_mask:0xf bank_mask:0xf
	v_mov_b32_dpp v211, v67 row_ror:1 row_mask:0xf bank_mask:0xf
	v_mov_b32_dpp v213, v67 row_ror:2 row_mask:0xf bank_mask:0xf
	s_nop 1
	v_mov_b32_dpp v210, v82 row_shr:1 row_mask:0xf bank_mask:0xf
	v_mov_b32_dpp v212, v82 row_shr:2 row_mask:0xf bank_mask:0xf
	v_mov_b32_dpp v211, v83 row_shr:1 row_mask:0xf bank_mask:0xf
	v_mov_b32_dpp v213, v83 row_shr:2 row_mask:0xf bank_mask:0xf
	s_nop 1
	v_pk_mul_f32 v[210:211], v[186:187], v[210:211]
	v_pk_fma_f32 v[214:215], v[194:195], v[82:83], v[210:211]
	v_pk_fma_f32 v[214:215], v[178:179], v[212:213], v[214:215]
	v_pk_add_f32 v[214:215], v[202:203], v[214:215]
	v_mul_f32_e32 v216, 0x3d372713, v214
	v_mul_f32_e32 v216, v214, v216
	v_fma_f32 v216, v214, v216, v214
	v_mul_f32_e32 v216, 0x3f4c422a, v216
	v_mul_f32_e32 v216, 0xc038aa3b, v216
	v_exp_f32_e32 v216, v216
	s_nop 0
	v_add_f32_e32 v216, 1.0, v216
	v_rcp_f32_e32 v216, v216
	s_nop 0
	v_mul_f32_e32 v214, v214, v216
	v_mul_f32_e32 v214, v90, v214
	v_mul_f32_e32 v216, 0x3d372713, v215
	v_mul_f32_e32 v216, v215, v216
	v_fma_f32 v216, v215, v216, v215
	v_mul_f32_e32 v216, 0x3f4c422a, v216
	v_mul_f32_e32 v216, 0xc038aa3b, v216
	v_exp_f32_e32 v216, v216
	s_nop 0
	v_add_f32_e32 v216, 1.0, v216
	v_rcp_f32_e32 v216, v216
	s_nop 0
	v_mul_f32_e32 v215, v215, v216
	v_mul_f32_e32 v215, v91, v215
	v_cvt_pk_bf16_f32 v90, v214, v215
	v_mov_b32_dpp v210, v68 row_ror:1 row_mask:0xf bank_mask:0xf
	v_mov_b32_dpp v212, v68 row_ror:2 row_mask:0xf bank_mask:0xf
	v_mov_b32_dpp v211, v69 row_ror:1 row_mask:0xf bank_mask:0xf
	v_mov_b32_dpp v213, v69 row_ror:2 row_mask:0xf bank_mask:0xf
	s_nop 1
	v_mov_b32_dpp v210, v84 row_shr:1 row_mask:0xf bank_mask:0xf
	v_mov_b32_dpp v212, v84 row_shr:2 row_mask:0xf bank_mask:0xf
	v_mov_b32_dpp v211, v85 row_shr:1 row_mask:0xf bank_mask:0xf
	v_mov_b32_dpp v213, v85 row_shr:2 row_mask:0xf bank_mask:0xf
	s_nop 1
	v_pk_mul_f32 v[210:211], v[188:189], v[210:211]
	v_pk_fma_f32 v[214:215], v[196:197], v[84:85], v[210:211]
	v_pk_fma_f32 v[214:215], v[180:181], v[212:213], v[214:215]
	v_pk_add_f32 v[214:215], v[204:205], v[214:215]
	v_mul_f32_e32 v216, 0x3d372713, v214
	v_mul_f32_e32 v216, v214, v216
	v_fma_f32 v216, v214, v216, v214
	v_mul_f32_e32 v216, 0x3f4c422a, v216
	v_mul_f32_e32 v216, 0xc038aa3b, v216
	v_exp_f32_e32 v216, v216
	s_nop 0
	v_add_f32_e32 v216, 1.0, v216
	v_rcp_f32_e32 v216, v216
	s_nop 0
	v_mul_f32_e32 v214, v214, v216
	v_mul_f32_e32 v214, v92, v214
	v_mul_f32_e32 v216, 0x3d372713, v215
	v_mul_f32_e32 v216, v215, v216
	v_fma_f32 v216, v215, v216, v215
	v_mul_f32_e32 v216, 0x3f4c422a, v216
	v_mul_f32_e32 v216, 0xc038aa3b, v216
	v_exp_f32_e32 v216, v216
	s_nop 0
	v_add_f32_e32 v216, 1.0, v216
	v_rcp_f32_e32 v216, v216
	s_nop 0
	v_mul_f32_e32 v215, v215, v216
	v_mul_f32_e32 v215, v93, v215
	v_cvt_pk_bf16_f32 v91, v214, v215
	v_mov_b32_dpp v210, v70 row_ror:1 row_mask:0xf bank_mask:0xf
	v_mov_b32_dpp v212, v70 row_ror:2 row_mask:0xf bank_mask:0xf
	v_mov_b32_dpp v211, v71 row_ror:1 row_mask:0xf bank_mask:0xf
	v_mov_b32_dpp v213, v71 row_ror:2 row_mask:0xf bank_mask:0xf
	s_nop 1
	v_mov_b32_dpp v210, v86 row_shr:1 row_mask:0xf bank_mask:0xf
	v_mov_b32_dpp v212, v86 row_shr:2 row_mask:0xf bank_mask:0xf
	v_mov_b32_dpp v211, v87 row_shr:1 row_mask:0xf bank_mask:0xf
	v_mov_b32_dpp v213, v87 row_shr:2 row_mask:0xf bank_mask:0xf
	s_nop 1
	v_pk_mul_f32 v[210:211], v[190:191], v[210:211]
	v_pk_fma_f32 v[214:215], v[198:199], v[86:87], v[210:211]
	v_pk_fma_f32 v[214:215], v[182:183], v[212:213], v[214:215]
	v_pk_add_f32 v[214:215], v[206:207], v[214:215]
	v_mul_f32_e32 v216, 0x3d372713, v214
	v_mul_f32_e32 v216, v214, v216
	v_fma_f32 v216, v214, v216, v214
	v_mul_f32_e32 v216, 0x3f4c422a, v216
	v_mul_f32_e32 v216, 0xc038aa3b, v216
	v_exp_f32_e32 v216, v216
	s_nop 0
	v_add_f32_e32 v216, 1.0, v216
	v_rcp_f32_e32 v216, v216
	s_nop 0
	v_mul_f32_e32 v214, v214, v216
	v_mul_f32_e32 v214, v94, v214
	v_mul_f32_e32 v216, 0x3d372713, v215
	v_mul_f32_e32 v216, v215, v216
	v_fma_f32 v216, v215, v216, v215
	v_mul_f32_e32 v216, 0x3f4c422a, v216
	v_mul_f32_e32 v216, 0xc038aa3b, v216
	v_exp_f32_e32 v216, v216
	s_nop 0
	v_add_f32_e32 v216, 1.0, v216
	v_rcp_f32_e32 v216, v216
	s_nop 0
	v_mul_f32_e32 v215, v215, v216
	v_mul_f32_e32 v215, v95, v215
	v_cvt_pk_bf16_f32 v92, v214, v215
	v_mov_b32_dpp v210, v72 row_ror:1 row_mask:0xf bank_mask:0xf
	v_mov_b32_dpp v212, v72 row_ror:2 row_mask:0xf bank_mask:0xf
	v_mov_b32_dpp v211, v73 row_ror:1 row_mask:0xf bank_mask:0xf
	v_mov_b32_dpp v213, v73 row_ror:2 row_mask:0xf bank_mask:0xf
	s_nop 1
	v_mov_b32_dpp v210, v88 row_shr:1 row_mask:0xf bank_mask:0xf
	v_mov_b32_dpp v212, v88 row_shr:2 row_mask:0xf bank_mask:0xf
	v_mov_b32_dpp v211, v89 row_shr:1 row_mask:0xf bank_mask:0xf
	v_mov_b32_dpp v213, v89 row_shr:2 row_mask:0xf bank_mask:0xf
	s_nop 1
	v_pk_mul_f32 v[210:211], v[192:193], v[210:211]
	v_pk_fma_f32 v[214:215], v[200:201], v[88:89], v[210:211]
	v_pk_fma_f32 v[214:215], v[184:185], v[212:213], v[214:215]
	v_pk_add_f32 v[214:215], v[208:209], v[214:215]
	v_mul_f32_e32 v216, 0x3d372713, v214
	v_mul_f32_e32 v216, v214, v216
	v_fma_f32 v216, v214, v216, v214
	v_mul_f32_e32 v216, 0x3f4c422a, v216
	v_mul_f32_e32 v216, 0xc038aa3b, v216
	v_exp_f32_e32 v216, v216
	s_nop 0
	v_add_f32_e32 v216, 1.0, v216
	v_rcp_f32_e32 v216, v216
	s_nop 0
	v_mul_f32_e32 v214, v214, v216
	v_mul_f32_e32 v214, v96, v214
	v_mul_f32_e32 v216, 0x3d372713, v215
	v_mul_f32_e32 v216, v215, v216
	v_fma_f32 v216, v215, v216, v215
	v_mul_f32_e32 v216, 0x3f4c422a, v216
	v_mul_f32_e32 v216, 0xc038aa3b, v216
	v_exp_f32_e32 v216, v216
	s_nop 0
	v_add_f32_e32 v216, 1.0, v216
	v_rcp_f32_e32 v216, v216
	s_nop 0
	v_mul_f32_e32 v215, v215, v216
	v_mul_f32_e32 v215, v97, v215
	v_cvt_pk_bf16_f32 v93, v214, v215
	s_add_i32 s26, s66, -80
	v_cmp_gt_i32_e64 s[24:25], s26, v227
	s_nop 1
	s_and_saveexec_b64 s[26:27], s[24:25]
	global_store_dwordx4 v242, v[90:93], s[6:7] offset:1024
	s_mov_b64 exec, s[26:27]
	s_nop 4
	v_mov_b32_dpp v210, v50 row_ror:1 row_mask:0xf bank_mask:0xf
	v_mov_b32_dpp v212, v50 row_ror:2 row_mask:0xf bank_mask:0xf
	v_mov_b32_dpp v211, v51 row_ror:1 row_mask:0xf bank_mask:0xf
	v_mov_b32_dpp v213, v51 row_ror:2 row_mask:0xf bank_mask:0xf
	s_nop 1
	v_mov_b32_dpp v210, v66 row_shr:1 row_mask:0xf bank_mask:0xf
	v_mov_b32_dpp v212, v66 row_shr:2 row_mask:0xf bank_mask:0xf
	v_mov_b32_dpp v211, v67 row_shr:1 row_mask:0xf bank_mask:0xf
	v_mov_b32_dpp v213, v67 row_shr:2 row_mask:0xf bank_mask:0xf
	s_nop 1
	v_pk_mul_f32 v[210:211], v[186:187], v[210:211]
	v_pk_fma_f32 v[214:215], v[194:195], v[66:67], v[210:211]
	v_pk_fma_f32 v[214:215], v[178:179], v[212:213], v[214:215]
	v_pk_add_f32 v[214:215], v[202:203], v[214:215]
	v_mul_f32_e32 v216, 0x3d372713, v214
	v_mul_f32_e32 v216, v214, v216
	v_fma_f32 v216, v214, v216, v214
	v_mul_f32_e32 v216, 0x3f4c422a, v216
	v_mul_f32_e32 v216, 0xc038aa3b, v216
	v_exp_f32_e32 v216, v216
	s_nop 0
	v_add_f32_e32 v216, 1.0, v216
	v_rcp_f32_e32 v216, v216
	s_nop 0
	v_mul_f32_e32 v214, v214, v216
	v_mul_f32_e32 v214, v74, v214
	v_mul_f32_e32 v216, 0x3d372713, v215
	v_mul_f32_e32 v216, v215, v216
	v_fma_f32 v216, v215, v216, v215
	v_mul_f32_e32 v216, 0x3f4c422a, v216
	v_mul_f32_e32 v216, 0xc038aa3b, v216
	v_exp_f32_e32 v216, v216
	s_nop 0
	v_add_f32_e32 v216, 1.0, v216
	v_rcp_f32_e32 v216, v216
	s_nop 0
	v_mul_f32_e32 v215, v215, v216
	v_mul_f32_e32 v215, v75, v215
	v_cvt_pk_bf16_f32 v74, v214, v215
	v_mov_b32_dpp v210, v52 row_ror:1 row_mask:0xf bank_mask:0xf
	v_mov_b32_dpp v212, v52 row_ror:2 row_mask:0xf bank_mask:0xf
	v_mov_b32_dpp v211, v53 row_ror:1 row_mask:0xf bank_mask:0xf
	v_mov_b32_dpp v213, v53 row_ror:2 row_mask:0xf bank_mask:0xf
	s_nop 1
	v_mov_b32_dpp v210, v68 row_shr:1 row_mask:0xf bank_mask:0xf
	v_mov_b32_dpp v212, v68 row_shr:2 row_mask:0xf bank_mask:0xf
	v_mov_b32_dpp v211, v69 row_shr:1 row_mask:0xf bank_mask:0xf
	v_mov_b32_dpp v213, v69 row_shr:2 row_mask:0xf bank_mask:0xf
	s_nop 1
	v_pk_mul_f32 v[210:211], v[188:189], v[210:211]
	v_pk_fma_f32 v[214:215], v[196:197], v[68:69], v[210:211]
	v_pk_fma_f32 v[214:215], v[180:181], v[212:213], v[214:215]
	v_pk_add_f32 v[214:215], v[204:205], v[214:215]
	v_mul_f32_e32 v216, 0x3d372713, v214
	v_mul_f32_e32 v216, v214, v216
	v_fma_f32 v216, v214, v216, v214
	v_mul_f32_e32 v216, 0x3f4c422a, v216
	v_mul_f32_e32 v216, 0xc038aa3b, v216
	v_exp_f32_e32 v216, v216
	s_nop 0
	v_add_f32_e32 v216, 1.0, v216
	v_rcp_f32_e32 v216, v216
	s_nop 0
	v_mul_f32_e32 v214, v214, v216
	v_mul_f32_e32 v214, v76, v214
	v_mul_f32_e32 v216, 0x3d372713, v215
	v_mul_f32_e32 v216, v215, v216
	v_fma_f32 v216, v215, v216, v215
	v_mul_f32_e32 v216, 0x3f4c422a, v216
	v_mul_f32_e32 v216, 0xc038aa3b, v216
	v_exp_f32_e32 v216, v216
	s_nop 0
	v_add_f32_e32 v216, 1.0, v216
	v_rcp_f32_e32 v216, v216
	s_nop 0
	v_mul_f32_e32 v215, v215, v216
	v_mul_f32_e32 v215, v77, v215
	v_cvt_pk_bf16_f32 v75, v214, v215
	v_mov_b32_dpp v210, v54 row_ror:1 row_mask:0xf bank_mask:0xf
	v_mov_b32_dpp v212, v54 row_ror:2 row_mask:0xf bank_mask:0xf
	v_mov_b32_dpp v211, v55 row_ror:1 row_mask:0xf bank_mask:0xf
	v_mov_b32_dpp v213, v55 row_ror:2 row_mask:0xf bank_mask:0xf
	s_nop 1
	v_mov_b32_dpp v210, v70 row_shr:1 row_mask:0xf bank_mask:0xf
	v_mov_b32_dpp v212, v70 row_shr:2 row_mask:0xf bank_mask:0xf
	v_mov_b32_dpp v211, v71 row_shr:1 row_mask:0xf bank_mask:0xf
	v_mov_b32_dpp v213, v71 row_shr:2 row_mask:0xf bank_mask:0xf
	s_nop 1
	v_pk_mul_f32 v[210:211], v[190:191], v[210:211]
	v_pk_fma_f32 v[214:215], v[198:199], v[70:71], v[210:211]
	v_pk_fma_f32 v[214:215], v[182:183], v[212:213], v[214:215]
	v_pk_add_f32 v[214:215], v[206:207], v[214:215]
	v_mul_f32_e32 v216, 0x3d372713, v214
	v_mul_f32_e32 v216, v214, v216
	v_fma_f32 v216, v214, v216, v214
	v_mul_f32_e32 v216, 0x3f4c422a, v216
	v_mul_f32_e32 v216, 0xc038aa3b, v216
	v_exp_f32_e32 v216, v216
	s_nop 0
	v_add_f32_e32 v216, 1.0, v216
	v_rcp_f32_e32 v216, v216
	s_nop 0
	v_mul_f32_e32 v214, v214, v216
	v_mul_f32_e32 v214, v78, v214
	v_mul_f32_e32 v216, 0x3d372713, v215
	v_mul_f32_e32 v216, v215, v216
	v_fma_f32 v216, v215, v216, v215
	v_mul_f32_e32 v216, 0x3f4c422a, v216
	v_mul_f32_e32 v216, 0xc038aa3b, v216
	v_exp_f32_e32 v216, v216
	s_nop 0
	v_add_f32_e32 v216, 1.0, v216
	v_rcp_f32_e32 v216, v216
	s_nop 0
	v_mul_f32_e32 v215, v215, v216
	v_mul_f32_e32 v215, v79, v215
	v_cvt_pk_bf16_f32 v76, v214, v215
	v_mov_b32_dpp v210, v56 row_ror:1 row_mask:0xf bank_mask:0xf
	v_mov_b32_dpp v212, v56 row_ror:2 row_mask:0xf bank_mask:0xf
	v_mov_b32_dpp v211, v57 row_ror:1 row_mask:0xf bank_mask:0xf
	v_mov_b32_dpp v213, v57 row_ror:2 row_mask:0xf bank_mask:0xf
	s_nop 1
	v_mov_b32_dpp v210, v72 row_shr:1 row_mask:0xf bank_mask:0xf
	v_mov_b32_dpp v212, v72 row_shr:2 row_mask:0xf bank_mask:0xf
	v_mov_b32_dpp v211, v73 row_shr:1 row_mask:0xf bank_mask:0xf
	v_mov_b32_dpp v213, v73 row_shr:2 row_mask:0xf bank_mask:0xf
	s_nop 1
	v_pk_mul_f32 v[210:211], v[192:193], v[210:211]
	v_pk_fma_f32 v[214:215], v[200:201], v[72:73], v[210:211]
	v_pk_fma_f32 v[214:215], v[184:185], v[212:213], v[214:215]
	v_pk_add_f32 v[214:215], v[208:209], v[214:215]
	v_mul_f32_e32 v216, 0x3d372713, v214
	v_mul_f32_e32 v216, v214, v216
	v_fma_f32 v216, v214, v216, v214
	v_mul_f32_e32 v216, 0x3f4c422a, v216
	v_mul_f32_e32 v216, 0xc038aa3b, v216
	v_exp_f32_e32 v216, v216
	s_nop 0
	v_add_f32_e32 v216, 1.0, v216
	v_rcp_f32_e32 v216, v216
	s_nop 0
	v_mul_f32_e32 v214, v214, v216
	v_mul_f32_e32 v214, v80, v214
	v_mul_f32_e32 v216, 0x3d372713, v215
	v_mul_f32_e32 v216, v215, v216
	v_fma_f32 v216, v215, v216, v215
	v_mul_f32_e32 v216, 0x3f4c422a, v216
	v_mul_f32_e32 v216, 0xc038aa3b, v216
	v_exp_f32_e32 v216, v216
	s_nop 0
	v_add_f32_e32 v216, 1.0, v216
	v_rcp_f32_e32 v216, v216
	s_nop 0
	v_mul_f32_e32 v215, v215, v216
	v_mul_f32_e32 v215, v81, v215
	v_cvt_pk_bf16_f32 v77, v214, v215
	s_add_i32 s26, s66, -64
	v_cmp_gt_i32_e64 s[24:25], s26, v227
	s_nop 1
	s_and_saveexec_b64 s[26:27], s[24:25]
	global_store_dwordx4 v242, v[74:77], s[6:7]
	s_mov_b64 exec, s[26:27]
	s_nop 4
	v_mov_b32_dpp v210, v34 row_ror:1 row_mask:0xf bank_mask:0xf
	v_mov_b32_dpp v212, v34 row_ror:2 row_mask:0xf bank_mask:0xf
	v_mov_b32_dpp v211, v35 row_ror:1 row_mask:0xf bank_mask:0xf
	v_mov_b32_dpp v213, v35 row_ror:2 row_mask:0xf bank_mask:0xf
	s_nop 1
	v_mov_b32_dpp v210, v50 row_shr:1 row_mask:0xf bank_mask:0xf
	v_mov_b32_dpp v212, v50 row_shr:2 row_mask:0xf bank_mask:0xf
	v_mov_b32_dpp v211, v51 row_shr:1 row_mask:0xf bank_mask:0xf
	v_mov_b32_dpp v213, v51 row_shr:2 row_mask:0xf bank_mask:0xf
	s_nop 1
	v_pk_mul_f32 v[210:211], v[186:187], v[210:211]
	v_pk_fma_f32 v[214:215], v[194:195], v[50:51], v[210:211]
	v_pk_fma_f32 v[214:215], v[178:179], v[212:213], v[214:215]
	v_pk_add_f32 v[214:215], v[202:203], v[214:215]
	v_mul_f32_e32 v216, 0x3d372713, v214
	v_mul_f32_e32 v216, v214, v216
	v_fma_f32 v216, v214, v216, v214
	v_mul_f32_e32 v216, 0x3f4c422a, v216
	v_mul_f32_e32 v216, 0xc038aa3b, v216
	v_exp_f32_e32 v216, v216
	s_nop 0
	v_add_f32_e32 v216, 1.0, v216
	v_rcp_f32_e32 v216, v216
	s_nop 0
	v_mul_f32_e32 v214, v214, v216
	v_mul_f32_e32 v214, v58, v214
	v_mul_f32_e32 v216, 0x3d372713, v215
	v_mul_f32_e32 v216, v215, v216
	v_fma_f32 v216, v215, v216, v215
	v_mul_f32_e32 v216, 0x3f4c422a, v216
	v_mul_f32_e32 v216, 0xc038aa3b, v216
	v_exp_f32_e32 v216, v216
	s_nop 0
	v_add_f32_e32 v216, 1.0, v216
	v_rcp_f32_e32 v216, v216
	s_nop 0
	v_mul_f32_e32 v215, v215, v216
	v_mul_f32_e32 v215, v59, v215
	v_cvt_pk_bf16_f32 v58, v214, v215
	v_mov_b32_dpp v210, v36 row_ror:1 row_mask:0xf bank_mask:0xf
	v_mov_b32_dpp v212, v36 row_ror:2 row_mask:0xf bank_mask:0xf
	v_mov_b32_dpp v211, v37 row_ror:1 row_mask:0xf bank_mask:0xf
	v_mov_b32_dpp v213, v37 row_ror:2 row_mask:0xf bank_mask:0xf
	s_nop 1
	v_mov_b32_dpp v210, v52 row_shr:1 row_mask:0xf bank_mask:0xf
	v_mov_b32_dpp v212, v52 row_shr:2 row_mask:0xf bank_mask:0xf
	v_mov_b32_dpp v211, v53 row_shr:1 row_mask:0xf bank_mask:0xf
	v_mov_b32_dpp v213, v53 row_shr:2 row_mask:0xf bank_mask:0xf
	s_nop 1
	v_pk_mul_f32 v[210:211], v[188:189], v[210:211]
	v_pk_fma_f32 v[214:215], v[196:197], v[52:53], v[210:211]
	v_pk_fma_f32 v[214:215], v[180:181], v[212:213], v[214:215]
	v_pk_add_f32 v[214:215], v[204:205], v[214:215]
	v_mul_f32_e32 v216, 0x3d372713, v214
	v_mul_f32_e32 v216, v214, v216
	v_fma_f32 v216, v214, v216, v214
	v_mul_f32_e32 v216, 0x3f4c422a, v216
	v_mul_f32_e32 v216, 0xc038aa3b, v216
	v_exp_f32_e32 v216, v216
	s_nop 0
	v_add_f32_e32 v216, 1.0, v216
	v_rcp_f32_e32 v216, v216
	s_nop 0
	v_mul_f32_e32 v214, v214, v216
	v_mul_f32_e32 v214, v60, v214
	v_mul_f32_e32 v216, 0x3d372713, v215
	v_mul_f32_e32 v216, v215, v216
	v_fma_f32 v216, v215, v216, v215
	v_mul_f32_e32 v216, 0x3f4c422a, v216
	v_mul_f32_e32 v216, 0xc038aa3b, v216
	v_exp_f32_e32 v216, v216
	s_nop 0
	v_add_f32_e32 v216, 1.0, v216
	v_rcp_f32_e32 v216, v216
	s_nop 0
	v_mul_f32_e32 v215, v215, v216
	v_mul_f32_e32 v215, v61, v215
	v_cvt_pk_bf16_f32 v59, v214, v215
	v_mov_b32_dpp v210, v38 row_ror:1 row_mask:0xf bank_mask:0xf
	v_mov_b32_dpp v212, v38 row_ror:2 row_mask:0xf bank_mask:0xf
	v_mov_b32_dpp v211, v39 row_ror:1 row_mask:0xf bank_mask:0xf
	v_mov_b32_dpp v213, v39 row_ror:2 row_mask:0xf bank_mask:0xf
	s_nop 1
	v_mov_b32_dpp v210, v54 row_shr:1 row_mask:0xf bank_mask:0xf
	v_mov_b32_dpp v212, v54 row_shr:2 row_mask:0xf bank_mask:0xf
	v_mov_b32_dpp v211, v55 row_shr:1 row_mask:0xf bank_mask:0xf
	v_mov_b32_dpp v213, v55 row_shr:2 row_mask:0xf bank_mask:0xf
	s_nop 1
	v_pk_mul_f32 v[210:211], v[190:191], v[210:211]
	v_pk_fma_f32 v[214:215], v[198:199], v[54:55], v[210:211]
	v_pk_fma_f32 v[214:215], v[182:183], v[212:213], v[214:215]
	v_pk_add_f32 v[214:215], v[206:207], v[214:215]
	v_mul_f32_e32 v216, 0x3d372713, v214
	v_mul_f32_e32 v216, v214, v216
	v_fma_f32 v216, v214, v216, v214
	v_mul_f32_e32 v216, 0x3f4c422a, v216
	v_mul_f32_e32 v216, 0xc038aa3b, v216
	v_exp_f32_e32 v216, v216
	s_nop 0
	v_add_f32_e32 v216, 1.0, v216
	v_rcp_f32_e32 v216, v216
	s_nop 0
	v_mul_f32_e32 v214, v214, v216
	v_mul_f32_e32 v214, v62, v214
	v_mul_f32_e32 v216, 0x3d372713, v215
	v_mul_f32_e32 v216, v215, v216
	v_fma_f32 v216, v215, v216, v215
	v_mul_f32_e32 v216, 0x3f4c422a, v216
	v_mul_f32_e32 v216, 0xc038aa3b, v216
	v_exp_f32_e32 v216, v216
	s_nop 0
	v_add_f32_e32 v216, 1.0, v216
	v_rcp_f32_e32 v216, v216
	s_nop 0
	v_mul_f32_e32 v215, v215, v216
	v_mul_f32_e32 v215, v63, v215
	v_cvt_pk_bf16_f32 v60, v214, v215
	v_mov_b32_dpp v210, v40 row_ror:1 row_mask:0xf bank_mask:0xf
	v_mov_b32_dpp v212, v40 row_ror:2 row_mask:0xf bank_mask:0xf
	v_mov_b32_dpp v211, v41 row_ror:1 row_mask:0xf bank_mask:0xf
	v_mov_b32_dpp v213, v41 row_ror:2 row_mask:0xf bank_mask:0xf
	s_nop 1
	v_mov_b32_dpp v210, v56 row_shr:1 row_mask:0xf bank_mask:0xf
	v_mov_b32_dpp v212, v56 row_shr:2 row_mask:0xf bank_mask:0xf
	v_mov_b32_dpp v211, v57 row_shr:1 row_mask:0xf bank_mask:0xf
	v_mov_b32_dpp v213, v57 row_shr:2 row_mask:0xf bank_mask:0xf
	s_nop 1
	v_pk_mul_f32 v[210:211], v[192:193], v[210:211]
	v_pk_fma_f32 v[214:215], v[200:201], v[56:57], v[210:211]
	v_pk_fma_f32 v[214:215], v[184:185], v[212:213], v[214:215]
	v_pk_add_f32 v[214:215], v[208:209], v[214:215]
	v_mul_f32_e32 v216, 0x3d372713, v214
	v_mul_f32_e32 v216, v214, v216
	v_fma_f32 v216, v214, v216, v214
	v_mul_f32_e32 v216, 0x3f4c422a, v216
	v_mul_f32_e32 v216, 0xc038aa3b, v216
	v_exp_f32_e32 v216, v216
	s_nop 0
	v_add_f32_e32 v216, 1.0, v216
	v_rcp_f32_e32 v216, v216
	s_nop 0
	v_mul_f32_e32 v214, v214, v216
	v_mul_f32_e32 v214, v64, v214
	v_mul_f32_e32 v216, 0x3d372713, v215
	v_mul_f32_e32 v216, v215, v216
	v_fma_f32 v216, v215, v216, v215
	v_mul_f32_e32 v216, 0x3f4c422a, v216
	v_mul_f32_e32 v216, 0xc038aa3b, v216
	v_exp_f32_e32 v216, v216
	s_nop 0
	v_add_f32_e32 v216, 1.0, v216
	v_rcp_f32_e32 v216, v216
	s_nop 0
	v_mul_f32_e32 v215, v215, v216
	v_mul_f32_e32 v215, v65, v215
	v_cvt_pk_bf16_f32 v61, v214, v215
	s_add_i32 s26, s66, -48
	v_cmp_gt_i32_e64 s[24:25], s26, v227
	s_nop 1
	s_and_saveexec_b64 s[26:27], s[24:25]
	global_store_dwordx4 v242, v[58:61], s[18:19] offset:3072
	s_mov_b64 exec, s[26:27]
	s_nop 4
	v_mov_b32_dpp v210, v18 row_ror:1 row_mask:0xf bank_mask:0xf
	v_mov_b32_dpp v212, v18 row_ror:2 row_mask:0xf bank_mask:0xf
	v_mov_b32_dpp v211, v19 row_ror:1 row_mask:0xf bank_mask:0xf
	v_mov_b32_dpp v213, v19 row_ror:2 row_mask:0xf bank_mask:0xf
	s_nop 1
	v_mov_b32_dpp v210, v34 row_shr:1 row_mask:0xf bank_mask:0xf
	v_mov_b32_dpp v212, v34 row_shr:2 row_mask:0xf bank_mask:0xf
	v_mov_b32_dpp v211, v35 row_shr:1 row_mask:0xf bank_mask:0xf
	v_mov_b32_dpp v213, v35 row_shr:2 row_mask:0xf bank_mask:0xf
	s_nop 1
	v_pk_mul_f32 v[210:211], v[186:187], v[210:211]
	v_pk_fma_f32 v[214:215], v[194:195], v[34:35], v[210:211]
	v_pk_fma_f32 v[214:215], v[178:179], v[212:213], v[214:215]
	v_pk_add_f32 v[214:215], v[202:203], v[214:215]
	v_mul_f32_e32 v216, 0x3d372713, v214
	v_mul_f32_e32 v216, v214, v216
	v_fma_f32 v216, v214, v216, v214
	v_mul_f32_e32 v216, 0x3f4c422a, v216
	v_mul_f32_e32 v216, 0xc038aa3b, v216
	v_exp_f32_e32 v216, v216
	s_nop 0
	v_add_f32_e32 v216, 1.0, v216
	v_rcp_f32_e32 v216, v216
	s_nop 0
	v_mul_f32_e32 v214, v214, v216
	v_mul_f32_e32 v214, v42, v214
	v_mul_f32_e32 v216, 0x3d372713, v215
	v_mul_f32_e32 v216, v215, v216
	v_fma_f32 v216, v215, v216, v215
	v_mul_f32_e32 v216, 0x3f4c422a, v216
	v_mul_f32_e32 v216, 0xc038aa3b, v216
	v_exp_f32_e32 v216, v216
	s_nop 0
	v_add_f32_e32 v216, 1.0, v216
	v_rcp_f32_e32 v216, v216
	s_nop 0
	v_mul_f32_e32 v215, v215, v216
	v_mul_f32_e32 v215, v43, v215
	v_cvt_pk_bf16_f32 v42, v214, v215
	v_mov_b32_dpp v210, v20 row_ror:1 row_mask:0xf bank_mask:0xf
	v_mov_b32_dpp v212, v20 row_ror:2 row_mask:0xf bank_mask:0xf
	v_mov_b32_dpp v211, v21 row_ror:1 row_mask:0xf bank_mask:0xf
	v_mov_b32_dpp v213, v21 row_ror:2 row_mask:0xf bank_mask:0xf
	s_nop 1
	v_mov_b32_dpp v210, v36 row_shr:1 row_mask:0xf bank_mask:0xf
	v_mov_b32_dpp v212, v36 row_shr:2 row_mask:0xf bank_mask:0xf
	v_mov_b32_dpp v211, v37 row_shr:1 row_mask:0xf bank_mask:0xf
	v_mov_b32_dpp v213, v37 row_shr:2 row_mask:0xf bank_mask:0xf
	s_nop 1
	v_pk_mul_f32 v[210:211], v[188:189], v[210:211]
	v_pk_fma_f32 v[214:215], v[196:197], v[36:37], v[210:211]
	v_pk_fma_f32 v[214:215], v[180:181], v[212:213], v[214:215]
	v_pk_add_f32 v[214:215], v[204:205], v[214:215]
	v_mul_f32_e32 v216, 0x3d372713, v214
	v_mul_f32_e32 v216, v214, v216
	v_fma_f32 v216, v214, v216, v214
	v_mul_f32_e32 v216, 0x3f4c422a, v216
	v_mul_f32_e32 v216, 0xc038aa3b, v216
	v_exp_f32_e32 v216, v216
	s_nop 0
	v_add_f32_e32 v216, 1.0, v216
	v_rcp_f32_e32 v216, v216
	s_nop 0
	v_mul_f32_e32 v214, v214, v216
	v_mul_f32_e32 v214, v44, v214
	v_mul_f32_e32 v216, 0x3d372713, v215
	v_mul_f32_e32 v216, v215, v216
	v_fma_f32 v216, v215, v216, v215
	v_mul_f32_e32 v216, 0x3f4c422a, v216
	v_mul_f32_e32 v216, 0xc038aa3b, v216
	v_exp_f32_e32 v216, v216
	s_nop 0
	v_add_f32_e32 v216, 1.0, v216
	v_rcp_f32_e32 v216, v216
	s_nop 0
	v_mul_f32_e32 v215, v215, v216
	v_mul_f32_e32 v215, v45, v215
	v_cvt_pk_bf16_f32 v43, v214, v215
	v_mov_b32_dpp v210, v22 row_ror:1 row_mask:0xf bank_mask:0xf
	v_mov_b32_dpp v212, v22 row_ror:2 row_mask:0xf bank_mask:0xf
	v_mov_b32_dpp v211, v23 row_ror:1 row_mask:0xf bank_mask:0xf
	v_mov_b32_dpp v213, v23 row_ror:2 row_mask:0xf bank_mask:0xf
	s_nop 1
	v_mov_b32_dpp v210, v38 row_shr:1 row_mask:0xf bank_mask:0xf
	v_mov_b32_dpp v212, v38 row_shr:2 row_mask:0xf bank_mask:0xf
	v_mov_b32_dpp v211, v39 row_shr:1 row_mask:0xf bank_mask:0xf
	v_mov_b32_dpp v213, v39 row_shr:2 row_mask:0xf bank_mask:0xf
	s_nop 1
	v_pk_mul_f32 v[210:211], v[190:191], v[210:211]
	v_pk_fma_f32 v[214:215], v[198:199], v[38:39], v[210:211]
	v_pk_fma_f32 v[214:215], v[182:183], v[212:213], v[214:215]
	v_pk_add_f32 v[214:215], v[206:207], v[214:215]
	v_mul_f32_e32 v216, 0x3d372713, v214
	v_mul_f32_e32 v216, v214, v216
	v_fma_f32 v216, v214, v216, v214
	v_mul_f32_e32 v216, 0x3f4c422a, v216
	v_mul_f32_e32 v216, 0xc038aa3b, v216
	v_exp_f32_e32 v216, v216
	s_nop 0
	v_add_f32_e32 v216, 1.0, v216
	v_rcp_f32_e32 v216, v216
	s_nop 0
	v_mul_f32_e32 v214, v214, v216
	v_mul_f32_e32 v214, v46, v214
	v_mul_f32_e32 v216, 0x3d372713, v215
	v_mul_f32_e32 v216, v215, v216
	v_fma_f32 v216, v215, v216, v215
	v_mul_f32_e32 v216, 0x3f4c422a, v216
	v_mul_f32_e32 v216, 0xc038aa3b, v216
	v_exp_f32_e32 v216, v216
	s_nop 0
	v_add_f32_e32 v216, 1.0, v216
	v_rcp_f32_e32 v216, v216
	s_nop 0
	v_mul_f32_e32 v215, v215, v216
	v_mul_f32_e32 v215, v47, v215
	v_cvt_pk_bf16_f32 v44, v214, v215
	v_mov_b32_dpp v210, v24 row_ror:1 row_mask:0xf bank_mask:0xf
	v_mov_b32_dpp v212, v24 row_ror:2 row_mask:0xf bank_mask:0xf
	v_mov_b32_dpp v211, v25 row_ror:1 row_mask:0xf bank_mask:0xf
	v_mov_b32_dpp v213, v25 row_ror:2 row_mask:0xf bank_mask:0xf
	s_nop 1
	v_mov_b32_dpp v210, v40 row_shr:1 row_mask:0xf bank_mask:0xf
	v_mov_b32_dpp v212, v40 row_shr:2 row_mask:0xf bank_mask:0xf
	v_mov_b32_dpp v211, v41 row_shr:1 row_mask:0xf bank_mask:0xf
	v_mov_b32_dpp v213, v41 row_shr:2 row_mask:0xf bank_mask:0xf
	s_nop 1
	v_pk_mul_f32 v[210:211], v[192:193], v[210:211]
	v_pk_fma_f32 v[214:215], v[200:201], v[40:41], v[210:211]
	v_pk_fma_f32 v[214:215], v[184:185], v[212:213], v[214:215]
	v_pk_add_f32 v[214:215], v[208:209], v[214:215]
	v_mul_f32_e32 v216, 0x3d372713, v214
	v_mul_f32_e32 v216, v214, v216
	v_fma_f32 v216, v214, v216, v214
	v_mul_f32_e32 v216, 0x3f4c422a, v216
	v_mul_f32_e32 v216, 0xc038aa3b, v216
	v_exp_f32_e32 v216, v216
	s_nop 0
	v_add_f32_e32 v216, 1.0, v216
	v_rcp_f32_e32 v216, v216
	s_nop 0
	v_mul_f32_e32 v214, v214, v216
	v_mul_f32_e32 v214, v48, v214
	v_mul_f32_e32 v216, 0x3d372713, v215
	v_mul_f32_e32 v216, v215, v216
	v_fma_f32 v216, v215, v216, v215
	v_mul_f32_e32 v216, 0x3f4c422a, v216
	v_mul_f32_e32 v216, 0xc038aa3b, v216
	v_exp_f32_e32 v216, v216
	s_nop 0
	v_add_f32_e32 v216, 1.0, v216
	v_rcp_f32_e32 v216, v216
	s_nop 0
	v_mul_f32_e32 v215, v215, v216
	v_mul_f32_e32 v215, v49, v215
	v_cvt_pk_bf16_f32 v45, v214, v215
	s_add_i32 s26, s66, -32
	v_cmp_gt_i32_e64 s[24:25], s26, v227
	s_nop 1
	s_and_saveexec_b64 s[26:27], s[24:25]
	global_store_dwordx4 v242, v[42:45], s[18:19] offset:2048
	s_mov_b64 exec, s[26:27]
	s_nop 4
	v_mov_b32_dpp v210, v2 row_ror:1 row_mask:0xf bank_mask:0xf
	v_mov_b32_dpp v212, v2 row_ror:2 row_mask:0xf bank_mask:0xf
	v_mov_b32_dpp v211, v3 row_ror:1 row_mask:0xf bank_mask:0xf
	v_mov_b32_dpp v213, v3 row_ror:2 row_mask:0xf bank_mask:0xf
	s_nop 1
	v_mov_b32_dpp v210, v18 row_shr:1 row_mask:0xf bank_mask:0xf
	v_mov_b32_dpp v212, v18 row_shr:2 row_mask:0xf bank_mask:0xf
	v_mov_b32_dpp v211, v19 row_shr:1 row_mask:0xf bank_mask:0xf
	v_mov_b32_dpp v213, v19 row_shr:2 row_mask:0xf bank_mask:0xf
	s_nop 1
	v_pk_mul_f32 v[210:211], v[186:187], v[210:211]
	v_pk_fma_f32 v[214:215], v[194:195], v[18:19], v[210:211]
	v_pk_fma_f32 v[214:215], v[178:179], v[212:213], v[214:215]
	v_pk_add_f32 v[214:215], v[202:203], v[214:215]
	v_mul_f32_e32 v216, 0x3d372713, v214
	v_mul_f32_e32 v216, v214, v216
	v_fma_f32 v216, v214, v216, v214
	v_mul_f32_e32 v216, 0x3f4c422a, v216
	v_mul_f32_e32 v216, 0xc038aa3b, v216
	v_exp_f32_e32 v216, v216
	s_nop 0
	v_add_f32_e32 v216, 1.0, v216
	v_rcp_f32_e32 v216, v216
	s_nop 0
	v_mul_f32_e32 v214, v214, v216
	v_mul_f32_e32 v214, v26, v214
	v_mul_f32_e32 v216, 0x3d372713, v215
	v_mul_f32_e32 v216, v215, v216
	v_fma_f32 v216, v215, v216, v215
	v_mul_f32_e32 v216, 0x3f4c422a, v216
	v_mul_f32_e32 v216, 0xc038aa3b, v216
	v_exp_f32_e32 v216, v216
	s_nop 0
	v_add_f32_e32 v216, 1.0, v216
	v_rcp_f32_e32 v216, v216
	s_nop 0
	v_mul_f32_e32 v215, v215, v216
	v_mul_f32_e32 v215, v27, v215
	v_cvt_pk_bf16_f32 v26, v214, v215
	v_mov_b32_dpp v210, v4 row_ror:1 row_mask:0xf bank_mask:0xf
	v_mov_b32_dpp v212, v4 row_ror:2 row_mask:0xf bank_mask:0xf
	v_mov_b32_dpp v211, v5 row_ror:1 row_mask:0xf bank_mask:0xf
	v_mov_b32_dpp v213, v5 row_ror:2 row_mask:0xf bank_mask:0xf
	s_nop 1
	v_mov_b32_dpp v210, v20 row_shr:1 row_mask:0xf bank_mask:0xf
	v_mov_b32_dpp v212, v20 row_shr:2 row_mask:0xf bank_mask:0xf
	v_mov_b32_dpp v211, v21 row_shr:1 row_mask:0xf bank_mask:0xf
	v_mov_b32_dpp v213, v21 row_shr:2 row_mask:0xf bank_mask:0xf
	s_nop 1
	v_pk_mul_f32 v[210:211], v[188:189], v[210:211]
	v_pk_fma_f32 v[214:215], v[196:197], v[20:21], v[210:211]
	v_pk_fma_f32 v[214:215], v[180:181], v[212:213], v[214:215]
	v_pk_add_f32 v[214:215], v[204:205], v[214:215]
	v_mul_f32_e32 v216, 0x3d372713, v214
	v_mul_f32_e32 v216, v214, v216
	v_fma_f32 v216, v214, v216, v214
	v_mul_f32_e32 v216, 0x3f4c422a, v216
	v_mul_f32_e32 v216, 0xc038aa3b, v216
	v_exp_f32_e32 v216, v216
	s_nop 0
	v_add_f32_e32 v216, 1.0, v216
	v_rcp_f32_e32 v216, v216
	s_nop 0
	v_mul_f32_e32 v214, v214, v216
	v_mul_f32_e32 v214, v28, v214
	v_mul_f32_e32 v216, 0x3d372713, v215
	v_mul_f32_e32 v216, v215, v216
	v_fma_f32 v216, v215, v216, v215
	v_mul_f32_e32 v216, 0x3f4c422a, v216
	v_mul_f32_e32 v216, 0xc038aa3b, v216
	v_exp_f32_e32 v216, v216
	s_nop 0
	v_add_f32_e32 v216, 1.0, v216
	v_rcp_f32_e32 v216, v216
	s_nop 0
	v_mul_f32_e32 v215, v215, v216
	v_mul_f32_e32 v215, v29, v215
	v_cvt_pk_bf16_f32 v27, v214, v215
	v_mov_b32_dpp v210, v6 row_ror:1 row_mask:0xf bank_mask:0xf
	v_mov_b32_dpp v212, v6 row_ror:2 row_mask:0xf bank_mask:0xf
	v_mov_b32_dpp v211, v7 row_ror:1 row_mask:0xf bank_mask:0xf
	v_mov_b32_dpp v213, v7 row_ror:2 row_mask:0xf bank_mask:0xf
	s_nop 1
	v_mov_b32_dpp v210, v22 row_shr:1 row_mask:0xf bank_mask:0xf
	v_mov_b32_dpp v212, v22 row_shr:2 row_mask:0xf bank_mask:0xf
	v_mov_b32_dpp v211, v23 row_shr:1 row_mask:0xf bank_mask:0xf
	v_mov_b32_dpp v213, v23 row_shr:2 row_mask:0xf bank_mask:0xf
	s_nop 1
	v_pk_mul_f32 v[210:211], v[190:191], v[210:211]
	v_pk_fma_f32 v[214:215], v[198:199], v[22:23], v[210:211]
	v_pk_fma_f32 v[214:215], v[182:183], v[212:213], v[214:215]
	v_pk_add_f32 v[214:215], v[206:207], v[214:215]
	v_mul_f32_e32 v216, 0x3d372713, v214
	v_mul_f32_e32 v216, v214, v216
	v_fma_f32 v216, v214, v216, v214
	v_mul_f32_e32 v216, 0x3f4c422a, v216
	v_mul_f32_e32 v216, 0xc038aa3b, v216
	v_exp_f32_e32 v216, v216
	s_nop 0
	v_add_f32_e32 v216, 1.0, v216
	v_rcp_f32_e32 v216, v216
	s_nop 0
	v_mul_f32_e32 v214, v214, v216
	v_mul_f32_e32 v214, v30, v214
	v_mul_f32_e32 v216, 0x3d372713, v215
	v_mul_f32_e32 v216, v215, v216
	v_fma_f32 v216, v215, v216, v215
	v_mul_f32_e32 v216, 0x3f4c422a, v216
	v_mul_f32_e32 v216, 0xc038aa3b, v216
	v_exp_f32_e32 v216, v216
	s_nop 0
	v_add_f32_e32 v216, 1.0, v216
	v_rcp_f32_e32 v216, v216
	s_nop 0
	v_mul_f32_e32 v215, v215, v216
	v_mul_f32_e32 v215, v31, v215
	v_cvt_pk_bf16_f32 v28, v214, v215
	v_mov_b32_dpp v210, v8 row_ror:1 row_mask:0xf bank_mask:0xf
	v_mov_b32_dpp v212, v8 row_ror:2 row_mask:0xf bank_mask:0xf
	v_mov_b32_dpp v211, v9 row_ror:1 row_mask:0xf bank_mask:0xf
	v_mov_b32_dpp v213, v9 row_ror:2 row_mask:0xf bank_mask:0xf
	s_nop 1
	v_mov_b32_dpp v210, v24 row_shr:1 row_mask:0xf bank_mask:0xf
	v_mov_b32_dpp v212, v24 row_shr:2 row_mask:0xf bank_mask:0xf
	v_mov_b32_dpp v211, v25 row_shr:1 row_mask:0xf bank_mask:0xf
	v_mov_b32_dpp v213, v25 row_shr:2 row_mask:0xf bank_mask:0xf
	s_nop 1
	v_pk_mul_f32 v[210:211], v[192:193], v[210:211]
	v_pk_fma_f32 v[214:215], v[200:201], v[24:25], v[210:211]
	v_pk_fma_f32 v[214:215], v[184:185], v[212:213], v[214:215]
	v_pk_add_f32 v[214:215], v[208:209], v[214:215]
	v_mul_f32_e32 v216, 0x3d372713, v214
	v_mul_f32_e32 v216, v214, v216
	v_fma_f32 v216, v214, v216, v214
	v_mul_f32_e32 v216, 0x3f4c422a, v216
	v_mul_f32_e32 v216, 0xc038aa3b, v216
	v_exp_f32_e32 v216, v216
	s_nop 0
	v_add_f32_e32 v216, 1.0, v216
	v_rcp_f32_e32 v216, v216
	s_nop 0
	v_mul_f32_e32 v214, v214, v216
	v_mul_f32_e32 v214, v32, v214
	v_mul_f32_e32 v216, 0x3d372713, v215
	v_mul_f32_e32 v216, v215, v216
	v_fma_f32 v216, v215, v216, v215
	v_mul_f32_e32 v216, 0x3f4c422a, v216
	v_mul_f32_e32 v216, 0xc038aa3b, v216
	v_exp_f32_e32 v216, v216
	s_nop 0
	v_add_f32_e32 v216, 1.0, v216
	v_rcp_f32_e32 v216, v216
	s_nop 0
	v_mul_f32_e32 v215, v215, v216
	v_mul_f32_e32 v215, v33, v215
	v_cvt_pk_bf16_f32 v29, v214, v215
	s_add_i32 s26, s66, -16
	v_cmp_gt_i32_e64 s[24:25], s26, v227
	s_nop 1
	s_and_saveexec_b64 s[26:27], s[24:25]
	global_store_dwordx4 v242, v[26:29], s[18:19] offset:1024
	s_mov_b64 exec, s[26:27]
	s_nop 4
	v_mov_b32_dpp v210, v218 row_ror:1 row_mask:0xf bank_mask:0xf
	v_mov_b32_dpp v212, v218 row_ror:2 row_mask:0xf bank_mask:0xf
	v_mov_b32_dpp v211, v219 row_ror:1 row_mask:0xf bank_mask:0xf
	v_mov_b32_dpp v213, v219 row_ror:2 row_mask:0xf bank_mask:0xf
	s_nop 1
	v_mov_b32_dpp v210, v2 row_shr:1 row_mask:0xf bank_mask:0xf
	v_mov_b32_dpp v212, v2 row_shr:2 row_mask:0xf bank_mask:0xf
	v_mov_b32_dpp v211, v3 row_shr:1 row_mask:0xf bank_mask:0xf
	v_mov_b32_dpp v213, v3 row_shr:2 row_mask:0xf bank_mask:0xf
	s_nop 1
	v_pk_mul_f32 v[210:211], v[186:187], v[210:211]
	v_pk_fma_f32 v[214:215], v[194:195], v[2:3], v[210:211]
	v_pk_fma_f32 v[214:215], v[178:179], v[212:213], v[214:215]
	v_pk_add_f32 v[214:215], v[202:203], v[214:215]
	v_mul_f32_e32 v216, 0x3d372713, v214
	v_mul_f32_e32 v216, v214, v216
	v_fma_f32 v216, v214, v216, v214
	v_mul_f32_e32 v216, 0x3f4c422a, v216
	v_mul_f32_e32 v216, 0xc038aa3b, v216
	v_exp_f32_e32 v216, v216
	s_nop 0
	v_add_f32_e32 v216, 1.0, v216
	v_rcp_f32_e32 v216, v216
	s_nop 0
	v_mul_f32_e32 v214, v214, v216
	v_mul_f32_e32 v214, v10, v214
	v_mul_f32_e32 v216, 0x3d372713, v215
	v_mul_f32_e32 v216, v215, v216
	v_fma_f32 v216, v215, v216, v215
	v_mul_f32_e32 v216, 0x3f4c422a, v216
	v_mul_f32_e32 v216, 0xc038aa3b, v216
	v_exp_f32_e32 v216, v216
	s_nop 0
	v_add_f32_e32 v216, 1.0, v216
	v_rcp_f32_e32 v216, v216
	s_nop 0
	v_mul_f32_e32 v215, v215, v216
	v_mul_f32_e32 v215, v11, v215
	v_cvt_pk_bf16_f32 v10, v214, v215
	v_mov_b32_dpp v210, v220 row_ror:1 row_mask:0xf bank_mask:0xf
	v_mov_b32_dpp v212, v220 row_ror:2 row_mask:0xf bank_mask:0xf
	v_mov_b32_dpp v211, v221 row_ror:1 row_mask:0xf bank_mask:0xf
	v_mov_b32_dpp v213, v221 row_ror:2 row_mask:0xf bank_mask:0xf
	s_nop 1
	v_mov_b32_dpp v210, v4 row_shr:1 row_mask:0xf bank_mask:0xf
	v_mov_b32_dpp v212, v4 row_shr:2 row_mask:0xf bank_mask:0xf
	v_mov_b32_dpp v211, v5 row_shr:1 row_mask:0xf bank_mask:0xf
	v_mov_b32_dpp v213, v5 row_shr:2 row_mask:0xf bank_mask:0xf
	s_nop 1
	v_pk_mul_f32 v[210:211], v[188:189], v[210:211]
	v_pk_fma_f32 v[214:215], v[196:197], v[4:5], v[210:211]
	v_pk_fma_f32 v[214:215], v[180:181], v[212:213], v[214:215]
	v_pk_add_f32 v[214:215], v[204:205], v[214:215]
	v_mul_f32_e32 v216, 0x3d372713, v214
	v_mul_f32_e32 v216, v214, v216
	v_fma_f32 v216, v214, v216, v214
	v_mul_f32_e32 v216, 0x3f4c422a, v216
	v_mul_f32_e32 v216, 0xc038aa3b, v216
	v_exp_f32_e32 v216, v216
	s_nop 0
	v_add_f32_e32 v216, 1.0, v216
	v_rcp_f32_e32 v216, v216
	s_nop 0
	v_mul_f32_e32 v214, v214, v216
	v_mul_f32_e32 v214, v12, v214
	v_mul_f32_e32 v216, 0x3d372713, v215
	v_mul_f32_e32 v216, v215, v216
	v_fma_f32 v216, v215, v216, v215
	v_mul_f32_e32 v216, 0x3f4c422a, v216
	v_mul_f32_e32 v216, 0xc038aa3b, v216
	v_exp_f32_e32 v216, v216
	s_nop 0
	v_add_f32_e32 v216, 1.0, v216
	v_rcp_f32_e32 v216, v216
	s_nop 0
	v_mul_f32_e32 v215, v215, v216
	v_mul_f32_e32 v215, v13, v215
	v_cvt_pk_bf16_f32 v11, v214, v215
	v_mov_b32_dpp v210, v222 row_ror:1 row_mask:0xf bank_mask:0xf
	v_mov_b32_dpp v212, v222 row_ror:2 row_mask:0xf bank_mask:0xf
	v_mov_b32_dpp v211, v223 row_ror:1 row_mask:0xf bank_mask:0xf
	v_mov_b32_dpp v213, v223 row_ror:2 row_mask:0xf bank_mask:0xf
	s_nop 1
	v_mov_b32_dpp v210, v6 row_shr:1 row_mask:0xf bank_mask:0xf
	v_mov_b32_dpp v212, v6 row_shr:2 row_mask:0xf bank_mask:0xf
	v_mov_b32_dpp v211, v7 row_shr:1 row_mask:0xf bank_mask:0xf
	v_mov_b32_dpp v213, v7 row_shr:2 row_mask:0xf bank_mask:0xf
	s_nop 1
	v_pk_mul_f32 v[210:211], v[190:191], v[210:211]
	v_pk_fma_f32 v[214:215], v[198:199], v[6:7], v[210:211]
	v_pk_fma_f32 v[214:215], v[182:183], v[212:213], v[214:215]
	v_pk_add_f32 v[214:215], v[206:207], v[214:215]
	v_mul_f32_e32 v216, 0x3d372713, v214
	v_mul_f32_e32 v216, v214, v216
	v_fma_f32 v216, v214, v216, v214
	v_mul_f32_e32 v216, 0x3f4c422a, v216
	v_mul_f32_e32 v216, 0xc038aa3b, v216
	v_exp_f32_e32 v216, v216
	s_nop 0
	v_add_f32_e32 v216, 1.0, v216
	v_rcp_f32_e32 v216, v216
	s_nop 0
	v_mul_f32_e32 v214, v214, v216
	v_mul_f32_e32 v214, v14, v214
	v_mul_f32_e32 v216, 0x3d372713, v215
	v_mul_f32_e32 v216, v215, v216
	v_fma_f32 v216, v215, v216, v215
	v_mul_f32_e32 v216, 0x3f4c422a, v216
	v_mul_f32_e32 v216, 0xc038aa3b, v216
	v_exp_f32_e32 v216, v216
	s_nop 0
	v_add_f32_e32 v216, 1.0, v216
	v_rcp_f32_e32 v216, v216
	s_nop 0
	v_mul_f32_e32 v215, v215, v216
	v_mul_f32_e32 v215, v15, v215
	v_cvt_pk_bf16_f32 v12, v214, v215
	v_mov_b32_dpp v210, v224 row_ror:1 row_mask:0xf bank_mask:0xf
	v_mov_b32_dpp v212, v224 row_ror:2 row_mask:0xf bank_mask:0xf
	v_mov_b32_dpp v211, v225 row_ror:1 row_mask:0xf bank_mask:0xf
	v_mov_b32_dpp v213, v225 row_ror:2 row_mask:0xf bank_mask:0xf
	s_nop 1
	v_mov_b32_dpp v210, v8 row_shr:1 row_mask:0xf bank_mask:0xf
	v_mov_b32_dpp v212, v8 row_shr:2 row_mask:0xf bank_mask:0xf
	v_mov_b32_dpp v211, v9 row_shr:1 row_mask:0xf bank_mask:0xf
	v_mov_b32_dpp v213, v9 row_shr:2 row_mask:0xf bank_mask:0xf
	s_nop 1
	v_pk_mul_f32 v[210:211], v[192:193], v[210:211]
	v_pk_fma_f32 v[214:215], v[200:201], v[8:9], v[210:211]
	v_pk_fma_f32 v[214:215], v[184:185], v[212:213], v[214:215]
	v_pk_add_f32 v[214:215], v[208:209], v[214:215]
	v_mul_f32_e32 v216, 0x3d372713, v214
	v_mul_f32_e32 v216, v214, v216
	v_fma_f32 v216, v214, v216, v214
	v_mul_f32_e32 v216, 0x3f4c422a, v216
	v_mul_f32_e32 v216, 0xc038aa3b, v216
	v_exp_f32_e32 v216, v216
	s_nop 0
	v_add_f32_e32 v216, 1.0, v216
	v_rcp_f32_e32 v216, v216
	s_nop 0
	v_mul_f32_e32 v214, v214, v216
	v_mul_f32_e32 v214, v16, v214
	v_mul_f32_e32 v216, 0x3d372713, v215
	v_mul_f32_e32 v216, v215, v216
	v_fma_f32 v216, v215, v216, v215
	v_mul_f32_e32 v216, 0x3f4c422a, v216
	v_mul_f32_e32 v216, 0xc038aa3b, v216
	v_exp_f32_e32 v216, v216
	s_nop 0
	v_add_f32_e32 v216, 1.0, v216
	v_rcp_f32_e32 v216, v216
	s_nop 0
	v_mul_f32_e32 v215, v215, v216
	v_mul_f32_e32 v215, v17, v215
	v_cvt_pk_bf16_f32 v13, v214, v215
	s_add_i32 s26, s66, 0
	v_cmp_gt_i32_e64 s[24:25], s26, v227
	v_cmp_lt_u32_e32 vcc, 1, v227
	s_and_b64 s[24:25], s[24:25], vcc
	s_nop 1
	s_and_saveexec_b64 s[26:27], s[24:25]
	global_store_dwordx4 v242, v[10:13], s[18:19]
	s_mov_b64 exec, s[26:27]
	s_nop 4
	s_mov_b32 s34, s38
	s_mov_b32 s35, s30
	s_mov_b32 s36, s31
	s_branch .Lup_tile
.Lup_tail_last:
	s_waitcnt vmcnt(6) lgkmcnt(0)
	s_barrier
	v_add_u32_e32 v240, s61, v238
	v_add_u32_e32 v241, s61, v239
	s_add_i32 m0, s60, s62
	v_mfma_f32_16x16x32_bf16 v[2:5], v[162:165], v[130:133], v[2:5]
	global_load_lds_dwordx4 v226, s[54:55]
	v_mfma_f32_16x16x32_bf16 v[6:9], v[166:169], v[130:133], v[6:9]
	global_load_lds_dwordx4 v226, s[54:55] offset:1024
	v_mfma_f32_16x16x32_bf16 v[10:13], v[170:173], v[130:133], v[10:13]
	global_load_lds_dwordx4 v226, s[54:55] offset:2048
	v_mfma_f32_16x16x32_bf16 v[14:17], v[174:177], v[130:133], v[14:17]
	global_load_lds_dwordx4 v226, s[54:55] offset:3072
	s_add_i32 m0, s60, s63
	v_mfma_f32_16x16x32_bf16 v[18:21], v[162:165], v[134:137], v[18:21]
	global_load_lds_dwordx4 v230, s[56:57]
	v_mfma_f32_16x16x32_bf16 v[22:25], v[166:169], v[134:137], v[22:25]
	global_load_lds_dwordx4 v231, s[56:57] offset:1024
	v_mfma_f32_16x16x32_bf16 v[26:29], v[170:173], v[134:137], v[26:29]
	v_mfma_f32_16x16x32_bf16 v[30:33], v[174:177], v[134:137], v[30:33]
	v_mfma_f32_16x16x32_bf16 v[34:37], v[162:165], v[138:141], v[34:37]
	ds_read_b128 v[210:213], v241 offset:0
	v_mfma_f32_16x16x32_bf16 v[38:41], v[166:169], v[138:141], v[38:41]
	ds_read_b128 v[214:217], v241 offset:256
	v_mfma_f32_16x16x32_bf16 v[42:45], v[170:173], v[138:141], v[42:45]
	ds_read_b128 v[218:221], v241 offset:2048
	v_mfma_f32_16x16x32_bf16 v[46:49], v[174:177], v[138:141], v[46:49]
	ds_read_b128 v[222:225], v241 offset:2304
	v_mfma_f32_16x16x32_bf16 v[50:53], v[162:165], v[142:145], v[50:53]
	ds_read_b128 v[178:181], v240 offset:0
	v_mfma_f32_16x16x32_bf16 v[54:57], v[166:169], v[142:145], v[54:57]
	ds_read_b128 v[182:185], v240 offset:1024
	v_mfma_f32_16x16x32_bf16 v[58:61], v[170:173], v[142:145], v[58:61]
	ds_read_b128 v[186:189], v240 offset:2048
	v_mfma_f32_16x16x32_bf16 v[62:65], v[174:177], v[142:145], v[62:65]
	ds_read_b128 v[190:193], v240 offset:3072
	v_mfma_f32_16x16x32_bf16 v[66:69], v[162:165], v[146:149], v[66:69]
	ds_read_b128 v[194:197], v240 offset:4096
	v_mfma_f32_16x16x32_bf16 v[70:73], v[166:169], v[146:149], v[70:73]
	ds_read_b128 v[198:201], v240 offset:5120
	v_mfma_f32_16x16x32_bf16 v[74:77], v[170:173], v[146:149], v[74:77]
	ds_read_b128 v[202:205], v240 offset:6144
	v_mfma_f32_16x16x32_bf16 v[78:81], v[174:177], v[146:149], v[78:81]
	ds_read_b128 v[206:209], v240 offset:7168
	v_mfma_f32_16x16x32_bf16 v[82:85], v[162:165], v[150:153], v[82:85]
	v_mfma_f32_16x16x32_bf16 v[86:89], v[166:169], v[150:153], v[86:89]
	v_mfma_f32_16x16x32_bf16 v[90:93], v[170:173], v[150:153], v[90:93]
	v_mfma_f32_16x16x32_bf16 v[94:97], v[174:177], v[150:153], v[94:97]
	v_mfma_f32_16x16x32_bf16 v[98:101], v[162:165], v[154:157], v[98:101]
	v_mfma_f32_16x16x32_bf16 v[102:105], v[166:169], v[154:157], v[102:105]
	v_mfma_f32_16x16x32_bf16 v[106:109], v[170:173], v[154:157], v[106:109]
	v_mfma_f32_16x16x32_bf16 v[110:113], v[174:177], v[154:157], v[110:113]
	v_mfma_f32_16x16x32_bf16 v[114:117], v[162:165], v[158:161], v[114:117]
	v_mfma_f32_16x16x32_bf16 v[118:121], v[166:169], v[158:161], v[118:121]
	v_mfma_f32_16x16x32_bf16 v[122:125], v[170:173], v[158:161], v[122:125]
	v_mfma_f32_16x16x32_bf16 v[126:129], v[174:177], v[158:161], v[126:129]
	s_add_i32 s60, s60, 0x6000
	s_cmp_eq_u32 s60, 0x12000
	s_cselect_b32 s60, 0, s60
	s_add_u32 s54, s54, s72
	s_addc_u32 s55, s55, 0
	s_add_u32 s56, s56, s73
	s_addc_u32 s57, s57, 0
	s_add_i32 s61, s61, 0x6000
	s_cmp_eq_u32 s61, 0x12000
	s_cselect_b32 s61, 0, s61
	s_waitcnt vmcnt(6) lgkmcnt(0)
	s_barrier
	v_add_u32_e32 v240, s61, v238
	v_add_u32_e32 v241, s61, v239
	v_mfma_f32_16x16x32_bf16 v[2:5], v[210:213], v[178:181], v[2:5]
	v_mfma_f32_16x16x32_bf16 v[6:9], v[214:217], v[178:181], v[6:9]
	v_mfma_f32_16x16x32_bf16 v[10:13], v[218:221], v[178:181], v[10:13]
	v_mfma_f32_16x16x32_bf16 v[14:17], v[222:225], v[178:181], v[14:17]
	v_mfma_f32_16x16x32_bf16 v[18:21], v[210:213], v[182:185], v[18:21]
	v_mfma_f32_16x16x32_bf16 v[22:25], v[214:217], v[182:185], v[22:25]
	v_mfma_f32_16x16x32_bf16 v[26:29], v[218:221], v[182:185], v[26:29]
	v_mfma_f32_16x16x32_bf16 v[30:33], v[222:225], v[182:185], v[30:33]
	v_mfma_f32_16x16x32_bf16 v[34:37], v[210:213], v[186:189], v[34:37]
	ds_read_b128 v[162:165], v241 offset:0
	v_mfma_f32_16x16x32_bf16 v[38:41], v[214:217], v[186:189], v[38:41]
	ds_read_b128 v[166:169], v241 offset:256
	v_mfma_f32_16x16x32_bf16 v[42:45], v[218:221], v[186:189], v[42:45]
	ds_read_b128 v[170:173], v241 offset:2048
	v_mfma_f32_16x16x32_bf16 v[46:49], v[222:225], v[186:189], v[46:49]
	ds_read_b128 v[174:177], v241 offset:2304
	v_mfma_f32_16x16x32_bf16 v[50:53], v[210:213], v[190:193], v[50:53]
	ds_read_b128 v[130:133], v240 offset:0
	v_mfma_f32_16x16x32_bf16 v[54:57], v[214:217], v[190:193], v[54:57]
	ds_read_b128 v[134:137], v240 offset:1024
	v_mfma_f32_16x16x32_bf16 v[58:61], v[218:221], v[190:193], v[58:61]
	ds_read_b128 v[138:141], v240 offset:2048
	v_mfma_f32_16x16x32_bf16 v[62:65], v[222:225], v[190:193], v[62:65]
	ds_read_b128 v[142:145], v240 offset:3072
	v_mfma_f32_16x16x32_bf16 v[66:69], v[210:213], v[194:197], v[66:69]
	ds_read_b128 v[146:149], v240 offset:4096
	v_mfma_f32_16x16x32_bf16 v[70:73], v[214:217], v[194:197], v[70:73]
	ds_read_b128 v[150:153], v240 offset:5120
	v_mfma_f32_16x16x32_bf16 v[74:77], v[218:221], v[194:197], v[74:77]
	ds_read_b128 v[154:157], v240 offset:6144
	v_mfma_f32_16x16x32_bf16 v[78:81], v[222:225], v[194:197], v[78:81]
	ds_read_b128 v[158:161], v240 offset:7168
	v_mfma_f32_16x16x32_bf16 v[82:85], v[210:213], v[198:201], v[82:85]
	v_mfma_f32_16x16x32_bf16 v[86:89], v[214:217], v[198:201], v[86:89]
	v_mfma_f32_16x16x32_bf16 v[90:93], v[218:221], v[198:201], v[90:93]
	v_mfma_f32_16x16x32_bf16 v[94:97], v[222:225], v[198:201], v[94:97]
	v_mfma_f32_16x16x32_bf16 v[98:101], v[210:213], v[202:205], v[98:101]
	v_mfma_f32_16x16x32_bf16 v[102:105], v[214:217], v[202:205], v[102:105]
	v_mfma_f32_16x16x32_bf16 v[106:109], v[218:221], v[202:205], v[106:109]
	v_mfma_f32_16x16x32_bf16 v[110:113], v[222:225], v[202:205], v[110:113]
	v_mfma_f32_16x16x32_bf16 v[114:117], v[210:213], v[206:209], v[114:117]
	v_mfma_f32_16x16x32_bf16 v[118:121], v[214:217], v[206:209], v[118:121]
	v_mfma_f32_16x16x32_bf16 v[122:125], v[218:221], v[206:209], v[122:125]
	v_mfma_f32_16x16x32_bf16 v[126:129], v[222:225], v[206:209], v[126:129]
	s_add_i32 s61, s61, 0x6000
	s_cmp_eq_u32 s61, 0x12000
	s_cselect_b32 s61, 0, s61
	s_waitcnt vmcnt(0) lgkmcnt(0)
	s_barrier
	v_add_u32_e32 v240, s61, v238
	v_add_u32_e32 v241, s61, v239
	v_mfma_f32_16x16x32_bf16 v[2:5], v[162:165], v[130:133], v[2:5]
	v_mfma_f32_16x16x32_bf16 v[6:9], v[166:169], v[130:133], v[6:9]
	v_mfma_f32_16x16x32_bf16 v[10:13], v[170:173], v[130:133], v[10:13]
	v_mfma_f32_16x16x32_bf16 v[14:17], v[174:177], v[130:133], v[14:17]
	v_mfma_f32_16x16x32_bf16 v[18:21], v[162:165], v[134:137], v[18:21]
	v_mfma_f32_16x16x32_bf16 v[22:25], v[166:169], v[134:137], v[22:25]
	v_mfma_f32_16x16x32_bf16 v[26:29], v[170:173], v[134:137], v[26:29]
	v_mfma_f32_16x16x32_bf16 v[30:33], v[174:177], v[134:137], v[30:33]
	v_mfma_f32_16x16x32_bf16 v[34:37], v[162:165], v[138:141], v[34:37]
	ds_read_b128 v[210:213], v241 offset:0
	v_mfma_f32_16x16x32_bf16 v[38:41], v[166:169], v[138:141], v[38:41]
	ds_read_b128 v[214:217], v241 offset:256
	v_mfma_f32_16x16x32_bf16 v[42:45], v[170:173], v[138:141], v[42:45]
	ds_read_b128 v[218:221], v241 offset:2048
	v_mfma_f32_16x16x32_bf16 v[46:49], v[174:177], v[138:141], v[46:49]
	ds_read_b128 v[222:225], v241 offset:2304
	v_mfma_f32_16x16x32_bf16 v[50:53], v[162:165], v[142:145], v[50:53]
	ds_read_b128 v[178:181], v240 offset:0
	v_mfma_f32_16x16x32_bf16 v[54:57], v[166:169], v[142:145], v[54:57]
	ds_read_b128 v[182:185], v240 offset:1024
	v_mfma_f32_16x16x32_bf16 v[58:61], v[170:173], v[142:145], v[58:61]
	ds_read_b128 v[186:189], v240 offset:2048
	v_mfma_f32_16x16x32_bf16 v[62:65], v[174:177], v[142:145], v[62:65]
	ds_read_b128 v[190:193], v240 offset:3072
	v_mfma_f32_16x16x32_bf16 v[66:69], v[162:165], v[146:149], v[66:69]
	ds_read_b128 v[194:197], v240 offset:4096
	v_mfma_f32_16x16x32_bf16 v[70:73], v[166:169], v[146:149], v[70:73]
	ds_read_b128 v[198:201], v240 offset:5120
	v_mfma_f32_16x16x32_bf16 v[74:77], v[170:173], v[146:149], v[74:77]
	ds_read_b128 v[202:205], v240 offset:6144
	v_mfma_f32_16x16x32_bf16 v[78:81], v[174:177], v[146:149], v[78:81]
	ds_read_b128 v[206:209], v240 offset:7168
	v_mfma_f32_16x16x32_bf16 v[82:85], v[162:165], v[150:153], v[82:85]
	v_mfma_f32_16x16x32_bf16 v[86:89], v[166:169], v[150:153], v[86:89]
	v_mfma_f32_16x16x32_bf16 v[90:93], v[170:173], v[150:153], v[90:93]
	v_mfma_f32_16x16x32_bf16 v[94:97], v[174:177], v[150:153], v[94:97]
	v_mfma_f32_16x16x32_bf16 v[98:101], v[162:165], v[154:157], v[98:101]
	v_mfma_f32_16x16x32_bf16 v[102:105], v[166:169], v[154:157], v[102:105]
	v_mfma_f32_16x16x32_bf16 v[106:109], v[170:173], v[154:157], v[106:109]
	v_mfma_f32_16x16x32_bf16 v[110:113], v[174:177], v[154:157], v[110:113]
	v_mfma_f32_16x16x32_bf16 v[114:117], v[162:165], v[158:161], v[114:117]
	v_mfma_f32_16x16x32_bf16 v[118:121], v[166:169], v[158:161], v[118:121]
	v_mfma_f32_16x16x32_bf16 v[122:125], v[170:173], v[158:161], v[122:125]
	v_mfma_f32_16x16x32_bf16 v[126:129], v[174:177], v[158:161], v[126:129]
	s_add_i32 s61, s61, 0x6000
	s_cmp_eq_u32 s61, 0x12000
	s_cselect_b32 s61, 0, s61
	s_waitcnt lgkmcnt(0)
	s_barrier
	v_mfma_f32_16x16x32_bf16 v[2:5], v[210:213], v[178:181], v[2:5]
	v_mfma_f32_16x16x32_bf16 v[6:9], v[214:217], v[178:181], v[6:9]
	v_mfma_f32_16x16x32_bf16 v[10:13], v[218:221], v[178:181], v[10:13]
	v_mfma_f32_16x16x32_bf16 v[14:17], v[222:225], v[178:181], v[14:17]
	v_mfma_f32_16x16x32_bf16 v[18:21], v[210:213], v[182:185], v[18:21]
	v_mfma_f32_16x16x32_bf16 v[22:25], v[214:217], v[182:185], v[22:25]
	v_mfma_f32_16x16x32_bf16 v[26:29], v[218:221], v[182:185], v[26:29]
	v_mfma_f32_16x16x32_bf16 v[30:33], v[222:225], v[182:185], v[30:33]
	v_mfma_f32_16x16x32_bf16 v[34:37], v[210:213], v[186:189], v[34:37]
	v_mfma_f32_16x16x32_bf16 v[38:41], v[214:217], v[186:189], v[38:41]
	v_mfma_f32_16x16x32_bf16 v[42:45], v[218:221], v[186:189], v[42:45]
	v_mfma_f32_16x16x32_bf16 v[46:49], v[222:225], v[186:189], v[46:49]
	v_mfma_f32_16x16x32_bf16 v[50:53], v[210:213], v[190:193], v[50:53]
	v_mfma_f32_16x16x32_bf16 v[54:57], v[214:217], v[190:193], v[54:57]
	v_mfma_f32_16x16x32_bf16 v[58:61], v[218:221], v[190:193], v[58:61]
	v_mfma_f32_16x16x32_bf16 v[62:65], v[222:225], v[190:193], v[62:65]
	v_mfma_f32_16x16x32_bf16 v[66:69], v[210:213], v[194:197], v[66:69]
	v_mfma_f32_16x16x32_bf16 v[70:73], v[214:217], v[194:197], v[70:73]
	v_mfma_f32_16x16x32_bf16 v[74:77], v[218:221], v[194:197], v[74:77]
	v_mfma_f32_16x16x32_bf16 v[78:81], v[222:225], v[194:197], v[78:81]
	v_mfma_f32_16x16x32_bf16 v[82:85], v[210:213], v[198:201], v[82:85]
	v_mfma_f32_16x16x32_bf16 v[86:89], v[214:217], v[198:201], v[86:89]
	v_mfma_f32_16x16x32_bf16 v[90:93], v[218:221], v[198:201], v[90:93]
	v_mfma_f32_16x16x32_bf16 v[94:97], v[222:225], v[198:201], v[94:97]
	v_mfma_f32_16x16x32_bf16 v[98:101], v[210:213], v[202:205], v[98:101]
	v_mfma_f32_16x16x32_bf16 v[102:105], v[214:217], v[202:205], v[102:105]
	v_mfma_f32_16x16x32_bf16 v[106:109], v[218:221], v[202:205], v[106:109]
	v_mfma_f32_16x16x32_bf16 v[110:113], v[222:225], v[202:205], v[110:113]
	v_mfma_f32_16x16x32_bf16 v[114:117], v[210:213], v[206:209], v[114:117]
	v_mfma_f32_16x16x32_bf16 v[118:121], v[214:217], v[206:209], v[118:121]
	v_mfma_f32_16x16x32_bf16 v[122:125], v[218:221], v[206:209], v[122:125]
	v_mfma_f32_16x16x32_bf16 v[126:129], v[222:225], v[206:209], v[126:129]
	s_and_b32 s39, s35, 0xfff
	s_lshr_b32 s21, s36, 7
	s_lshl_b32 s26, s21, 8
	v_add_u32_e32 v216, s26, v228
	global_load_dwordx4 v[178:181], v216, s[82:83]
	global_load_dwordx4 v[182:185], v216, s[82:83] offset:16
	global_load_dwordx4 v[186:189], v216, s[92:93]
	global_load_dwordx4 v[190:193], v216, s[92:93] offset:16
	global_load_dwordx4 v[194:197], v216, s[96:97]
	global_load_dwordx4 v[198:201], v216, s[96:97] offset:16
	global_load_dwordx4 v[202:205], v216, s[28:29]
	global_load_dwordx4 v[206:209], v216, s[28:29] offset:16
	v_mbcnt_lo_u32_b32 v217, -1, 0
	v_mbcnt_hi_u32_b32 v217, -1, v217
	v_lshlrev_b32_e32 v217, 5, v217
	s_lshl_b32 s26, s43, 11
	s_add_i32 s26, s26, 0x12010
	v_add_u32_e32 v217, s26, v217
	s_cmp_eq_u32 s42, 0
	s_cbranch_scc0 .Lup_el_nowr
	ds_write_b128 v217, v[114:117]
	ds_write_b128 v217, v[118:121] offset:16

.Lup_el_cont:
	s_lshl_b32 s26, s21, 1
	s_add_i32 s26, s26, s43
	s_lshl_b32 s26, s26, 20
	s_lshl_b32 s27, s35, 6
	s_add_u32 s18, s52, s26
	s_addc_u32 s19, s53, 0
	s_add_u32 s18, s18, s27
	s_addc_u32 s19, s19, 0
	s_sub_u32 s18, s18, 0x80
	s_subb_u32 s19, s19, 0
	s_add_u32 s6, s18, 0x1000
	s_addc_u32 s7, s19, 0
	s_sub_i32 s66, 0x1002, s39
	s_waitcnt vmcnt(0) lgkmcnt(0)
	v_mov_b32_dpp v210, v98 row_ror:1 row_mask:0xf bank_mask:0xf
	v_mov_b32_dpp v212, v98 row_ror:2 row_mask:0xf bank_mask:0xf
	v_mov_b32_dpp v211, v99 row_ror:1 row_mask:0xf bank_mask:0xf
	v_mov_b32_dpp v213, v99 row_ror:2 row_mask:0xf bank_mask:0xf
	s_nop 1
	v_mov_b32_dpp v210, v114 row_shr:1 row_mask:0xf bank_mask:0xf
	v_mov_b32_dpp v212, v114 row_shr:2 row_mask:0xf bank_mask:0xf
	v_mov_b32_dpp v211, v115 row_shr:1 row_mask:0xf bank_mask:0xf
	v_mov_b32_dpp v213, v115 row_shr:2 row_mask:0xf bank_mask:0xf
	s_nop 1
	v_pk_mul_f32 v[210:211], v[186:187], v[210:211]
	v_pk_fma_f32 v[214:215], v[194:195], v[114:115], v[210:211]
	v_pk_fma_f32 v[214:215], v[178:179], v[212:213], v[214:215]
	v_pk_add_f32 v[214:215], v[202:203], v[214:215]
	v_mul_f32_e32 v216, 0x3d372713, v214
	v_mul_f32_e32 v216, v214, v216
	v_fma_f32 v216, v214, v216, v214
	v_mul_f32_e32 v216, 0x3f4c422a, v216
	v_mul_f32_e32 v216, 0xc038aa3b, v216
	v_exp_f32_e32 v216, v216
	s_nop 0
	v_add_f32_e32 v216, 1.0, v216
	v_rcp_f32_e32 v216, v216
	s_nop 0
	v_mul_f32_e32 v214, v214, v216
	v_mul_f32_e32 v214, v122, v214
	v_mul_f32_e32 v216, 0x3d372713, v215
	v_mul_f32_e32 v216, v215, v216
	v_fma_f32 v216, v215, v216, v215
	v_mul_f32_e32 v216, 0x3f4c422a, v216
	v_mul_f32_e32 v216, 0xc038aa3b, v216
	v_exp_f32_e32 v216, v216
	s_nop 0
	v_add_f32_e32 v216, 1.0, v216
	v_rcp_f32_e32 v216, v216
	s_nop 0
	v_mul_f32_e32 v215, v215, v216
	v_mul_f32_e32 v215, v123, v215
	v_cvt_pk_bf16_f32 v122, v214, v215
	v_mov_b32_dpp v210, v100 row_ror:1 row_mask:0xf bank_mask:0xf
	v_mov_b32_dpp v212, v100 row_ror:2 row_mask:0xf bank_mask:0xf
	v_mov_b32_dpp v211, v101 row_ror:1 row_mask:0xf bank_mask:0xf
	v_mov_b32_dpp v213, v101 row_ror:2 row_mask:0xf bank_mask:0xf
	s_nop 1
	v_mov_b32_dpp v210, v116 row_shr:1 row_mask:0xf bank_mask:0xf
	v_mov_b32_dpp v212, v116 row_shr:2 row_mask:0xf bank_mask:0xf
	v_mov_b32_dpp v211, v117 row_shr:1 row_mask:0xf bank_mask:0xf
	v_mov_b32_dpp v213, v117 row_shr:2 row_mask:0xf bank_mask:0xf
	s_nop 1
	v_pk_mul_f32 v[210:211], v[188:189], v[210:211]
	v_pk_fma_f32 v[214:215], v[196:197], v[116:117], v[210:211]
	v_pk_fma_f32 v[214:215], v[180:181], v[212:213], v[214:215]
	v_pk_add_f32 v[214:215], v[204:205], v[214:215]
	v_mul_f32_e32 v216, 0x3d372713, v214
	v_mul_f32_e32 v216, v214, v216
	v_fma_f32 v216, v214, v216, v214
	v_mul_f32_e32 v216, 0x3f4c422a, v216
	v_mul_f32_e32 v216, 0xc038aa3b, v216
	v_exp_f32_e32 v216, v216
	s_nop 0
	v_add_f32_e32 v216, 1.0, v216
	v_rcp_f32_e32 v216, v216
	s_nop 0
	v_mul_f32_e32 v214, v214, v216
	v_mul_f32_e32 v214, v124, v214
	v_mul_f32_e32 v216, 0x3d372713, v215
	v_mul_f32_e32 v216, v215, v216
	v_fma_f32 v216, v215, v216, v215
	v_mul_f32_e32 v216, 0x3f4c422a, v216
	v_mul_f32_e32 v216, 0xc038aa3b, v216
	v_exp_f32_e32 v216, v216
	s_nop 0
	v_add_f32_e32 v216, 1.0, v216
	v_rcp_f32_e32 v216, v216
	s_nop 0
	v_mul_f32_e32 v215, v215, v216
	v_mul_f32_e32 v215, v125, v215
	v_cvt_pk_bf16_f32 v123, v214, v215
	v_mov_b32_dpp v210, v102 row_ror:1 row_mask:0xf bank_mask:0xf
	v_mov_b32_dpp v212, v102 row_ror:2 row_mask:0xf bank_mask:0xf
	v_mov_b32_dpp v211, v103 row_ror:1 row_mask:0xf bank_mask:0xf
	v_mov_b32_dpp v213, v103 row_ror:2 row_mask:0xf bank_mask:0xf
	s_nop 1
	v_mov_b32_dpp v210, v118 row_shr:1 row_mask:0xf bank_mask:0xf
	v_mov_b32_dpp v212, v118 row_shr:2 row_mask:0xf bank_mask:0xf
	v_mov_b32_dpp v211, v119 row_shr:1 row_mask:0xf bank_mask:0xf
	v_mov_b32_dpp v213, v119 row_shr:2 row_mask:0xf bank_mask:0xf
	s_nop 1
	v_pk_mul_f32 v[210:211], v[190:191], v[210:211]
	v_pk_fma_f32 v[214:215], v[198:199], v[118:119], v[210:211]
	v_pk_fma_f32 v[214:215], v[182:183], v[212:213], v[214:215]
	v_pk_add_f32 v[214:215], v[206:207], v[214:215]
	v_mul_f32_e32 v216, 0x3d372713, v214
	v_mul_f32_e32 v216, v214, v216
	v_fma_f32 v216, v214, v216, v214
	v_mul_f32_e32 v216, 0x3f4c422a, v216
	v_mul_f32_e32 v216, 0xc038aa3b, v216
	v_exp_f32_e32 v216, v216
	s_nop 0
	v_add_f32_e32 v216, 1.0, v216
	v_rcp_f32_e32 v216, v216
	s_nop 0
	v_mul_f32_e32 v214, v214, v216
	v_mul_f32_e32 v214, v126, v214
	v_mul_f32_e32 v216, 0x3d372713, v215
	v_mul_f32_e32 v216, v215, v216
	v_fma_f32 v216, v215, v216, v215
	v_mul_f32_e32 v216, 0x3f4c422a, v216
	v_mul_f32_e32 v216, 0xc038aa3b, v216
	v_exp_f32_e32 v216, v216
	s_nop 0
	v_add_f32_e32 v216, 1.0, v216
	v_rcp_f32_e32 v216, v216
	s_nop 0
	v_mul_f32_e32 v215, v215, v216
	v_mul_f32_e32 v215, v127, v215
	v_cvt_pk_bf16_f32 v124, v214, v215
	v_mov_b32_dpp v210, v104 row_ror:1 row_mask:0xf bank_mask:0xf
	v_mov_b32_dpp v212, v104 row_ror:2 row_mask:0xf bank_mask:0xf
	v_mov_b32_dpp v211, v105 row_ror:1 row_mask:0xf bank_mask:0xf
	v_mov_b32_dpp v213, v105 row_ror:2 row_mask:0xf bank_mask:0xf
	s_nop 1
	v_mov_b32_dpp v210, v120 row_shr:1 row_mask:0xf bank_mask:0xf
	v_mov_b32_dpp v212, v120 row_shr:2 row_mask:0xf bank_mask:0xf
	v_mov_b32_dpp v211, v121 row_shr:1 row_mask:0xf bank_mask:0xf
	v_mov_b32_dpp v213, v121 row_shr:2 row_mask:0xf bank_mask:0xf
	s_nop 1
	v_pk_mul_f32 v[210:211], v[192:193], v[210:211]
	v_pk_fma_f32 v[214:215], v[200:201], v[120:121], v[210:211]
	v_pk_fma_f32 v[214:215], v[184:185], v[212:213], v[214:215]
	v_pk_add_f32 v[214:215], v[208:209], v[214:215]
	v_mul_f32_e32 v216, 0x3d372713, v214
	v_mul_f32_e32 v216, v214, v216
	v_fma_f32 v216, v214, v216, v214
	v_mul_f32_e32 v216, 0x3f4c422a, v216
	v_mul_f32_e32 v216, 0xc038aa3b, v216
	v_exp_f32_e32 v216, v216
	s_nop 0
	v_add_f32_e32 v216, 1.0, v216
	v_rcp_f32_e32 v216, v216
	s_nop 0
	v_mul_f32_e32 v214, v214, v216
	v_mul_f32_e32 v214, v128, v214
	v_mul_f32_e32 v216, 0x3d372713, v215
	v_mul_f32_e32 v216, v215, v216
	v_fma_f32 v216, v215, v216, v215
	v_mul_f32_e32 v216, 0x3f4c422a, v216
	v_mul_f32_e32 v216, 0xc038aa3b, v216
	v_exp_f32_e32 v216, v216
	s_nop 0
	v_add_f32_e32 v216, 1.0, v216
	v_rcp_f32_e32 v216, v216
	s_nop 0
	v_mul_f32_e32 v215, v215, v216
	v_mul_f32_e32 v215, v129, v215
	v_cvt_pk_bf16_f32 v125, v214, v215
	s_add_i32 s26, s66, -112
	v_cmp_gt_i32_e64 s[24:25], s26, v227
	s_nop 1
	s_and_saveexec_b64 s[26:27], s[24:25]
	global_store_dwordx4 v242, v[122:125], s[6:7] offset:3072
	s_mov_b64 exec, s[26:27]
	s_nop 4
	v_mov_b32_dpp v210, v82 row_ror:1 row_mask:0xf bank_mask:0xf
	v_mov_b32_dpp v212, v82 row_ror:2 row_mask:0xf bank_mask:0xf
	v_mov_b32_dpp v211, v83 row_ror:1 row_mask:0xf bank_mask:0xf
	v_mov_b32_dpp v213, v83 row_ror:2 row_mask:0xf bank_mask:0xf
	s_nop 1
	v_mov_b32_dpp v210, v98 row_shr:1 row_mask:0xf bank_mask:0xf
	v_mov_b32_dpp v212, v98 row_shr:2 row_mask:0xf bank_mask:0xf
	v_mov_b32_dpp v211, v99 row_shr:1 row_mask:0xf bank_mask:0xf
	v_mov_b32_dpp v213, v99 row_shr:2 row_mask:0xf bank_mask:0xf
	s_nop 1
	v_pk_mul_f32 v[210:211], v[186:187], v[210:211]
	v_pk_fma_f32 v[214:215], v[194:195], v[98:99], v[210:211]
	v_pk_fma_f32 v[214:215], v[178:179], v[212:213], v[214:215]
	v_pk_add_f32 v[214:215], v[202:203], v[214:215]
	v_mul_f32_e32 v216, 0x3d372713, v214
	v_mul_f32_e32 v216, v214, v216
	v_fma_f32 v216, v214, v216, v214
	v_mul_f32_e32 v216, 0x3f4c422a, v216
	v_mul_f32_e32 v216, 0xc038aa3b, v216
	v_exp_f32_e32 v216, v216
	s_nop 0
	v_add_f32_e32 v216, 1.0, v216
	v_rcp_f32_e32 v216, v216
	s_nop 0
	v_mul_f32_e32 v214, v214, v216
	v_mul_f32_e32 v214, v106, v214
	v_mul_f32_e32 v216, 0x3d372713, v215
	v_mul_f32_e32 v216, v215, v216
	v_fma_f32 v216, v215, v216, v215
	v_mul_f32_e32 v216, 0x3f4c422a, v216
	v_mul_f32_e32 v216, 0xc038aa3b, v216
	v_exp_f32_e32 v216, v216
	s_nop 0
	v_add_f32_e32 v216, 1.0, v216
	v_rcp_f32_e32 v216, v216
	s_nop 0
	v_mul_f32_e32 v215, v215, v216
	v_mul_f32_e32 v215, v107, v215
	v_cvt_pk_bf16_f32 v106, v214, v215
	v_mov_b32_dpp v210, v84 row_ror:1 row_mask:0xf bank_mask:0xf
	v_mov_b32_dpp v212, v84 row_ror:2 row_mask:0xf bank_mask:0xf
	v_mov_b32_dpp v211, v85 row_ror:1 row_mask:0xf bank_mask:0xf
	v_mov_b32_dpp v213, v85 row_ror:2 row_mask:0xf bank_mask:0xf
	s_nop 1
	v_mov_b32_dpp v210, v100 row_shr:1 row_mask:0xf bank_mask:0xf
	v_mov_b32_dpp v212, v100 row_shr:2 row_mask:0xf bank_mask:0xf
	v_mov_b32_dpp v211, v101 row_shr:1 row_mask:0xf bank_mask:0xf
	v_mov_b32_dpp v213, v101 row_shr:2 row_mask:0xf bank_mask:0xf
	s_nop 1
	v_pk_mul_f32 v[210:211], v[188:189], v[210:211]
	v_pk_fma_f32 v[214:215], v[196:197], v[100:101], v[210:211]
	v_pk_fma_f32 v[214:215], v[180:181], v[212:213], v[214:215]
	v_pk_add_f32 v[214:215], v[204:205], v[214:215]
	v_mul_f32_e32 v216, 0x3d372713, v214
	v_mul_f32_e32 v216, v214, v216
	v_fma_f32 v216, v214, v216, v214
	v_mul_f32_e32 v216, 0x3f4c422a, v216
	v_mul_f32_e32 v216, 0xc038aa3b, v216
	v_exp_f32_e32 v216, v216
	s_nop 0
	v_add_f32_e32 v216, 1.0, v216
	v_rcp_f32_e32 v216, v216
	s_nop 0
	v_mul_f32_e32 v214, v214, v216
	v_mul_f32_e32 v214, v108, v214
	v_mul_f32_e32 v216, 0x3d372713, v215
	v_mul_f32_e32 v216, v215, v216
	v_fma_f32 v216, v215, v216, v215
	v_mul_f32_e32 v216, 0x3f4c422a, v216
	v_mul_f32_e32 v216, 0xc038aa3b, v216
	v_exp_f32_e32 v216, v216
	s_nop 0
	v_add_f32_e32 v216, 1.0, v216
	v_rcp_f32_e32 v216, v216
	s_nop 0
	v_mul_f32_e32 v215, v215, v216
	v_mul_f32_e32 v215, v109, v215
	v_cvt_pk_bf16_f32 v107, v214, v215
	v_mov_b32_dpp v210, v86 row_ror:1 row_mask:0xf bank_mask:0xf
	v_mov_b32_dpp v212, v86 row_ror:2 row_mask:0xf bank_mask:0xf
	v_mov_b32_dpp v211, v87 row_ror:1 row_mask:0xf bank_mask:0xf
	v_mov_b32_dpp v213, v87 row_ror:2 row_mask:0xf bank_mask:0xf
	s_nop 1
	v_mov_b32_dpp v210, v102 row_shr:1 row_mask:0xf bank_mask:0xf
	v_mov_b32_dpp v212, v102 row_shr:2 row_mask:0xf bank_mask:0xf
	v_mov_b32_dpp v211, v103 row_shr:1 row_mask:0xf bank_mask:0xf
	v_mov_b32_dpp v213, v103 row_shr:2 row_mask:0xf bank_mask:0xf
	s_nop 1
	v_pk_mul_f32 v[210:211], v[190:191], v[210:211]
	v_pk_fma_f32 v[214:215], v[198:199], v[102:103], v[210:211]
	v_pk_fma_f32 v[214:215], v[182:183], v[212:213], v[214:215]
	v_pk_add_f32 v[214:215], v[206:207], v[214:215]
	v_mul_f32_e32 v216, 0x3d372713, v214
	v_mul_f32_e32 v216, v214, v216
	v_fma_f32 v216, v214, v216, v214
	v_mul_f32_e32 v216, 0x3f4c422a, v216
	v_mul_f32_e32 v216, 0xc038aa3b, v216
	v_exp_f32_e32 v216, v216
	s_nop 0
	v_add_f32_e32 v216, 1.0, v216
	v_rcp_f32_e32 v216, v216
	s_nop 0
	v_mul_f32_e32 v214, v214, v216
	v_mul_f32_e32 v214, v110, v214
	v_mul_f32_e32 v216, 0x3d372713, v215
	v_mul_f32_e32 v216, v215, v216
	v_fma_f32 v216, v215, v216, v215
	v_mul_f32_e32 v216, 0x3f4c422a, v216
	v_mul_f32_e32 v216, 0xc038aa3b, v216
	v_exp_f32_e32 v216, v216
	s_nop 0
	v_add_f32_e32 v216, 1.0, v216
	v_rcp_f32_e32 v216, v216
	s_nop 0
	v_mul_f32_e32 v215, v215, v216
	v_mul_f32_e32 v215, v111, v215
	v_cvt_pk_bf16_f32 v108, v214, v215
	v_mov_b32_dpp v210, v88 row_ror:1 row_mask:0xf bank_mask:0xf
	v_mov_b32_dpp v212, v88 row_ror:2 row_mask:0xf bank_mask:0xf
	v_mov_b32_dpp v211, v89 row_ror:1 row_mask:0xf bank_mask:0xf
	v_mov_b32_dpp v213, v89 row_ror:2 row_mask:0xf bank_mask:0xf
	s_nop 1
	v_mov_b32_dpp v210, v104 row_shr:1 row_mask:0xf bank_mask:0xf
	v_mov_b32_dpp v212, v104 row_shr:2 row_mask:0xf bank_mask:0xf
	v_mov_b32_dpp v211, v105 row_shr:1 row_mask:0xf bank_mask:0xf
	v_mov_b32_dpp v213, v105 row_shr:2 row_mask:0xf bank_mask:0xf
	s_nop 1
	v_pk_mul_f32 v[210:211], v[192:193], v[210:211]
	v_pk_fma_f32 v[214:215], v[200:201], v[104:105], v[210:211]
	v_pk_fma_f32 v[214:215], v[184:185], v[212:213], v[214:215]
	v_pk_add_f32 v[214:215], v[208:209], v[214:215]
	v_mul_f32_e32 v216, 0x3d372713, v214
	v_mul_f32_e32 v216, v214, v216
	v_fma_f32 v216, v214, v216, v214
	v_mul_f32_e32 v216, 0x3f4c422a, v216
	v_mul_f32_e32 v216, 0xc038aa3b, v216
	v_exp_f32_e32 v216, v216
	s_nop 0
	v_add_f32_e32 v216, 1.0, v216
	v_rcp_f32_e32 v216, v216
	s_nop 0
	v_mul_f32_e32 v214, v214, v216
	v_mul_f32_e32 v214, v112, v214
	v_mul_f32_e32 v216, 0x3d372713, v215
	v_mul_f32_e32 v216, v215, v216
	v_fma_f32 v216, v215, v216, v215
	v_mul_f32_e32 v216, 0x3f4c422a, v216
	v_mul_f32_e32 v216, 0xc038aa3b, v216
	v_exp_f32_e32 v216, v216
	s_nop 0
	v_add_f32_e32 v216, 1.0, v216
	v_rcp_f32_e32 v216, v216
	s_nop 0
	v_mul_f32_e32 v215, v215, v216
	v_mul_f32_e32 v215, v113, v215
	v_cvt_pk_bf16_f32 v109, v214, v215
	s_add_i32 s26, s66, -96
	v_cmp_gt_i32_e64 s[24:25], s26, v227
	s_nop 1
	s_and_saveexec_b64 s[26:27], s[24:25]
	global_store_dwordx4 v242, v[106:109], s[6:7] offset:2048
	s_mov_b64 exec, s[26:27]
	s_nop 4
	v_mov_b32_dpp v210, v66 row_ror:1 row_mask:0xf bank_mask:0xf
	v_mov_b32_dpp v212, v66 row_ror:2 row_mask:0xf bank_mask:0xf
	v_mov_b32_dpp v211, v67 row_ror:1 row_mask:0xf bank_mask:0xf
	v_mov_b32_dpp v213, v67 row_ror:2 row_mask:0xf bank_mask:0xf
	s_nop 1
	v_mov_b32_dpp v210, v82 row_shr:1 row_mask:0xf bank_mask:0xf
	v_mov_b32_dpp v212, v82 row_shr:2 row_mask:0xf bank_mask:0xf
	v_mov_b32_dpp v211, v83 row_shr:1 row_mask:0xf bank_mask:0xf
	v_mov_b32_dpp v213, v83 row_shr:2 row_mask:0xf bank_mask:0xf
	s_nop 1
	v_pk_mul_f32 v[210:211], v[186:187], v[210:211]
	v_pk_fma_f32 v[214:215], v[194:195], v[82:83], v[210:211]
	v_pk_fma_f32 v[214:215], v[178:179], v[212:213], v[214:215]
	v_pk_add_f32 v[214:215], v[202:203], v[214:215]
	v_mul_f32_e32 v216, 0x3d372713, v214
	v_mul_f32_e32 v216, v214, v216
	v_fma_f32 v216, v214, v216, v214
	v_mul_f32_e32 v216, 0x3f4c422a, v216
	v_mul_f32_e32 v216, 0xc038aa3b, v216
	v_exp_f32_e32 v216, v216
	s_nop 0
	v_add_f32_e32 v216, 1.0, v216
	v_rcp_f32_e32 v216, v216
	s_nop 0
	v_mul_f32_e32 v214, v214, v216
	v_mul_f32_e32 v214, v90, v214
	v_mul_f32_e32 v216, 0x3d372713, v215
	v_mul_f32_e32 v216, v215, v216
	v_fma_f32 v216, v215, v216, v215
	v_mul_f32_e32 v216, 0x3f4c422a, v216
	v_mul_f32_e32 v216, 0xc038aa3b, v216
	v_exp_f32_e32 v216, v216
	s_nop 0
	v_add_f32_e32 v216, 1.0, v216
	v_rcp_f32_e32 v216, v216
	s_nop 0
	v_mul_f32_e32 v215, v215, v216
	v_mul_f32_e32 v215, v91, v215
	v_cvt_pk_bf16_f32 v90, v214, v215
	v_mov_b32_dpp v210, v68 row_ror:1 row_mask:0xf bank_mask:0xf
	v_mov_b32_dpp v212, v68 row_ror:2 row_mask:0xf bank_mask:0xf
	v_mov_b32_dpp v211, v69 row_ror:1 row_mask:0xf bank_mask:0xf
	v_mov_b32_dpp v213, v69 row_ror:2 row_mask:0xf bank_mask:0xf
	s_nop 1
	v_mov_b32_dpp v210, v84 row_shr:1 row_mask:0xf bank_mask:0xf
	v_mov_b32_dpp v212, v84 row_shr:2 row_mask:0xf bank_mask:0xf
	v_mov_b32_dpp v211, v85 row_shr:1 row_mask:0xf bank_mask:0xf
	v_mov_b32_dpp v213, v85 row_shr:2 row_mask:0xf bank_mask:0xf
	s_nop 1
	v_pk_mul_f32 v[210:211], v[188:189], v[210:211]
	v_pk_fma_f32 v[214:215], v[196:197], v[84:85], v[210:211]
	v_pk_fma_f32 v[214:215], v[180:181], v[212:213], v[214:215]
	v_pk_add_f32 v[214:215], v[204:205], v[214:215]
	v_mul_f32_e32 v216, 0x3d372713, v214
	v_mul_f32_e32 v216, v214, v216
	v_fma_f32 v216, v214, v216, v214
	v_mul_f32_e32 v216, 0x3f4c422a, v216
	v_mul_f32_e32 v216, 0xc038aa3b, v216
	v_exp_f32_e32 v216, v216
	s_nop 0
	v_add_f32_e32 v216, 1.0, v216
	v_rcp_f32_e32 v216, v216
	s_nop 0
	v_mul_f32_e32 v214, v214, v216
	v_mul_f32_e32 v214, v92, v214
	v_mul_f32_e32 v216, 0x3d372713, v215
	v_mul_f32_e32 v216, v215, v216
	v_fma_f32 v216, v215, v216, v215
	v_mul_f32_e32 v216, 0x3f4c422a, v216
	v_mul_f32_e32 v216, 0xc038aa3b, v216
	v_exp_f32_e32 v216, v216
	s_nop 0
	v_add_f32_e32 v216, 1.0, v216
	v_rcp_f32_e32 v216, v216
	s_nop 0
	v_mul_f32_e32 v215, v215, v216
	v_mul_f32_e32 v215, v93, v215
	v_cvt_pk_bf16_f32 v91, v214, v215
	v_mov_b32_dpp v210, v70 row_ror:1 row_mask:0xf bank_mask:0xf
	v_mov_b32_dpp v212, v70 row_ror:2 row_mask:0xf bank_mask:0xf
	v_mov_b32_dpp v211, v71 row_ror:1 row_mask:0xf bank_mask:0xf
	v_mov_b32_dpp v213, v71 row_ror:2 row_mask:0xf bank_mask:0xf
	s_nop 1
	v_mov_b32_dpp v210, v86 row_shr:1 row_mask:0xf bank_mask:0xf
	v_mov_b32_dpp v212, v86 row_shr:2 row_mask:0xf bank_mask:0xf
	v_mov_b32_dpp v211, v87 row_shr:1 row_mask:0xf bank_mask:0xf
	v_mov_b32_dpp v213, v87 row_shr:2 row_mask:0xf bank_mask:0xf
	s_nop 1
	v_pk_mul_f32 v[210:211], v[190:191], v[210:211]
	v_pk_fma_f32 v[214:215], v[198:199], v[86:87], v[210:211]
	v_pk_fma_f32 v[214:215], v[182:183], v[212:213], v[214:215]
	v_pk_add_f32 v[214:215], v[206:207], v[214:215]
	v_mul_f32_e32 v216, 0x3d372713, v214
	v_mul_f32_e32 v216, v214, v216
	v_fma_f32 v216, v214, v216, v214
	v_mul_f32_e32 v216, 0x3f4c422a, v216
	v_mul_f32_e32 v216, 0xc038aa3b, v216
	v_exp_f32_e32 v216, v216
	s_nop 0
	v_add_f32_e32 v216, 1.0, v216
	v_rcp_f32_e32 v216, v216
	s_nop 0
	v_mul_f32_e32 v214, v214, v216
	v_mul_f32_e32 v214, v94, v214
	v_mul_f32_e32 v216, 0x3d372713, v215
	v_mul_f32_e32 v216, v215, v216
	v_fma_f32 v216, v215, v216, v215
	v_mul_f32_e32 v216, 0x3f4c422a, v216
	v_mul_f32_e32 v216, 0xc038aa3b, v216
	v_exp_f32_e32 v216, v216
	s_nop 0
	v_add_f32_e32 v216, 1.0, v216
	v_rcp_f32_e32 v216, v216
	s_nop 0
	v_mul_f32_e32 v215, v215, v216
	v_mul_f32_e32 v215, v95, v215
	v_cvt_pk_bf16_f32 v92, v214, v215
	v_mov_b32_dpp v210, v72 row_ror:1 row_mask:0xf bank_mask:0xf
	v_mov_b32_dpp v212, v72 row_ror:2 row_mask:0xf bank_mask:0xf
	v_mov_b32_dpp v211, v73 row_ror:1 row_mask:0xf bank_mask:0xf
	v_mov_b32_dpp v213, v73 row_ror:2 row_mask:0xf bank_mask:0xf
	s_nop 1
	v_mov_b32_dpp v210, v88 row_shr:1 row_mask:0xf bank_mask:0xf
	v_mov_b32_dpp v212, v88 row_shr:2 row_mask:0xf bank_mask:0xf
	v_mov_b32_dpp v211, v89 row_shr:1 row_mask:0xf bank_mask:0xf
	v_mov_b32_dpp v213, v89 row_shr:2 row_mask:0xf bank_mask:0xf
	s_nop 1
	v_pk_mul_f32 v[210:211], v[192:193], v[210:211]
	v_pk_fma_f32 v[214:215], v[200:201], v[88:89], v[210:211]
	v_pk_fma_f32 v[214:215], v[184:185], v[212:213], v[214:215]
	v_pk_add_f32 v[214:215], v[208:209], v[214:215]
	v_mul_f32_e32 v216, 0x3d372713, v214
	v_mul_f32_e32 v216, v214, v216
	v_fma_f32 v216, v214, v216, v214
	v_mul_f32_e32 v216, 0x3f4c422a, v216
	v_mul_f32_e32 v216, 0xc038aa3b, v216
	v_exp_f32_e32 v216, v216
	s_nop 0
	v_add_f32_e32 v216, 1.0, v216
	v_rcp_f32_e32 v216, v216
	s_nop 0
	v_mul_f32_e32 v214, v214, v216
	v_mul_f32_e32 v214, v96, v214
	v_mul_f32_e32 v216, 0x3d372713, v215
	v_mul_f32_e32 v216, v215, v216
	v_fma_f32 v216, v215, v216, v215
	v_mul_f32_e32 v216, 0x3f4c422a, v216
	v_mul_f32_e32 v216, 0xc038aa3b, v216
	v_exp_f32_e32 v216, v216
	s_nop 0
	v_add_f32_e32 v216, 1.0, v216
	v_rcp_f32_e32 v216, v216
	s_nop 0
	v_mul_f32_e32 v215, v215, v216
	v_mul_f32_e32 v215, v97, v215
	v_cvt_pk_bf16_f32 v93, v214, v215
	s_add_i32 s26, s66, -80
	v_cmp_gt_i32_e64 s[24:25], s26, v227
	s_nop 1
	s_and_saveexec_b64 s[26:27], s[24:25]
	global_store_dwordx4 v242, v[90:93], s[6:7] offset:1024
	s_mov_b64 exec, s[26:27]
	s_nop 4
	v_mov_b32_dpp v210, v50 row_ror:1 row_mask:0xf bank_mask:0xf
	v_mov_b32_dpp v212, v50 row_ror:2 row_mask:0xf bank_mask:0xf
	v_mov_b32_dpp v211, v51 row_ror:1 row_mask:0xf bank_mask:0xf
	v_mov_b32_dpp v213, v51 row_ror:2 row_mask:0xf bank_mask:0xf
	s_nop 1
	v_mov_b32_dpp v210, v66 row_shr:1 row_mask:0xf bank_mask:0xf
	v_mov_b32_dpp v212, v66 row_shr:2 row_mask:0xf bank_mask:0xf
	v_mov_b32_dpp v211, v67 row_shr:1 row_mask:0xf bank_mask:0xf
	v_mov_b32_dpp v213, v67 row_shr:2 row_mask:0xf bank_mask:0xf
	s_nop 1
	v_pk_mul_f32 v[210:211], v[186:187], v[210:211]
	v_pk_fma_f32 v[214:215], v[194:195], v[66:67], v[210:211]
	v_pk_fma_f32 v[214:215], v[178:179], v[212:213], v[214:215]
	v_pk_add_f32 v[214:215], v[202:203], v[214:215]
	v_mul_f32_e32 v216, 0x3d372713, v214
	v_mul_f32_e32 v216, v214, v216
	v_fma_f32 v216, v214, v216, v214
	v_mul_f32_e32 v216, 0x3f4c422a, v216
	v_mul_f32_e32 v216, 0xc038aa3b, v216
	v_exp_f32_e32 v216, v216
	s_nop 0
	v_add_f32_e32 v216, 1.0, v216
	v_rcp_f32_e32 v216, v216
	s_nop 0
	v_mul_f32_e32 v214, v214, v216
	v_mul_f32_e32 v214, v74, v214
	v_mul_f32_e32 v216, 0x3d372713, v215
	v_mul_f32_e32 v216, v215, v216
	v_fma_f32 v216, v215, v216, v215
	v_mul_f32_e32 v216, 0x3f4c422a, v216
	v_mul_f32_e32 v216, 0xc038aa3b, v216
	v_exp_f32_e32 v216, v216
	s_nop 0
	v_add_f32_e32 v216, 1.0, v216
	v_rcp_f32_e32 v216, v216
	s_nop 0
	v_mul_f32_e32 v215, v215, v216
	v_mul_f32_e32 v215, v75, v215
	v_cvt_pk_bf16_f32 v74, v214, v215
	v_mov_b32_dpp v210, v52 row_ror:1 row_mask:0xf bank_mask:0xf
	v_mov_b32_dpp v212, v52 row_ror:2 row_mask:0xf bank_mask:0xf
	v_mov_b32_dpp v211, v53 row_ror:1 row_mask:0xf bank_mask:0xf
	v_mov_b32_dpp v213, v53 row_ror:2 row_mask:0xf bank_mask:0xf
	s_nop 1
	v_mov_b32_dpp v210, v68 row_shr:1 row_mask:0xf bank_mask:0xf
	v_mov_b32_dpp v212, v68 row_shr:2 row_mask:0xf bank_mask:0xf
	v_mov_b32_dpp v211, v69 row_shr:1 row_mask:0xf bank_mask:0xf
	v_mov_b32_dpp v213, v69 row_shr:2 row_mask:0xf bank_mask:0xf
	s_nop 1
	v_pk_mul_f32 v[210:211], v[188:189], v[210:211]
	v_pk_fma_f32 v[214:215], v[196:197], v[68:69], v[210:211]
	v_pk_fma_f32 v[214:215], v[180:181], v[212:213], v[214:215]
	v_pk_add_f32 v[214:215], v[204:205], v[214:215]
	v_mul_f32_e32 v216, 0x3d372713, v214
	v_mul_f32_e32 v216, v214, v216
	v_fma_f32 v216, v214, v216, v214
	v_mul_f32_e32 v216, 0x3f4c422a, v216
	v_mul_f32_e32 v216, 0xc038aa3b, v216
	v_exp_f32_e32 v216, v216
	s_nop 0
	v_add_f32_e32 v216, 1.0, v216
	v_rcp_f32_e32 v216, v216
	s_nop 0
	v_mul_f32_e32 v214, v214, v216
	v_mul_f32_e32 v214, v76, v214
	v_mul_f32_e32 v216, 0x3d372713, v215
	v_mul_f32_e32 v216, v215, v216
	v_fma_f32 v216, v215, v216, v215
	v_mul_f32_e32 v216, 0x3f4c422a, v216
	v_mul_f32_e32 v216, 0xc038aa3b, v216
	v_exp_f32_e32 v216, v216
	s_nop 0
	v_add_f32_e32 v216, 1.0, v216
	v_rcp_f32_e32 v216, v216
	s_nop 0
	v_mul_f32_e32 v215, v215, v216
	v_mul_f32_e32 v215, v77, v215
	v_cvt_pk_bf16_f32 v75, v214, v215
	v_mov_b32_dpp v210, v54 row_ror:1 row_mask:0xf bank_mask:0xf
	v_mov_b32_dpp v212, v54 row_ror:2 row_mask:0xf bank_mask:0xf
	v_mov_b32_dpp v211, v55 row_ror:1 row_mask:0xf bank_mask:0xf
	v_mov_b32_dpp v213, v55 row_ror:2 row_mask:0xf bank_mask:0xf
	s_nop 1
	v_mov_b32_dpp v210, v70 row_shr:1 row_mask:0xf bank_mask:0xf
	v_mov_b32_dpp v212, v70 row_shr:2 row_mask:0xf bank_mask:0xf
	v_mov_b32_dpp v211, v71 row_shr:1 row_mask:0xf bank_mask:0xf
	v_mov_b32_dpp v213, v71 row_shr:2 row_mask:0xf bank_mask:0xf
	s_nop 1
	v_pk_mul_f32 v[210:211], v[190:191], v[210:211]
	v_pk_fma_f32 v[214:215], v[198:199], v[70:71], v[210:211]
	v_pk_fma_f32 v[214:215], v[182:183], v[212:213], v[214:215]
	v_pk_add_f32 v[214:215], v[206:207], v[214:215]
	v_mul_f32_e32 v216, 0x3d372713, v214
	v_mul_f32_e32 v216, v214, v216
	v_fma_f32 v216, v214, v216, v214
	v_mul_f32_e32 v216, 0x3f4c422a, v216
	v_mul_f32_e32 v216, 0xc038aa3b, v216
	v_exp_f32_e32 v216, v216
	s_nop 0
	v_add_f32_e32 v216, 1.0, v216
	v_rcp_f32_e32 v216, v216
	s_nop 0
	v_mul_f32_e32 v214, v214, v216
	v_mul_f32_e32 v214, v78, v214
	v_mul_f32_e32 v216, 0x3d372713, v215
	v_mul_f32_e32 v216, v215, v216
	v_fma_f32 v216, v215, v216, v215
	v_mul_f32_e32 v216, 0x3f4c422a, v216
	v_mul_f32_e32 v216, 0xc038aa3b, v216
	v_exp_f32_e32 v216, v216
	s_nop 0
	v_add_f32_e32 v216, 1.0, v216
	v_rcp_f32_e32 v216, v216
	s_nop 0
	v_mul_f32_e32 v215, v215, v216
	v_mul_f32_e32 v215, v79, v215
	v_cvt_pk_bf16_f32 v76, v214, v215
	v_mov_b32_dpp v210, v56 row_ror:1 row_mask:0xf bank_mask:0xf
	v_mov_b32_dpp v212, v56 row_ror:2 row_mask:0xf bank_mask:0xf
	v_mov_b32_dpp v211, v57 row_ror:1 row_mask:0xf bank_mask:0xf
	v_mov_b32_dpp v213, v57 row_ror:2 row_mask:0xf bank_mask:0xf
	s_nop 1
	v_mov_b32_dpp v210, v72 row_shr:1 row_mask:0xf bank_mask:0xf
	v_mov_b32_dpp v212, v72 row_shr:2 row_mask:0xf bank_mask:0xf
	v_mov_b32_dpp v211, v73 row_shr:1 row_mask:0xf bank_mask:0xf
	v_mov_b32_dpp v213, v73 row_shr:2 row_mask:0xf bank_mask:0xf
	s_nop 1
	v_pk_mul_f32 v[210:211], v[192:193], v[210:211]
	v_pk_fma_f32 v[214:215], v[200:201], v[72:73], v[210:211]
	v_pk_fma_f32 v[214:215], v[184:185], v[212:213], v[214:215]
	v_pk_add_f32 v[214:215], v[208:209], v[214:215]
	v_mul_f32_e32 v216, 0x3d372713, v214
	v_mul_f32_e32 v216, v214, v216
	v_fma_f32 v216, v214, v216, v214
	v_mul_f32_e32 v216, 0x3f4c422a, v216
	v_mul_f32_e32 v216, 0xc038aa3b, v216
	v_exp_f32_e32 v216, v216
	s_nop 0
	v_add_f32_e32 v216, 1.0, v216
	v_rcp_f32_e32 v216, v216
	s_nop 0
	v_mul_f32_e32 v214, v214, v216
	v_mul_f32_e32 v214, v80, v214
	v_mul_f32_e32 v216, 0x3d372713, v215
	v_mul_f32_e32 v216, v215, v216
	v_fma_f32 v216, v215, v216, v215
	v_mul_f32_e32 v216, 0x3f4c422a, v216
	v_mul_f32_e32 v216, 0xc038aa3b, v216
	v_exp_f32_e32 v216, v216
	s_nop 0
	v_add_f32_e32 v216, 1.0, v216
	v_rcp_f32_e32 v216, v216
	s_nop 0
	v_mul_f32_e32 v215, v215, v216
	v_mul_f32_e32 v215, v81, v215
	v_cvt_pk_bf16_f32 v77, v214, v215
	s_add_i32 s26, s66, -64
	v_cmp_gt_i32_e64 s[24:25], s26, v227
	s_nop 1
	s_and_saveexec_b64 s[26:27], s[24:25]
	global_store_dwordx4 v242, v[74:77], s[6:7]
	s_mov_b64 exec, s[26:27]
	s_nop 4
	v_mov_b32_dpp v210, v34 row_ror:1 row_mask:0xf bank_mask:0xf
	v_mov_b32_dpp v212, v34 row_ror:2 row_mask:0xf bank_mask:0xf
	v_mov_b32_dpp v211, v35 row_ror:1 row_mask:0xf bank_mask:0xf
	v_mov_b32_dpp v213, v35 row_ror:2 row_mask:0xf bank_mask:0xf
	s_nop 1
	v_mov_b32_dpp v210, v50 row_shr:1 row_mask:0xf bank_mask:0xf
	v_mov_b32_dpp v212, v50 row_shr:2 row_mask:0xf bank_mask:0xf
	v_mov_b32_dpp v211, v51 row_shr:1 row_mask:0xf bank_mask:0xf
	v_mov_b32_dpp v213, v51 row_shr:2 row_mask:0xf bank_mask:0xf
	s_nop 1
	v_pk_mul_f32 v[210:211], v[186:187], v[210:211]
	v_pk_fma_f32 v[214:215], v[194:195], v[50:51], v[210:211]
	v_pk_fma_f32 v[214:215], v[178:179], v[212:213], v[214:215]
	v_pk_add_f32 v[214:215], v[202:203], v[214:215]
	v_mul_f32_e32 v216, 0x3d372713, v214
	v_mul_f32_e32 v216, v214, v216
	v_fma_f32 v216, v214, v216, v214
	v_mul_f32_e32 v216, 0x3f4c422a, v216
	v_mul_f32_e32 v216, 0xc038aa3b, v216
	v_exp_f32_e32 v216, v216
	s_nop 0
	v_add_f32_e32 v216, 1.0, v216
	v_rcp_f32_e32 v216, v216
	s_nop 0
	v_mul_f32_e32 v214, v214, v216
	v_mul_f32_e32 v214, v58, v214
	v_mul_f32_e32 v216, 0x3d372713, v215
	v_mul_f32_e32 v216, v215, v216
	v_fma_f32 v216, v215, v216, v215
	v_mul_f32_e32 v216, 0x3f4c422a, v216
	v_mul_f32_e32 v216, 0xc038aa3b, v216
	v_exp_f32_e32 v216, v216
	s_nop 0
	v_add_f32_e32 v216, 1.0, v216
	v_rcp_f32_e32 v216, v216
	s_nop 0
	v_mul_f32_e32 v215, v215, v216
	v_mul_f32_e32 v215, v59, v215
	v_cvt_pk_bf16_f32 v58, v214, v215
	v_mov_b32_dpp v210, v36 row_ror:1 row_mask:0xf bank_mask:0xf
	v_mov_b32_dpp v212, v36 row_ror:2 row_mask:0xf bank_mask:0xf
	v_mov_b32_dpp v211, v37 row_ror:1 row_mask:0xf bank_mask:0xf
	v_mov_b32_dpp v213, v37 row_ror:2 row_mask:0xf bank_mask:0xf
	s_nop 1
	v_mov_b32_dpp v210, v52 row_shr:1 row_mask:0xf bank_mask:0xf
	v_mov_b32_dpp v212, v52 row_shr:2 row_mask:0xf bank_mask:0xf
	v_mov_b32_dpp v211, v53 row_shr:1 row_mask:0xf bank_mask:0xf
	v_mov_b32_dpp v213, v53 row_shr:2 row_mask:0xf bank_mask:0xf
	s_nop 1
	v_pk_mul_f32 v[210:211], v[188:189], v[210:211]
	v_pk_fma_f32 v[214:215], v[196:197], v[52:53], v[210:211]
	v_pk_fma_f32 v[214:215], v[180:181], v[212:213], v[214:215]
	v_pk_add_f32 v[214:215], v[204:205], v[214:215]
	v_mul_f32_e32 v216, 0x3d372713, v214
	v_mul_f32_e32 v216, v214, v216
	v_fma_f32 v216, v214, v216, v214
	v_mul_f32_e32 v216, 0x3f4c422a, v216
	v_mul_f32_e32 v216, 0xc038aa3b, v216
	v_exp_f32_e32 v216, v216
	s_nop 0
	v_add_f32_e32 v216, 1.0, v216
	v_rcp_f32_e32 v216, v216
	s_nop 0
	v_mul_f32_e32 v214, v214, v216
	v_mul_f32_e32 v214, v60, v214
	v_mul_f32_e32 v216, 0x3d372713, v215
	v_mul_f32_e32 v216, v215, v216
	v_fma_f32 v216, v215, v216, v215
	v_mul_f32_e32 v216, 0x3f4c422a, v216
	v_mul_f32_e32 v216, 0xc038aa3b, v216
	v_exp_f32_e32 v216, v216
	s_nop 0
	v_add_f32_e32 v216, 1.0, v216
	v_rcp_f32_e32 v216, v216
	s_nop 0
	v_mul_f32_e32 v215, v215, v216
	v_mul_f32_e32 v215, v61, v215
	v_cvt_pk_bf16_f32 v59, v214, v215
	v_mov_b32_dpp v210, v38 row_ror:1 row_mask:0xf bank_mask:0xf
	v_mov_b32_dpp v212, v38 row_ror:2 row_mask:0xf bank_mask:0xf
	v_mov_b32_dpp v211, v39 row_ror:1 row_mask:0xf bank_mask:0xf
	v_mov_b32_dpp v213, v39 row_ror:2 row_mask:0xf bank_mask:0xf
	s_nop 1
	v_mov_b32_dpp v210, v54 row_shr:1 row_mask:0xf bank_mask:0xf
	v_mov_b32_dpp v212, v54 row_shr:2 row_mask:0xf bank_mask:0xf
	v_mov_b32_dpp v211, v55 row_shr:1 row_mask:0xf bank_mask:0xf
	v_mov_b32_dpp v213, v55 row_shr:2 row_mask:0xf bank_mask:0xf
	s_nop 1
	v_pk_mul_f32 v[210:211], v[190:191], v[210:211]
	v_pk_fma_f32 v[214:215], v[198:199], v[54:55], v[210:211]
	v_pk_fma_f32 v[214:215], v[182:183], v[212:213], v[214:215]
	v_pk_add_f32 v[214:215], v[206:207], v[214:215]
	v_mul_f32_e32 v216, 0x3d372713, v214
	v_mul_f32_e32 v216, v214, v216
	v_fma_f32 v216, v214, v216, v214
	v_mul_f32_e32 v216, 0x3f4c422a, v216
	v_mul_f32_e32 v216, 0xc038aa3b, v216
	v_exp_f32_e32 v216, v216
	s_nop 0
	v_add_f32_e32 v216, 1.0, v216
	v_rcp_f32_e32 v216, v216
	s_nop 0
	v_mul_f32_e32 v214, v214, v216
	v_mul_f32_e32 v214, v62, v214
	v_mul_f32_e32 v216, 0x3d372713, v215
	v_mul_f32_e32 v216, v215, v216
	v_fma_f32 v216, v215, v216, v215
	v_mul_f32_e32 v216, 0x3f4c422a, v216
	v_mul_f32_e32 v216, 0xc038aa3b, v216
	v_exp_f32_e32 v216, v216
	s_nop 0
	v_add_f32_e32 v216, 1.0, v216
	v_rcp_f32_e32 v216, v216
	s_nop 0
	v_mul_f32_e32 v215, v215, v216
	v_mul_f32_e32 v215, v63, v215
	v_cvt_pk_bf16_f32 v60, v214, v215
	v_mov_b32_dpp v210, v40 row_ror:1 row_mask:0xf bank_mask:0xf
	v_mov_b32_dpp v212, v40 row_ror:2 row_mask:0xf bank_mask:0xf
	v_mov_b32_dpp v211, v41 row_ror:1 row_mask:0xf bank_mask:0xf
	v_mov_b32_dpp v213, v41 row_ror:2 row_mask:0xf bank_mask:0xf
	s_nop 1
	v_mov_b32_dpp v210, v56 row_shr:1 row_mask:0xf bank_mask:0xf
	v_mov_b32_dpp v212, v56 row_shr:2 row_mask:0xf bank_mask:0xf
	v_mov_b32_dpp v211, v57 row_shr:1 row_mask:0xf bank_mask:0xf
	v_mov_b32_dpp v213, v57 row_shr:2 row_mask:0xf bank_mask:0xf
	s_nop 1
	v_pk_mul_f32 v[210:211], v[192:193], v[210:211]
	v_pk_fma_f32 v[214:215], v[200:201], v[56:57], v[210:211]
	v_pk_fma_f32 v[214:215], v[184:185], v[212:213], v[214:215]
	v_pk_add_f32 v[214:215], v[208:209], v[214:215]
	v_mul_f32_e32 v216, 0x3d372713, v214
	v_mul_f32_e32 v216, v214, v216
	v_fma_f32 v216, v214, v216, v214
	v_mul_f32_e32 v216, 0x3f4c422a, v216
	v_mul_f32_e32 v216, 0xc038aa3b, v216
	v_exp_f32_e32 v216, v216
	s_nop 0
	v_add_f32_e32 v216, 1.0, v216
	v_rcp_f32_e32 v216, v216
	s_nop 0
	v_mul_f32_e32 v214, v214, v216
	v_mul_f32_e32 v214, v64, v214
	v_mul_f32_e32 v216, 0x3d372713, v215
	v_mul_f32_e32 v216, v215, v216
	v_fma_f32 v216, v215, v216, v215
	v_mul_f32_e32 v216, 0x3f4c422a, v216
	v_mul_f32_e32 v216, 0xc038aa3b, v216
	v_exp_f32_e32 v216, v216
	s_nop 0
	v_add_f32_e32 v216, 1.0, v216
	v_rcp_f32_e32 v216, v216
	s_nop 0
	v_mul_f32_e32 v215, v215, v216
	v_mul_f32_e32 v215, v65, v215
	v_cvt_pk_bf16_f32 v61, v214, v215
	s_add_i32 s26, s66, -48
	v_cmp_gt_i32_e64 s[24:25], s26, v227
	s_nop 1
	s_and_saveexec_b64 s[26:27], s[24:25]
	global_store_dwordx4 v242, v[58:61], s[18:19] offset:3072
	s_mov_b64 exec, s[26:27]
	s_nop 4
	v_mov_b32_dpp v210, v18 row_ror:1 row_mask:0xf bank_mask:0xf
	v_mov_b32_dpp v212, v18 row_ror:2 row_mask:0xf bank_mask:0xf
	v_mov_b32_dpp v211, v19 row_ror:1 row_mask:0xf bank_mask:0xf
	v_mov_b32_dpp v213, v19 row_ror:2 row_mask:0xf bank_mask:0xf
	s_nop 1
	v_mov_b32_dpp v210, v34 row_shr:1 row_mask:0xf bank_mask:0xf
	v_mov_b32_dpp v212, v34 row_shr:2 row_mask:0xf bank_mask:0xf
	v_mov_b32_dpp v211, v35 row_shr:1 row_mask:0xf bank_mask:0xf
	v_mov_b32_dpp v213, v35 row_shr:2 row_mask:0xf bank_mask:0xf
	s_nop 1
	v_pk_mul_f32 v[210:211], v[186:187], v[210:211]
	v_pk_fma_f32 v[214:215], v[194:195], v[34:35], v[210:211]
	v_pk_fma_f32 v[214:215], v[178:179], v[212:213], v[214:215]
	v_pk_add_f32 v[214:215], v[202:203], v[214:215]
	v_mul_f32_e32 v216, 0x3d372713, v214
	v_mul_f32_e32 v216, v214, v216
	v_fma_f32 v216, v214, v216, v214
	v_mul_f32_e32 v216, 0x3f4c422a, v216
	v_mul_f32_e32 v216, 0xc038aa3b, v216
	v_exp_f32_e32 v216, v216
	s_nop 0
	v_add_f32_e32 v216, 1.0, v216
	v_rcp_f32_e32 v216, v216
	s_nop 0
	v_mul_f32_e32 v214, v214, v216
	v_mul_f32_e32 v214, v42, v214
	v_mul_f32_e32 v216, 0x3d372713, v215
	v_mul_f32_e32 v216, v215, v216
	v_fma_f32 v216, v215, v216, v215
	v_mul_f32_e32 v216, 0x3f4c422a, v216
	v_mul_f32_e32 v216, 0xc038aa3b, v216
	v_exp_f32_e32 v216, v216
	s_nop 0
	v_add_f32_e32 v216, 1.0, v216
	v_rcp_f32_e32 v216, v216
	s_nop 0
	v_mul_f32_e32 v215, v215, v216
	v_mul_f32_e32 v215, v43, v215
	v_cvt_pk_bf16_f32 v42, v214, v215
	v_mov_b32_dpp v210, v20 row_ror:1 row_mask:0xf bank_mask:0xf
	v_mov_b32_dpp v212, v20 row_ror:2 row_mask:0xf bank_mask:0xf
	v_mov_b32_dpp v211, v21 row_ror:1 row_mask:0xf bank_mask:0xf
	v_mov_b32_dpp v213, v21 row_ror:2 row_mask:0xf bank_mask:0xf
	s_nop 1
	v_mov_b32_dpp v210, v36 row_shr:1 row_mask:0xf bank_mask:0xf
	v_mov_b32_dpp v212, v36 row_shr:2 row_mask:0xf bank_mask:0xf
	v_mov_b32_dpp v211, v37 row_shr:1 row_mask:0xf bank_mask:0xf
	v_mov_b32_dpp v213, v37 row_shr:2 row_mask:0xf bank_mask:0xf
	s_nop 1
	v_pk_mul_f32 v[210:211], v[188:189], v[210:211]
	v_pk_fma_f32 v[214:215], v[196:197], v[36:37], v[210:211]
	v_pk_fma_f32 v[214:215], v[180:181], v[212:213], v[214:215]
	v_pk_add_f32 v[214:215], v[204:205], v[214:215]
	v_mul_f32_e32 v216, 0x3d372713, v214
	v_mul_f32_e32 v216, v214, v216
	v_fma_f32 v216, v214, v216, v214
	v_mul_f32_e32 v216, 0x3f4c422a, v216
	v_mul_f32_e32 v216, 0xc038aa3b, v216
	v_exp_f32_e32 v216, v216
	s_nop 0
	v_add_f32_e32 v216, 1.0, v216
	v_rcp_f32_e32 v216, v216
	s_nop 0
	v_mul_f32_e32 v214, v214, v216
	v_mul_f32_e32 v214, v44, v214
	v_mul_f32_e32 v216, 0x3d372713, v215
	v_mul_f32_e32 v216, v215, v216
	v_fma_f32 v216, v215, v216, v215
	v_mul_f32_e32 v216, 0x3f4c422a, v216
	v_mul_f32_e32 v216, 0xc038aa3b, v216
	v_exp_f32_e32 v216, v216
	s_nop 0
	v_add_f32_e32 v216, 1.0, v216
	v_rcp_f32_e32 v216, v216
	s_nop 0
	v_mul_f32_e32 v215, v215, v216
	v_mul_f32_e32 v215, v45, v215
	v_cvt_pk_bf16_f32 v43, v214, v215
	v_mov_b32_dpp v210, v22 row_ror:1 row_mask:0xf bank_mask:0xf
	v_mov_b32_dpp v212, v22 row_ror:2 row_mask:0xf bank_mask:0xf
	v_mov_b32_dpp v211, v23 row_ror:1 row_mask:0xf bank_mask:0xf
	v_mov_b32_dpp v213, v23 row_ror:2 row_mask:0xf bank_mask:0xf
	s_nop 1
	v_mov_b32_dpp v210, v38 row_shr:1 row_mask:0xf bank_mask:0xf
	v_mov_b32_dpp v212, v38 row_shr:2 row_mask:0xf bank_mask:0xf
	v_mov_b32_dpp v211, v39 row_shr:1 row_mask:0xf bank_mask:0xf
	v_mov_b32_dpp v213, v39 row_shr:2 row_mask:0xf bank_mask:0xf
	s_nop 1
	v_pk_mul_f32 v[210:211], v[190:191], v[210:211]
	v_pk_fma_f32 v[214:215], v[198:199], v[38:39], v[210:211]
	v_pk_fma_f32 v[214:215], v[182:183], v[212:213], v[214:215]
	v_pk_add_f32 v[214:215], v[206:207], v[214:215]
	v_mul_f32_e32 v216, 0x3d372713, v214
	v_mul_f32_e32 v216, v214, v216
	v_fma_f32 v216, v214, v216, v214
	v_mul_f32_e32 v216, 0x3f4c422a, v216
	v_mul_f32_e32 v216, 0xc038aa3b, v216
	v_exp_f32_e32 v216, v216
	s_nop 0
	v_add_f32_e32 v216, 1.0, v216
	v_rcp_f32_e32 v216, v216
	s_nop 0
	v_mul_f32_e32 v214, v214, v216
	v_mul_f32_e32 v214, v46, v214
	v_mul_f32_e32 v216, 0x3d372713, v215
	v_mul_f32_e32 v216, v215, v216
	v_fma_f32 v216, v215, v216, v215
	v_mul_f32_e32 v216, 0x3f4c422a, v216
	v_mul_f32_e32 v216, 0xc038aa3b, v216
	v_exp_f32_e32 v216, v216
	s_nop 0
	v_add_f32_e32 v216, 1.0, v216
	v_rcp_f32_e32 v216, v216
	s_nop 0
	v_mul_f32_e32 v215, v215, v216
	v_mul_f32_e32 v215, v47, v215
	v_cvt_pk_bf16_f32 v44, v214, v215
	v_mov_b32_dpp v210, v24 row_ror:1 row_mask:0xf bank_mask:0xf
	v_mov_b32_dpp v212, v24 row_ror:2 row_mask:0xf bank_mask:0xf
	v_mov_b32_dpp v211, v25 row_ror:1 row_mask:0xf bank_mask:0xf
	v_mov_b32_dpp v213, v25 row_ror:2 row_mask:0xf bank_mask:0xf
	s_nop 1
	v_mov_b32_dpp v210, v40 row_shr:1 row_mask:0xf bank_mask:0xf
	v_mov_b32_dpp v212, v40 row_shr:2 row_mask:0xf bank_mask:0xf
	v_mov_b32_dpp v211, v41 row_shr:1 row_mask:0xf bank_mask:0xf
	v_mov_b32_dpp v213, v41 row_shr:2 row_mask:0xf bank_mask:0xf
	s_nop 1
	v_pk_mul_f32 v[210:211], v[192:193], v[210:211]
	v_pk_fma_f32 v[214:215], v[200:201], v[40:41], v[210:211]
	v_pk_fma_f32 v[214:215], v[184:185], v[212:213], v[214:215]
	v_pk_add_f32 v[214:215], v[208:209], v[214:215]
	v_mul_f32_e32 v216, 0x3d372713, v214
	v_mul_f32_e32 v216, v214, v216
	v_fma_f32 v216, v214, v216, v214
	v_mul_f32_e32 v216, 0x3f4c422a, v216
	v_mul_f32_e32 v216, 0xc038aa3b, v216
	v_exp_f32_e32 v216, v216
	s_nop 0
	v_add_f32_e32 v216, 1.0, v216
	v_rcp_f32_e32 v216, v216
	s_nop 0
	v_mul_f32_e32 v214, v214, v216
	v_mul_f32_e32 v214, v48, v214
	v_mul_f32_e32 v216, 0x3d372713, v215
	v_mul_f32_e32 v216, v215, v216
	v_fma_f32 v216, v215, v216, v215
	v_mul_f32_e32 v216, 0x3f4c422a, v216
	v_mul_f32_e32 v216, 0xc038aa3b, v216
	v_exp_f32_e32 v216, v216
	s_nop 0
	v_add_f32_e32 v216, 1.0, v216
	v_rcp_f32_e32 v216, v216
	s_nop 0
	v_mul_f32_e32 v215, v215, v216
	v_mul_f32_e32 v215, v49, v215
	v_cvt_pk_bf16_f32 v45, v214, v215
	s_add_i32 s26, s66, -32
	v_cmp_gt_i32_e64 s[24:25], s26, v227
	s_nop 1
	s_and_saveexec_b64 s[26:27], s[24:25]
	global_store_dwordx4 v242, v[42:45], s[18:19] offset:2048
	s_mov_b64 exec, s[26:27]
	s_nop 4
	v_mov_b32_dpp v210, v2 row_ror:1 row_mask:0xf bank_mask:0xf
	v_mov_b32_dpp v212, v2 row_ror:2 row_mask:0xf bank_mask:0xf
	v_mov_b32_dpp v211, v3 row_ror:1 row_mask:0xf bank_mask:0xf
	v_mov_b32_dpp v213, v3 row_ror:2 row_mask:0xf bank_mask:0xf
	s_nop 1
	v_mov_b32_dpp v210, v18 row_shr:1 row_mask:0xf bank_mask:0xf
	v_mov_b32_dpp v212, v18 row_shr:2 row_mask:0xf bank_mask:0xf
	v_mov_b32_dpp v211, v19 row_shr:1 row_mask:0xf bank_mask:0xf
	v_mov_b32_dpp v213, v19 row_shr:2 row_mask:0xf bank_mask:0xf
	s_nop 1
	v_pk_mul_f32 v[210:211], v[186:187], v[210:211]
	v_pk_fma_f32 v[214:215], v[194:195], v[18:19], v[210:211]
	v_pk_fma_f32 v[214:215], v[178:179], v[212:213], v[214:215]
	v_pk_add_f32 v[214:215], v[202:203], v[214:215]
	v_mul_f32_e32 v216, 0x3d372713, v214
	v_mul_f32_e32 v216, v214, v216
	v_fma_f32 v216, v214, v216, v214
	v_mul_f32_e32 v216, 0x3f4c422a, v216
	v_mul_f32_e32 v216, 0xc038aa3b, v216
	v_exp_f32_e32 v216, v216
	s_nop 0
	v_add_f32_e32 v216, 1.0, v216
	v_rcp_f32_e32 v216, v216
	s_nop 0
	v_mul_f32_e32 v214, v214, v216
	v_mul_f32_e32 v214, v26, v214
	v_mul_f32_e32 v216, 0x3d372713, v215
	v_mul_f32_e32 v216, v215, v216
	v_fma_f32 v216, v215, v216, v215
	v_mul_f32_e32 v216, 0x3f4c422a, v216
	v_mul_f32_e32 v216, 0xc038aa3b, v216
	v_exp_f32_e32 v216, v216
	s_nop 0
	v_add_f32_e32 v216, 1.0, v216
	v_rcp_f32_e32 v216, v216
	s_nop 0
	v_mul_f32_e32 v215, v215, v216
	v_mul_f32_e32 v215, v27, v215
	v_cvt_pk_bf16_f32 v26, v214, v215
	v_mov_b32_dpp v210, v4 row_ror:1 row_mask:0xf bank_mask:0xf
	v_mov_b32_dpp v212, v4 row_ror:2 row_mask:0xf bank_mask:0xf
	v_mov_b32_dpp v211, v5 row_ror:1 row_mask:0xf bank_mask:0xf
	v_mov_b32_dpp v213, v5 row_ror:2 row_mask:0xf bank_mask:0xf
	s_nop 1
	v_mov_b32_dpp v210, v20 row_shr:1 row_mask:0xf bank_mask:0xf
	v_mov_b32_dpp v212, v20 row_shr:2 row_mask:0xf bank_mask:0xf
	v_mov_b32_dpp v211, v21 row_shr:1 row_mask:0xf bank_mask:0xf
	v_mov_b32_dpp v213, v21 row_shr:2 row_mask:0xf bank_mask:0xf
	s_nop 1
	v_pk_mul_f32 v[210:211], v[188:189], v[210:211]
	v_pk_fma_f32 v[214:215], v[196:197], v[20:21], v[210:211]
	v_pk_fma_f32 v[214:215], v[180:181], v[212:213], v[214:215]
	v_pk_add_f32 v[214:215], v[204:205], v[214:215]
	v_mul_f32_e32 v216, 0x3d372713, v214
	v_mul_f32_e32 v216, v214, v216
	v_fma_f32 v216, v214, v216, v214
	v_mul_f32_e32 v216, 0x3f4c422a, v216
	v_mul_f32_e32 v216, 0xc038aa3b, v216
	v_exp_f32_e32 v216, v216
	s_nop 0
	v_add_f32_e32 v216, 1.0, v216
	v_rcp_f32_e32 v216, v216
	s_nop 0
	v_mul_f32_e32 v214, v214, v216
	v_mul_f32_e32 v214, v28, v214
	v_mul_f32_e32 v216, 0x3d372713, v215
	v_mul_f32_e32 v216, v215, v216
	v_fma_f32 v216, v215, v216, v215
	v_mul_f32_e32 v216, 0x3f4c422a, v216
	v_mul_f32_e32 v216, 0xc038aa3b, v216
	v_exp_f32_e32 v216, v216
	s_nop 0
	v_add_f32_e32 v216, 1.0, v216
	v_rcp_f32_e32 v216, v216
	s_nop 0
	v_mul_f32_e32 v215, v215, v216
	v_mul_f32_e32 v215, v29, v215
	v_cvt_pk_bf16_f32 v27, v214, v215
	v_mov_b32_dpp v210, v6 row_ror:1 row_mask:0xf bank_mask:0xf
	v_mov_b32_dpp v212, v6 row_ror:2 row_mask:0xf bank_mask:0xf
	v_mov_b32_dpp v211, v7 row_ror:1 row_mask:0xf bank_mask:0xf
	v_mov_b32_dpp v213, v7 row_ror:2 row_mask:0xf bank_mask:0xf
	s_nop 1
	v_mov_b32_dpp v210, v22 row_shr:1 row_mask:0xf bank_mask:0xf
	v_mov_b32_dpp v212, v22 row_shr:2 row_mask:0xf bank_mask:0xf
	v_mov_b32_dpp v211, v23 row_shr:1 row_mask:0xf bank_mask:0xf
	v_mov_b32_dpp v213, v23 row_shr:2 row_mask:0xf bank_mask:0xf
	s_nop 1
	v_pk_mul_f32 v[210:211], v[190:191], v[210:211]
	v_pk_fma_f32 v[214:215], v[198:199], v[22:23], v[210:211]
	v_pk_fma_f32 v[214:215], v[182:183], v[212:213], v[214:215]
	v_pk_add_f32 v[214:215], v[206:207], v[214:215]
	v_mul_f32_e32 v216, 0x3d372713, v214
	v_mul_f32_e32 v216, v214, v216
	v_fma_f32 v216, v214, v216, v214
	v_mul_f32_e32 v216, 0x3f4c422a, v216
	v_mul_f32_e32 v216, 0xc038aa3b, v216
	v_exp_f32_e32 v216, v216
	s_nop 0
	v_add_f32_e32 v216, 1.0, v216
	v_rcp_f32_e32 v216, v216
	s_nop 0
	v_mul_f32_e32 v214, v214, v216
	v_mul_f32_e32 v214, v30, v214
	v_mul_f32_e32 v216, 0x3d372713, v215
	v_mul_f32_e32 v216, v215, v216
	v_fma_f32 v216, v215, v216, v215
	v_mul_f32_e32 v216, 0x3f4c422a, v216
	v_mul_f32_e32 v216, 0xc038aa3b, v216
	v_exp_f32_e32 v216, v216
	s_nop 0
	v_add_f32_e32 v216, 1.0, v216
	v_rcp_f32_e32 v216, v216
	s_nop 0
	v_mul_f32_e32 v215, v215, v216
	v_mul_f32_e32 v215, v31, v215
	v_cvt_pk_bf16_f32 v28, v214, v215
	v_mov_b32_dpp v210, v8 row_ror:1 row_mask:0xf bank_mask:0xf
	v_mov_b32_dpp v212, v8 row_ror:2 row_mask:0xf bank_mask:0xf
	v_mov_b32_dpp v211, v9 row_ror:1 row_mask:0xf bank_mask:0xf
	v_mov_b32_dpp v213, v9 row_ror:2 row_mask:0xf bank_mask:0xf
	s_nop 1
	v_mov_b32_dpp v210, v24 row_shr:1 row_mask:0xf bank_mask:0xf
	v_mov_b32_dpp v212, v24 row_shr:2 row_mask:0xf bank_mask:0xf
	v_mov_b32_dpp v211, v25 row_shr:1 row_mask:0xf bank_mask:0xf
	v_mov_b32_dpp v213, v25 row_shr:2 row_mask:0xf bank_mask:0xf
	s_nop 1
	v_pk_mul_f32 v[210:211], v[192:193], v[210:211]
	v_pk_fma_f32 v[214:215], v[200:201], v[24:25], v[210:211]
	v_pk_fma_f32 v[214:215], v[184:185], v[212:213], v[214:215]
	v_pk_add_f32 v[214:215], v[208:209], v[214:215]
	v_mul_f32_e32 v216, 0x3d372713, v214
	v_mul_f32_e32 v216, v214, v216
	v_fma_f32 v216, v214, v216, v214
	v_mul_f32_e32 v216, 0x3f4c422a, v216
	v_mul_f32_e32 v216, 0xc038aa3b, v216
	v_exp_f32_e32 v216, v216
	s_nop 0
	v_add_f32_e32 v216, 1.0, v216
	v_rcp_f32_e32 v216, v216
	s_nop 0
	v_mul_f32_e32 v214, v214, v216
	v_mul_f32_e32 v214, v32, v214
	v_mul_f32_e32 v216, 0x3d372713, v215
	v_mul_f32_e32 v216, v215, v216
	v_fma_f32 v216, v215, v216, v215
	v_mul_f32_e32 v216, 0x3f4c422a, v216
	v_mul_f32_e32 v216, 0xc038aa3b, v216
	v_exp_f32_e32 v216, v216
	s_nop 0
	v_add_f32_e32 v216, 1.0, v216
	v_rcp_f32_e32 v216, v216
	s_nop 0
	v_mul_f32_e32 v215, v215, v216
	v_mul_f32_e32 v215, v33, v215
	v_cvt_pk_bf16_f32 v29, v214, v215
	s_add_i32 s26, s66, -16
	v_cmp_gt_i32_e64 s[24:25], s26, v227
	s_nop 1
	s_and_saveexec_b64 s[26:27], s[24:25]
	global_store_dwordx4 v242, v[26:29], s[18:19] offset:1024
	s_mov_b64 exec, s[26:27]
	s_nop 4
	v_mov_b32_dpp v210, v218 row_ror:1 row_mask:0xf bank_mask:0xf
	v_mov_b32_dpp v212, v218 row_ror:2 row_mask:0xf bank_mask:0xf
	v_mov_b32_dpp v211, v219 row_ror:1 row_mask:0xf bank_mask:0xf
	v_mov_b32_dpp v213, v219 row_ror:2 row_mask:0xf bank_mask:0xf
	s_nop 1
	v_mov_b32_dpp v210, v2 row_shr:1 row_mask:0xf bank_mask:0xf
	v_mov_b32_dpp v212, v2 row_shr:2 row_mask:0xf bank_mask:0xf
	v_mov_b32_dpp v211, v3 row_shr:1 row_mask:0xf bank_mask:0xf
	v_mov_b32_dpp v213, v3 row_shr:2 row_mask:0xf bank_mask:0xf
	s_nop 1
	v_pk_mul_f32 v[210:211], v[186:187], v[210:211]
	v_pk_fma_f32 v[214:215], v[194:195], v[2:3], v[210:211]
	v_pk_fma_f32 v[214:215], v[178:179], v[212:213], v[214:215]
	v_pk_add_f32 v[214:215], v[202:203], v[214:215]
	v_mul_f32_e32 v216, 0x3d372713, v214
	v_mul_f32_e32 v216, v214, v216
	v_fma_f32 v216, v214, v216, v214
	v_mul_f32_e32 v216, 0x3f4c422a, v216
	v_mul_f32_e32 v216, 0xc038aa3b, v216
	v_exp_f32_e32 v216, v216
	s_nop 0
	v_add_f32_e32 v216, 1.0, v216
	v_rcp_f32_e32 v216, v216
	s_nop 0
	v_mul_f32_e32 v214, v214, v216
	v_mul_f32_e32 v214, v10, v214
	v_mul_f32_e32 v216, 0x3d372713, v215
	v_mul_f32_e32 v216, v215, v216
	v_fma_f32 v216, v215, v216, v215
	v_mul_f32_e32 v216, 0x3f4c422a, v216
	v_mul_f32_e32 v216, 0xc038aa3b, v216
	v_exp_f32_e32 v216, v216
	s_nop 0
	v_add_f32_e32 v216, 1.0, v216
	v_rcp_f32_e32 v216, v216
	s_nop 0
	v_mul_f32_e32 v215, v215, v216
	v_mul_f32_e32 v215, v11, v215
	v_cvt_pk_bf16_f32 v10, v214, v215
	v_mov_b32_dpp v210, v220 row_ror:1 row_mask:0xf bank_mask:0xf
	v_mov_b32_dpp v212, v220 row_ror:2 row_mask:0xf bank_mask:0xf
	v_mov_b32_dpp v211, v221 row_ror:1 row_mask:0xf bank_mask:0xf
	v_mov_b32_dpp v213, v221 row_ror:2 row_mask:0xf bank_mask:0xf
	s_nop 1
	v_mov_b32_dpp v210, v4 row_shr:1 row_mask:0xf bank_mask:0xf
	v_mov_b32_dpp v212, v4 row_shr:2 row_mask:0xf bank_mask:0xf
	v_mov_b32_dpp v211, v5 row_shr:1 row_mask:0xf bank_mask:0xf
	v_mov_b32_dpp v213, v5 row_shr:2 row_mask:0xf bank_mask:0xf
	s_nop 1
	v_pk_mul_f32 v[210:211], v[188:189], v[210:211]
	v_pk_fma_f32 v[214:215], v[196:197], v[4:5], v[210:211]
	v_pk_fma_f32 v[214:215], v[180:181], v[212:213], v[214:215]
	v_pk_add_f32 v[214:215], v[204:205], v[214:215]
	v_mul_f32_e32 v216, 0x3d372713, v214
	v_mul_f32_e32 v216, v214, v216
	v_fma_f32 v216, v214, v216, v214
	v_mul_f32_e32 v216, 0x3f4c422a, v216
	v_mul_f32_e32 v216, 0xc038aa3b, v216
	v_exp_f32_e32 v216, v216
	s_nop 0
	v_add_f32_e32 v216, 1.0, v216
	v_rcp_f32_e32 v216, v216
	s_nop 0
	v_mul_f32_e32 v214, v214, v216
	v_mul_f32_e32 v214, v12, v214
	v_mul_f32_e32 v216, 0x3d372713, v215
	v_mul_f32_e32 v216, v215, v216
	v_fma_f32 v216, v215, v216, v215
	v_mul_f32_e32 v216, 0x3f4c422a, v216
	v_mul_f32_e32 v216, 0xc038aa3b, v216
	v_exp_f32_e32 v216, v216
	s_nop 0
	v_add_f32_e32 v216, 1.0, v216
	v_rcp_f32_e32 v216, v216
	s_nop 0
	v_mul_f32_e32 v215, v215, v216
	v_mul_f32_e32 v215, v13, v215
	v_cvt_pk_bf16_f32 v11, v214, v215
	v_mov_b32_dpp v210, v222 row_ror:1 row_mask:0xf bank_mask:0xf
	v_mov_b32_dpp v212, v222 row_ror:2 row_mask:0xf bank_mask:0xf
	v_mov_b32_dpp v211, v223 row_ror:1 row_mask:0xf bank_mask:0xf
	v_mov_b32_dpp v213, v223 row_ror:2 row_mask:0xf bank_mask:0xf
	s_nop 1
	v_mov_b32_dpp v210, v6 row_shr:1 row_mask:0xf bank_mask:0xf
	v_mov_b32_dpp v212, v6 row_shr:2 row_mask:0xf bank_mask:0xf
	v_mov_b32_dpp v211, v7 row_shr:1 row_mask:0xf bank_mask:0xf
	v_mov_b32_dpp v213, v7 row_shr:2 row_mask:0xf bank_mask:0xf
	s_nop 1
	v_pk_mul_f32 v[210:211], v[190:191], v[210:211]
	v_pk_fma_f32 v[214:215], v[198:199], v[6:7], v[210:211]
	v_pk_fma_f32 v[214:215], v[182:183], v[212:213], v[214:215]
	v_pk_add_f32 v[214:215], v[206:207], v[214:215]
	v_mul_f32_e32 v216, 0x3d372713, v214
	v_mul_f32_e32 v216, v214, v216
	v_fma_f32 v216, v214, v216, v214
	v_mul_f32_e32 v216, 0x3f4c422a, v216
	v_mul_f32_e32 v216, 0xc038aa3b, v216
	v_exp_f32_e32 v216, v216
	s_nop 0
	v_add_f32_e32 v216, 1.0, v216
	v_rcp_f32_e32 v216, v216
	s_nop 0
	v_mul_f32_e32 v214, v214, v216
	v_mul_f32_e32 v214, v14, v214
	v_mul_f32_e32 v216, 0x3d372713, v215
	v_mul_f32_e32 v216, v215, v216
	v_fma_f32 v216, v215, v216, v215
	v_mul_f32_e32 v216, 0x3f4c422a, v216
	v_mul_f32_e32 v216, 0xc038aa3b, v216
	v_exp_f32_e32 v216, v216
	s_nop 0
	v_add_f32_e32 v216, 1.0, v216
	v_rcp_f32_e32 v216, v216
	s_nop 0
	v_mul_f32_e32 v215, v215, v216
	v_mul_f32_e32 v215, v15, v215
	v_cvt_pk_bf16_f32 v12, v214, v215
	v_mov_b32_dpp v210, v224 row_ror:1 row_mask:0xf bank_mask:0xf
	v_mov_b32_dpp v212, v224 row_ror:2 row_mask:0xf bank_mask:0xf
	v_mov_b32_dpp v211, v225 row_ror:1 row_mask:0xf bank_mask:0xf
	v_mov_b32_dpp v213, v225 row_ror:2 row_mask:0xf bank_mask:0xf
	s_nop 1
	v_mov_b32_dpp v210, v8 row_shr:1 row_mask:0xf bank_mask:0xf
	v_mov_b32_dpp v212, v8 row_shr:2 row_mask:0xf bank_mask:0xf
	v_mov_b32_dpp v211, v9 row_shr:1 row_mask:0xf bank_mask:0xf
	v_mov_b32_dpp v213, v9 row_shr:2 row_mask:0xf bank_mask:0xf
	s_nop 1
	v_pk_mul_f32 v[210:211], v[192:193], v[210:211]
	v_pk_fma_f32 v[214:215], v[200:201], v[8:9], v[210:211]
	v_pk_fma_f32 v[214:215], v[184:185], v[212:213], v[214:215]
	v_pk_add_f32 v[214:215], v[208:209], v[214:215]
	v_mul_f32_e32 v216, 0x3d372713, v214
	v_mul_f32_e32 v216, v214, v216
	v_fma_f32 v216, v214, v216, v214
	v_mul_f32_e32 v216, 0x3f4c422a, v216
	v_mul_f32_e32 v216, 0xc038aa3b, v216
	v_exp_f32_e32 v216, v216
	s_nop 0
	v_add_f32_e32 v216, 1.0, v216
	v_rcp_f32_e32 v216, v216
	s_nop 0
	v_mul_f32_e32 v214, v214, v216
	v_mul_f32_e32 v214, v16, v214
	v_mul_f32_e32 v216, 0x3d372713, v215
	v_mul_f32_e32 v216, v215, v216
	v_fma_f32 v216, v215, v216, v215
	v_mul_f32_e32 v216, 0x3f4c422a, v216
	v_mul_f32_e32 v216, 0xc038aa3b, v216
	v_exp_f32_e32 v216, v216
	s_nop 0
	v_add_f32_e32 v216, 1.0, v216
	v_rcp_f32_e32 v216, v216
	s_nop 0
	v_mul_f32_e32 v215, v215, v216
	v_mul_f32_e32 v215, v17, v215
	v_cvt_pk_bf16_f32 v13, v214, v215
	s_add_i32 s26, s66, 0
	v_cmp_gt_i32_e64 s[24:25], s26, v227
	v_cmp_lt_u32_e32 vcc, 1, v227
	s_and_b64 s[24:25], s[24:25], vcc
	s_nop 1
	s_and_saveexec_b64 s[26:27], s[24:25]
	global_store_dwordx4 v242, v[10:13], s[18:19]
	s_mov_b64 exec, s[26:27]
	s_nop 4

	.amdhsa_kernel _Z11mega_kernel6Params
		.amdhsa_group_segment_fixed_size 77840
		.amdhsa_private_segment_fixed_size 0
		.amdhsa_kernarg_size 568
		.amdhsa_user_sgpr_count 2
		.amdhsa_user_sgpr_dispatch_ptr 0
		.amdhsa_user_sgpr_queue_ptr 0
		.amdhsa_user_sgpr_kernarg_segment_ptr 1
		.amdhsa_user_sgpr_dispatch_id 0
		.amdhsa_user_sgpr_kernarg_preload_length 0
		.amdhsa_user_sgpr_kernarg_preload_offset 0
		.amdhsa_user_sgpr_private_segment_size 0
		.amdhsa_uses_dynamic_stack 0
		.amdhsa_enable_private_segment 0
		.amdhsa_system_sgpr_workgroup_id_x 1
		.amdhsa_system_sgpr_workgroup_id_y 0
		.amdhsa_system_sgpr_workgroup_id_z 0
		.amdhsa_system_sgpr_workgroup_info 0
		.amdhsa_system_vgpr_workitem_id 2
		.amdhsa_next_free_vgpr 248
		.amdhsa_next_free_sgpr 100
		.amdhsa_accum_offset 248
		.amdhsa_reserve_vcc 1
		.amdhsa_float_round_mode_32 0
		.amdhsa_float_round_mode_16_64 0
		.amdhsa_float_denorm_mode_32 3
		.amdhsa_float_denorm_mode_16_64 3
		.amdhsa_dx10_clamp 1
		.amdhsa_ieee_mode 1
		.amdhsa_fp16_overflow 0
		.amdhsa_tg_split 0
		.amdhsa_exception_fp_ieee_invalid_op 0
		.amdhsa_exception_fp_denorm_src 0
		.amdhsa_exception_fp_ieee_div_zero 0
		.amdhsa_exception_fp_ieee_overflow 0
		.amdhsa_exception_fp_ieee_underflow 0
		.amdhsa_exception_fp_ieee_inexact 0
		.amdhsa_exception_int_div_zero 0
	.end_amdhsa_kernel

amdhsa.kernels:
  - .agpr_count:     0
    .args:
      - .offset:         0
        .size:           312
        .value_kind:     by_value
      - .offset:         312
        .size:           4
        .value_kind:     hidden_block_count_x
      - .offset:         316
        .size:           4
        .value_kind:     hidden_block_count_y
      - .offset:         320
        .size:           4
        .value_kind:     hidden_block_count_z
      - .offset:         324
        .size:           2
        .value_kind:     hidden_group_size_x
      - .offset:         326
        .size:           2
        .value_kind:     hidden_group_size_y
      - .offset:         328
        .size:           2
        .value_kind:     hidden_group_size_z
      - .offset:         330
        .size:           2
        .value_kind:     hidden_remainder_x
      - .offset:         332
        .size:           2
        .value_kind:     hidden_remainder_y
      - .offset:         334
        .size:           2
        .value_kind:     hidden_remainder_z
      - .offset:         352
        .size:           8
        .value_kind:     hidden_global_offset_x
      - .offset:         360
        .size:           8
        .value_kind:     hidden_global_offset_y
      - .offset:         368
        .size:           8
        .value_kind:     hidden_global_offset_z
      - .offset:         376
        .size:           2
        .value_kind:     hidden_grid_dims
      - .offset:         400
        .size:           8
        .value_kind:     hidden_multigrid_sync_arg
    .group_segment_fixed_size: 77840
    .kernarg_segment_align: 8
    .kernarg_segment_size: 568
    .language:       OpenCL C
    .language_version:
      - 2
      - 0
    .max_flat_workgroup_size: 256
    .name:           _Z11mega_kernel6Params
    .private_segment_fixed_size: 0
    .sgpr_count:     106
    .sgpr_spill_count: 74
    .symbol:         _Z11mega_kernel6Params.kd
    .uniform_work_group_size: 1
    .uses_dynamic_stack: false
    .vgpr_count:     248
    .vgpr_spill_count: 0
    .wavefront_size: 64
